# FFT: only dead-half packed f32 ops are split; packed ops with both halves live stay packed
# speedup vs baseline: 1.0072x; 1.0022x over previous
;     static __device__ __forceinline__ float sl(float g, float up) { return g * __builtin_amdgcn_rcpf(1.0f + __builtin_amdgcn_exp2f(-1.4426950408889634f * g)) * up; }
; #define tid ltid()
; template <int LR, bool INV>
; __device__ __forceinline__ void fft_pass(float2* X, const int N, const int sl, const int tid) {
;     ...
;   for (int g = tid; g < (N >> LR); g += NTHR) {
;     const int r = g & (s - 1);
;     const int i0 = ((g >> sl) << (sl + LR)) + r;
;     float2 x[R];
; #pragma unroll
;     for (int m = 0; m < R; ++m) x[m] = X[PIDX(i0 + (m << sl))];
.LBB0_651:
	v_and_or_b32 v31, v30, s67, v28
	v_ashrrev_i32_e32 v32, 4, v31
	v_lshlrev_b32_e32 v32, 3, v32
	v_lshlrev_b32_e32 v33, 3, v31
	v_add3_u32 v50, s52, v32, v33


;     static __device__ __forceinline__ float sl(float g, float up) { return g * __builtin_amdgcn_rcpf(1.0f + __builtin_amdgcn_exp2f(-1.4426950408889634f * g)) * up; }
; #define tid ltid()
; template <int LR, bool INV>
; __device__ __forceinline__ void fft_pass(float2* X, const int N, const int sl, const int tid) {
;     ...
;   for (int g = tid; g < (N >> LR); g += NTHR) {
;     const int r = g & (s - 1);
;     const int i0 = ((g >> sl) << (sl + LR)) + r;
;     float2 x[R];
; #pragma unroll
;     for (int m = 0; m < R; ++m) x[m] = X[PIDX(i0 + (m << sl))];
	v_or_b32_e32 v31, 0xe00, v31

;     static __device__ __forceinline__ float sl(float g, float up) { return g * __builtin_amdgcn_rcpf(1.0f + __builtin_amdgcn_exp2f(-1.4426950408889634f * g)) * up; }
; #define tid ltid()
; template <int LR, bool INV>
; __device__ __forceinline__ void fft_pass(float2* X, const int N, const int sl, const int tid) {
;     ...
;   for (int g = tid; g < (N >> LR); g += NTHR) {
;     const int r = g & (s - 1);
;     const int i0 = ((g >> sl) << (sl + LR)) + r;
;     float2 x[R];
; #pragma unroll
;     for (int m = 0; m < R; ++m) x[m] = X[PIDX(i0 + (m << sl))];
	v_ashrrev_i32_e32 v31, 4, v31

;     static __device__ __forceinline__ float sl(float g, float up) { return g * __builtin_amdgcn_rcpf(1.0f + __builtin_amdgcn_exp2f(-1.4426950408889634f * g)) * up; }
; #define tid ltid()
; template <int LR, bool INV>
; __device__ __forceinline__ void fft_pass(float2* X, const int N, const int sl, const int tid) {
;     ...
;   for (int g = tid; g < (N >> LR); g += NTHR) {
;     const int r = g & (s - 1);
;     const int i0 = ((g >> sl) << (sl + LR)) + r;
;     float2 x[R];
; #pragma unroll
;     for (int m = 0; m < R; ++m) x[m] = X[PIDX(i0 + (m << sl))];
	v_lshlrev_b32_e32 v31, 3, v31

;     static __device__ __forceinline__ float sl(float g, float up) { return g * __builtin_amdgcn_rcpf(1.0f + __builtin_amdgcn_exp2f(-1.4426950408889634f * g)) * up; }
; __device__ __forceinline__ float2 cmul(float2 a, float2 b) { return make_float2(a.x * b.x - a.y * b.y, a.x * b.y + a.y * b.x); }
; template <int LR, bool INV>
; __device__ __forceinline__ void fft_stages(float2 (&x)[1 << LR], const int r, const int s) {
;     ...
;   for (int st = 0; st < LR; ++st) {
;     const int hl = INV ? (1 << st) : (R >> (st + 1));
;     const float fb = (float)r * (0.5f / (float)(hl * s));
;     const float2 wb = make_float2(__builtin_amdgcn_cosf(fb), INV ? __builtin_amdgcn_sinf(fb) : -__builtin_amdgcn_sinf(fb));
; #pragma unroll
;     for (int m = 0; m < R; ++m) {
;       if (m & hl) continue;
;       const int k = m & (hl - 1); const int j = k * (8 / hl);
;       const float2 wc = make_float2(c16(j), INV ? s16(j) : -s16(j));
;       const float2 tw = cmul(wb, wc);
;       if (!INV) { const float2 p = x[m], q = x[m + hl]; x[m] = make_float2(p.x + q.x, p.y + q.y); x[m + hl] = cmul(make_float2(p.x - q.x, p.y - q.y), tw); }
;       else { const float2 p = x[m], q = cmul(x[m + hl], tw); x[m] = make_float2(p.x + q.x, p.y + q.y); x[m + hl] = make_float2(p.x - q.x, p.y - q.y); }
;     }
; template <int LR, bool INV>
; __device__ __forceinline__ void fft_pass(float2* X, const int N, const int sl, const int tid) {
;     ...
;     for (int m = 0; m < R; ++m) x[m] = X[PIDX(i0 + (m << sl))];
;     fft_stages<LR, INV>(x, r, s);
; #pragma unroll
;     for (int m = 0; m < R; ++m) X[PIDX(i0 + (m << sl))] = x[m];
	v_add3_u32 v31, s52, v31, v33
	ds_read_b64 v[32:33], v50
	ds_read_b64 v[34:35], v50 offset:4352
	ds_read_b64 v[36:37], v50 offset:8704
	ds_read_b64 v[38:39], v50 offset:13056
	ds_read_b64 v[40:41], v50 offset:17408
	ds_read_b64 v[42:43], v50 offset:21760
	ds_read_b64 v[44:45], v50 offset:26112
	ds_read_b64 v[46:47], v50 offset:30464
	v_add_u32_e32 v29, 0x200, v29
	s_waitcnt lgkmcnt(3)
	v_pk_add_f32 v[48:49], v[32:33], v[40:41]
	v_pk_add_f32 v[32:33], v[32:33], v[40:41] neg_lo:[0,1] neg_hi:[0,1]
	s_waitcnt lgkmcnt(2)
	v_pk_add_f32 v[40:41], v[34:35], v[42:43]
	v_pk_add_f32 v[34:35], v[34:35], v[42:43] neg_lo:[0,1] neg_hi:[0,1]
	s_waitcnt lgkmcnt(1)
	v_pk_add_f32 v[42:43], v[36:37], v[44:45]
	v_pk_add_f32 v[36:37], v[36:37], v[44:45] neg_lo:[0,1] neg_hi:[0,1]
	s_waitcnt lgkmcnt(0)
	v_pk_add_f32 v[44:45], v[38:39], v[46:47]
	v_pk_add_f32 v[38:39], v[38:39], v[46:47] neg_lo:[0,1] neg_hi:[0,1]
	v_pk_add_f32 v[46:47], v[48:49], v[42:43]
	v_pk_add_f32 v[42:43], v[48:49], v[42:43] neg_lo:[0,1] neg_hi:[0,1]
	v_pk_add_f32 v[48:49], v[40:41], v[44:45]
	v_pk_add_f32 v[40:41], v[40:41], v[44:45] neg_lo:[0,1] neg_hi:[0,1]
	v_pk_add_f32 v[44:45], v[46:47], v[48:49]
	v_pk_add_f32 v[46:47], v[46:47], v[48:49] neg_lo:[0,1] neg_hi:[0,1]
	ds_write_b64 v50, v[44:45]
	v_pk_mul_f32 v[44:45], v[14:15], v[46:47] op_sel:[0,1]
	v_cmp_lt_i32_e32 vcc, -1, v29
	v_fma_f32 v48, v12, v46, -v44
	v_fma_f32 v49, v13, v46, v45
	v_add_u32_e32 v30, 0x1000, v30

;     static __device__ __forceinline__ float sl(float g, float up) { return g * __builtin_amdgcn_rcpf(1.0f + __builtin_amdgcn_exp2f(-1.4426950408889634f * g)) * up; }
; __device__ __forceinline__ float2 cmul(float2 a, float2 b) { return make_float2(a.x * b.x - a.y * b.y, a.x * b.y + a.y * b.x); }
; template <int LR, bool INV>
; __device__ __forceinline__ void fft_stages(float2 (&x)[1 << LR], const int r, const int s) {
;   constexpr int R = 1 << LR;
; #pragma unroll
;   for (int st = 0; st < LR; ++st) {
;     const int hl = INV ? (1 << st) : (R >> (st + 1));
;     const float fb = (float)r * (0.5f / (float)(hl * s));
;     const float2 wb = make_float2(__builtin_amdgcn_cosf(fb), INV ? __builtin_amdgcn_sinf(fb) : -__builtin_amdgcn_sinf(fb));
; #pragma unroll
;     for (int m = 0; m < R; ++m) {
;       if (m & hl) continue;
;       const int k = m & (hl - 1); const int j = k * (8 / hl);
;       const float2 wc = make_float2(c16(j), INV ? s16(j) : -s16(j));
;       const float2 tw = cmul(wb, wc);
;       if (!INV) { const float2 p = x[m], q = x[m + hl]; x[m] = make_float2(p.x + q.x, p.y + q.y); x[m + hl] = cmul(make_float2(p.x - q.x, p.y - q.y), tw); }
;       else { const float2 p = x[m], q = cmul(x[m + hl], tw); x[m] = make_float2(p.x + q.x, p.y + q.y); x[m + hl] = make_float2(p.x - q.x, p.y - q.y); }
;     }
; template <int LR, bool INV>
; __device__ __forceinline__ void fft_pass(float2* X, const int N, const int sl, const int tid) {
;     ...
; #pragma unroll
;     for (int m = 0; m < R; ++m) X[PIDX(i0 + (m << sl))] = x[m];
	v_pk_mul_f32 v[44:45], v[16:17], v[42:43] op_sel:[0,1]
	ds_write_b64 v50, v[48:49] offset:4352
	v_fma_f32 v46, v8, v42, -v44
	v_fma_f32 v47, v9, v42, v45
	s_or_b64 s[14:15], vcc, s[14:15]

; __device__ __forceinline__ float2 cmul(float2 a, float2 b) { return make_float2(a.x * b.x - a.y * b.y, a.x * b.y + a.y * b.x); }
; template <int LR, bool INV>
; __device__ __forceinline__ void fft_stages(float2 (&x)[1 << LR], const int r, const int s) {
;   constexpr int R = 1 << LR;
; #pragma unroll
;   for (int st = 0; st < LR; ++st) {
;     const int hl = INV ? (1 << st) : (R >> (st + 1));
;     const float fb = (float)r * (0.5f / (float)(hl * s));
;     const float2 wb = make_float2(__builtin_amdgcn_cosf(fb), INV ? __builtin_amdgcn_sinf(fb) : -__builtin_amdgcn_sinf(fb));
; #pragma unroll
;     for (int m = 0; m < R; ++m) {
;       if (m & hl) continue;
;       const int k = m & (hl - 1); const int j = k * (8 / hl);
;       const float2 wc = make_float2(c16(j), INV ? s16(j) : -s16(j));
;       const float2 tw = cmul(wb, wc);
;       if (!INV) { const float2 p = x[m], q = x[m + hl]; x[m] = make_float2(p.x + q.x, p.y + q.y); x[m + hl] = cmul(make_float2(p.x - q.x, p.y - q.y), tw); }
;       else { const float2 p = x[m], q = cmul(x[m + hl], tw); x[m] = make_float2(p.x + q.x, p.y + q.y); x[m + hl] = make_float2(p.x - q.x, p.y - q.y); }
;     }
	v_pk_mul_f32 v[42:43], v[18:19], v[40:41] op_sel:[0,1]
	s_nop 0
	v_fma_f32 v44, v10, v40, -v42
	v_fma_f32 v45, v11, v40, v43

;     static __device__ __forceinline__ float sl(float g, float up) { return g * __builtin_amdgcn_rcpf(1.0f + __builtin_amdgcn_exp2f(-1.4426950408889634f * g)) * up; }
; __device__ __forceinline__ float2 cmul(float2 a, float2 b) { return make_float2(a.x * b.x - a.y * b.y, a.x * b.y + a.y * b.x); }
; template <int LR, bool INV>
; __device__ __forceinline__ void fft_stages(float2 (&x)[1 << LR], const int r, const int s) {
;   constexpr int R = 1 << LR;
; #pragma unroll
;   for (int st = 0; st < LR; ++st) {
;     const int hl = INV ? (1 << st) : (R >> (st + 1));
;     const float fb = (float)r * (0.5f / (float)(hl * s));
;     const float2 wb = make_float2(__builtin_amdgcn_cosf(fb), INV ? __builtin_amdgcn_sinf(fb) : -__builtin_amdgcn_sinf(fb));
; #pragma unroll
;     for (int m = 0; m < R; ++m) {
;       if (m & hl) continue;
;       const int k = m & (hl - 1); const int j = k * (8 / hl);
;       const float2 wc = make_float2(c16(j), INV ? s16(j) : -s16(j));
;       const float2 tw = cmul(wb, wc);
;       if (!INV) { const float2 p = x[m], q = x[m + hl]; x[m] = make_float2(p.x + q.x, p.y + q.y); x[m + hl] = cmul(make_float2(p.x - q.x, p.y - q.y), tw); }
;       else { const float2 p = x[m], q = cmul(x[m + hl], tw); x[m] = make_float2(p.x + q.x, p.y + q.y); x[m + hl] = make_float2(p.x - q.x, p.y - q.y); }
;     }
; template <int LR, bool INV>
; __device__ __forceinline__ void fft_pass(float2* X, const int N, const int sl, const int tid) {
;     ...
; #pragma unroll
;     for (int m = 0; m < R; ++m) X[PIDX(i0 + (m << sl))] = x[m];
	v_pk_add_f32 v[40:41], v[46:47], v[44:45]
	v_pk_add_f32 v[42:43], v[46:47], v[44:45] neg_lo:[0,1] neg_hi:[0,1]
	ds_write_b64 v50, v[40:41] offset:8704
	v_pk_mul_f32 v[40:41], v[14:15], v[42:43] op_sel:[0,1]
	s_nop 0
	v_fma_f32 v44, v12, v42, -v40
	v_fma_f32 v45, v13, v42, v41

;     static __device__ __forceinline__ float sl(float g, float up) { return g * __builtin_amdgcn_rcpf(1.0f + __builtin_amdgcn_exp2f(-1.4426950408889634f * g)) * up; }
; __device__ __forceinline__ float2 cmul(float2 a, float2 b) { return make_float2(a.x * b.x - a.y * b.y, a.x * b.y + a.y * b.x); }
; template <int LR, bool INV>
; __device__ __forceinline__ void fft_stages(float2 (&x)[1 << LR], const int r, const int s) {
;   constexpr int R = 1 << LR;
; #pragma unroll
;   for (int st = 0; st < LR; ++st) {
;     const int hl = INV ? (1 << st) : (R >> (st + 1));
;     const float fb = (float)r * (0.5f / (float)(hl * s));
;     const float2 wb = make_float2(__builtin_amdgcn_cosf(fb), INV ? __builtin_amdgcn_sinf(fb) : -__builtin_amdgcn_sinf(fb));
; #pragma unroll
;     for (int m = 0; m < R; ++m) {
;       if (m & hl) continue;
;       const int k = m & (hl - 1); const int j = k * (8 / hl);
;       const float2 wc = make_float2(c16(j), INV ? s16(j) : -s16(j));
;       const float2 tw = cmul(wb, wc);
;       if (!INV) { const float2 p = x[m], q = x[m + hl]; x[m] = make_float2(p.x + q.x, p.y + q.y); x[m + hl] = cmul(make_float2(p.x - q.x, p.y - q.y), tw); }
;       else { const float2 p = x[m], q = cmul(x[m + hl], tw); x[m] = make_float2(p.x + q.x, p.y + q.y); x[m + hl] = make_float2(p.x - q.x, p.y - q.y); }
;     }
; template <int LR, bool INV>
; __device__ __forceinline__ void fft_pass(float2* X, const int N, const int sl, const int tid) {
;     ...
; #pragma unroll
;     for (int m = 0; m < R; ++m) X[PIDX(i0 + (m << sl))] = x[m];
	v_pk_mul_f32 v[40:41], v[20:21], v[32:33] op_sel:[0,1]
	ds_write_b64 v50, v[44:45] offset:13056
	v_fma_f32 v42, v0, v32, -v40
	v_fma_f32 v43, v1, v32, v41

; __device__ __forceinline__ float2 cmul(float2 a, float2 b) { return make_float2(a.x * b.x - a.y * b.y, a.x * b.y + a.y * b.x); }
; template <int LR, bool INV>
; __device__ __forceinline__ void fft_stages(float2 (&x)[1 << LR], const int r, const int s) {
;   constexpr int R = 1 << LR;
; #pragma unroll
;   for (int st = 0; st < LR; ++st) {
;     const int hl = INV ? (1 << st) : (R >> (st + 1));
;     const float fb = (float)r * (0.5f / (float)(hl * s));
;     const float2 wb = make_float2(__builtin_amdgcn_cosf(fb), INV ? __builtin_amdgcn_sinf(fb) : -__builtin_amdgcn_sinf(fb));
; #pragma unroll
;     for (int m = 0; m < R; ++m) {
;       if (m & hl) continue;
;       const int k = m & (hl - 1); const int j = k * (8 / hl);
;       const float2 wc = make_float2(c16(j), INV ? s16(j) : -s16(j));
;       const float2 tw = cmul(wb, wc);
;       if (!INV) { const float2 p = x[m], q = x[m + hl]; x[m] = make_float2(p.x + q.x, p.y + q.y); x[m + hl] = cmul(make_float2(p.x - q.x, p.y - q.y), tw); }
;       else { const float2 p = x[m], q = cmul(x[m + hl], tw); x[m] = make_float2(p.x + q.x, p.y + q.y); x[m + hl] = make_float2(p.x - q.x, p.y - q.y); }
;     }
	v_pk_mul_f32 v[32:33], v[22:23], v[34:35] op_sel:[0,1]
	s_nop 0
	v_fma_f32 v40, v2, v34, -v32
	v_fma_f32 v41, v3, v34, v33

; __device__ __forceinline__ float2 cmul(float2 a, float2 b) { return make_float2(a.x * b.x - a.y * b.y, a.x * b.y + a.y * b.x); }
; template <int LR, bool INV>
; __device__ __forceinline__ void fft_stages(float2 (&x)[1 << LR], const int r, const int s) {
;   constexpr int R = 1 << LR;
; #pragma unroll
;   for (int st = 0; st < LR; ++st) {
;     const int hl = INV ? (1 << st) : (R >> (st + 1));
;     const float fb = (float)r * (0.5f / (float)(hl * s));
;     const float2 wb = make_float2(__builtin_amdgcn_cosf(fb), INV ? __builtin_amdgcn_sinf(fb) : -__builtin_amdgcn_sinf(fb));
; #pragma unroll
;     for (int m = 0; m < R; ++m) {
;       if (m & hl) continue;
;       const int k = m & (hl - 1); const int j = k * (8 / hl);
;       const float2 wc = make_float2(c16(j), INV ? s16(j) : -s16(j));
;       const float2 tw = cmul(wb, wc);
;       if (!INV) { const float2 p = x[m], q = x[m + hl]; x[m] = make_float2(p.x + q.x, p.y + q.y); x[m + hl] = cmul(make_float2(p.x - q.x, p.y - q.y), tw); }
;       else { const float2 p = x[m], q = cmul(x[m + hl], tw); x[m] = make_float2(p.x + q.x, p.y + q.y); x[m + hl] = make_float2(p.x - q.x, p.y - q.y); }
;     }
	v_pk_mul_f32 v[32:33], v[24:25], v[36:37] op_sel:[0,1]
	s_nop 0
	v_fma_f32 v34, v4, v36, -v32
	v_fma_f32 v35, v5, v36, v33

; __device__ __forceinline__ float2 cmul(float2 a, float2 b) { return make_float2(a.x * b.x - a.y * b.y, a.x * b.y + a.y * b.x); }
; template <int LR, bool INV>
; __device__ __forceinline__ void fft_stages(float2 (&x)[1 << LR], const int r, const int s) {
;   constexpr int R = 1 << LR;
; #pragma unroll
;   for (int st = 0; st < LR; ++st) {
;     const int hl = INV ? (1 << st) : (R >> (st + 1));
;     const float fb = (float)r * (0.5f / (float)(hl * s));
;     const float2 wb = make_float2(__builtin_amdgcn_cosf(fb), INV ? __builtin_amdgcn_sinf(fb) : -__builtin_amdgcn_sinf(fb));
; #pragma unroll
;     for (int m = 0; m < R; ++m) {
;       if (m & hl) continue;
;       const int k = m & (hl - 1); const int j = k * (8 / hl);
;       const float2 wc = make_float2(c16(j), INV ? s16(j) : -s16(j));
;       const float2 tw = cmul(wb, wc);
;       if (!INV) { const float2 p = x[m], q = x[m + hl]; x[m] = make_float2(p.x + q.x, p.y + q.y); x[m + hl] = cmul(make_float2(p.x - q.x, p.y - q.y), tw); }
;       else { const float2 p = x[m], q = cmul(x[m + hl], tw); x[m] = make_float2(p.x + q.x, p.y + q.y); x[m + hl] = make_float2(p.x - q.x, p.y - q.y); }
;     }
	v_pk_mul_f32 v[32:33], v[26:27], v[38:39] op_sel:[0,1]
	s_nop 0
	v_fma_f32 v36, v6, v38, -v32
	v_fma_f32 v37, v7, v38, v33

; __device__ __forceinline__ float2 cmul(float2 a, float2 b) { return make_float2(a.x * b.x - a.y * b.y, a.x * b.y + a.y * b.x); }
; template <int LR, bool INV>
; __device__ __forceinline__ void fft_stages(float2 (&x)[1 << LR], const int r, const int s) {
;     ...
;     for (int m = 0; m < R; ++m) {
;       if (m & hl) continue;
;       const int k = m & (hl - 1); const int j = k * (8 / hl);
;       const float2 wc = make_float2(c16(j), INV ? s16(j) : -s16(j));
;       const float2 tw = cmul(wb, wc);
;       if (!INV) { const float2 p = x[m], q = x[m + hl]; x[m] = make_float2(p.x + q.x, p.y + q.y); x[m + hl] = cmul(make_float2(p.x - q.x, p.y - q.y), tw); }
;       else { const float2 p = x[m], q = cmul(x[m + hl], tw); x[m] = make_float2(p.x + q.x, p.y + q.y); x[m + hl] = make_float2(p.x - q.x, p.y - q.y); }
;     }
	v_pk_add_f32 v[32:33], v[42:43], v[34:35]
	v_pk_add_f32 v[38:39], v[40:41], v[36:37]
	v_pk_add_f32 v[36:37], v[40:41], v[36:37] neg_lo:[0,1] neg_hi:[0,1]
	v_pk_add_f32 v[40:41], v[32:33], v[38:39]
	v_pk_add_f32 v[32:33], v[32:33], v[38:39] neg_lo:[0,1] neg_hi:[0,1]
	v_pk_add_f32 v[34:35], v[42:43], v[34:35] neg_lo:[0,1] neg_hi:[0,1]
	v_pk_mul_f32 v[38:39], v[14:15], v[32:33] op_sel:[0,1]
	ds_write_b64 v50, v[40:41] offset:17408
	v_fma_f32 v40, v12, v32, -v38
	v_fma_f32 v41, v13, v32, v39

; __device__ __forceinline__ float2 cmul(float2 a, float2 b) { return make_float2(a.x * b.x - a.y * b.y, a.x * b.y + a.y * b.x); }
; template <int LR, bool INV>
; __device__ __forceinline__ void fft_stages(float2 (&x)[1 << LR], const int r, const int s) {
;     ...
;       const float2 tw = cmul(wb, wc);
;       if (!INV) { const float2 p = x[m], q = x[m + hl]; x[m] = make_float2(p.x + q.x, p.y + q.y); x[m + hl] = cmul(make_float2(p.x - q.x, p.y - q.y), tw); }
	v_pk_mul_f32 v[32:33], v[16:17], v[34:35] op_sel:[0,1]
	ds_write_b64 v50, v[40:41] offset:21760
	v_fma_f32 v38, v8, v34, -v32
	v_fma_f32 v39, v9, v34, v33

; __device__ __forceinline__ float2 cmul(float2 a, float2 b) { return make_float2(a.x * b.x - a.y * b.y, a.x * b.y + a.y * b.x); }
; template <int LR, bool INV>
; __device__ __forceinline__ void fft_stages(float2 (&x)[1 << LR], const int r, const int s) {
;     ...
;       const float2 tw = cmul(wb, wc);
;       if (!INV) { const float2 p = x[m], q = x[m + hl]; x[m] = make_float2(p.x + q.x, p.y + q.y); x[m + hl] = cmul(make_float2(p.x - q.x, p.y - q.y), tw); }
	v_pk_mul_f32 v[32:33], v[18:19], v[36:37] op_sel:[0,1]
	s_nop 0
	v_fma_f32 v34, v10, v36, -v32
	v_fma_f32 v35, v11, v36, v33

;     static __device__ __forceinline__ float sl(float g, float up) { return g * __builtin_amdgcn_rcpf(1.0f + __builtin_amdgcn_exp2f(-1.4426950408889634f * g)) * up; }
; __device__ __forceinline__ float2 cmul(float2 a, float2 b) { return make_float2(a.x * b.x - a.y * b.y, a.x * b.y + a.y * b.x); }
; template <int LR, bool INV>
; __device__ __forceinline__ void fft_stages(float2 (&x)[1 << LR], const int r, const int s) {
;     ...
;     for (int m = 0; m < R; ++m) {
;       if (m & hl) continue;
;       const int k = m & (hl - 1); const int j = k * (8 / hl);
;       const float2 wc = make_float2(c16(j), INV ? s16(j) : -s16(j));
;       const float2 tw = cmul(wb, wc);
;       if (!INV) { const float2 p = x[m], q = x[m + hl]; x[m] = make_float2(p.x + q.x, p.y + q.y); x[m + hl] = cmul(make_float2(p.x - q.x, p.y - q.y), tw); }
;       else { const float2 p = x[m], q = cmul(x[m + hl], tw); x[m] = make_float2(p.x + q.x, p.y + q.y); x[m + hl] = make_float2(p.x - q.x, p.y - q.y); }
;     }
; template <int LR, bool INV>
; __device__ __forceinline__ void fft_pass(float2* X, const int N, const int sl, const int tid) {
;     ...
;     for (int m = 0; m < R; ++m) X[PIDX(i0 + (m << sl))] = x[m];
	v_pk_add_f32 v[32:33], v[38:39], v[34:35]
	v_pk_add_f32 v[34:35], v[38:39], v[34:35] neg_lo:[0,1] neg_hi:[0,1]
	ds_write_b64 v50, v[32:33] offset:26112
	v_pk_mul_f32 v[32:33], v[14:15], v[34:35] op_sel:[0,1]
	s_nop 0
	v_fma_f32 v36, v12, v34, -v32
	v_pk_fma_f32 v[32:33], v[12:13], v[34:35], v[32:33] op_sel_hi:[1,0,1]
	s_nop 0
	v_mov_b32_e32 v37, v33
	ds_write_b64 v50, v[36:37] offset:30464
	s_andn2_b64 exec, exec, s[14:15]
	s_cbranch_execnz .LBB0_651

;     static __device__ __forceinline__ float sl(float g, float up) { return g * __builtin_amdgcn_rcpf(1.0f + __builtin_amdgcn_exp2f(-1.4426950408889634f * g)) * up; }
; #define tid ltid()
; template <int LR, bool INV>
; __device__ __forceinline__ void fft_pass(float2* X, const int N, const int sl, const int tid) {
;     ...
;   for (int g = tid; g < (N >> LR); g += NTHR) {
;     const int r = g & (s - 1);
;     const int i0 = ((g >> sl) << (sl + LR)) + r;
;     float2 x[R];
; #pragma unroll
;     for (int m = 0; m < R; ++m) x[m] = X[PIDX(i0 + (m << sl))];
.LBB0_656:
	v_and_or_b32 v64, v63, s2, v61
	v_ashrrev_i32_e32 v65, 4, v64
	v_lshlrev_b32_e32 v66, 3, v64
	v_lshlrev_b32_e32 v65, 3, v65
	v_add3_u32 v98, s52, v66, v65


;     static __device__ __forceinline__ float sl(float g, float up) { return g * __builtin_amdgcn_rcpf(1.0f + __builtin_amdgcn_exp2f(-1.4426950408889634f * g)) * up; }
; __device__ __forceinline__ float2 cmul(float2 a, float2 b) { return make_float2(a.x * b.x - a.y * b.y, a.x * b.y + a.y * b.x); }
; #define tid ltid()
; template <int LR, bool INV>
; __device__ __forceinline__ void fft_stages(float2 (&x)[1 << LR], const int r, const int s) {
;     ...
;     for (int m = 0; m < R; ++m) {
;       if (m & hl) continue;
;       const int k = m & (hl - 1); const int j = k * (8 / hl);
;       const float2 wc = make_float2(c16(j), INV ? s16(j) : -s16(j));
;       const float2 tw = cmul(wb, wc);
;       if (!INV) { const float2 p = x[m], q = x[m + hl]; x[m] = make_float2(p.x + q.x, p.y + q.y); x[m + hl] = cmul(make_float2(p.x - q.x, p.y - q.y), tw); }
;       else { const float2 p = x[m], q = cmul(x[m + hl], tw); x[m] = make_float2(p.x + q.x, p.y + q.y); x[m + hl] = make_float2(p.x - q.x, p.y - q.y); }
;     }
; template <int LR, bool INV>
; __device__ __forceinline__ void fft_pass(float2* X, const int N, const int sl, const int tid) {
;     ...
;   for (int g = tid; g < (N >> LR); g += NTHR) {
;     const int r = g & (s - 1);
;     const int i0 = ((g >> sl) << (sl + LR)) + r;
;     float2 x[R];
; #pragma unroll
;     for (int m = 0; m < R; ++m) x[m] = X[PIDX(i0 + (m << sl))];
	ds_read_b64 v[64:65], v98
	ds_read_b64 v[66:67], v98 offset:4352
	ds_read_b64 v[68:69], v98 offset:8704
	ds_read_b64 v[70:71], v98 offset:13056
	ds_read_b64 v[72:73], v98 offset:17408
	ds_read_b64 v[74:75], v98 offset:21760
	ds_read_b64 v[76:77], v98 offset:26112
	ds_read_b64 v[78:79], v98 offset:30464
	ds_read_b64 v[80:81], v98 offset:34816
	ds_read_b64 v[82:83], v98 offset:39168
	ds_read_b64 v[84:85], v98 offset:43520
	ds_read_b64 v[86:87], v98 offset:47872
	ds_read_b64 v[88:89], v98 offset:52224
	ds_read_b64 v[90:91], v98 offset:56576
	ds_read_b64 v[92:93], v98 offset:60928
	ds_read_b64 v[94:95], v98 offset:65280
	s_waitcnt lgkmcnt(7)
	v_pk_add_f32 v[96:97], v[64:65], v[80:81]
	v_pk_add_f32 v[64:65], v[64:65], v[80:81] neg_lo:[0,1] neg_hi:[0,1]
	s_waitcnt lgkmcnt(6)
	v_pk_add_f32 v[80:81], v[66:67], v[82:83]
	v_pk_add_f32 v[66:67], v[66:67], v[82:83] neg_lo:[0,1] neg_hi:[0,1]
	s_waitcnt lgkmcnt(5)
	v_pk_add_f32 v[82:83], v[68:69], v[84:85]
	v_pk_add_f32 v[68:69], v[68:69], v[84:85] neg_lo:[0,1] neg_hi:[0,1]
	s_waitcnt lgkmcnt(4)
	v_pk_add_f32 v[84:85], v[70:71], v[86:87]
	v_pk_add_f32 v[70:71], v[70:71], v[86:87] neg_lo:[0,1] neg_hi:[0,1]
	s_waitcnt lgkmcnt(3)
	v_pk_add_f32 v[86:87], v[72:73], v[88:89]
	v_pk_add_f32 v[72:73], v[72:73], v[88:89] neg_lo:[0,1] neg_hi:[0,1]
	s_waitcnt lgkmcnt(2)
	v_pk_add_f32 v[88:89], v[74:75], v[90:91]
	v_pk_add_f32 v[74:75], v[74:75], v[90:91] neg_lo:[0,1] neg_hi:[0,1]
	s_waitcnt lgkmcnt(1)
	v_pk_add_f32 v[90:91], v[76:77], v[92:93]
	v_pk_add_f32 v[76:77], v[76:77], v[92:93] neg_lo:[0,1] neg_hi:[0,1]
	s_waitcnt lgkmcnt(0)
	v_pk_add_f32 v[92:93], v[78:79], v[94:95]
	v_pk_add_f32 v[78:79], v[78:79], v[94:95] neg_lo:[0,1] neg_hi:[0,1]
	v_pk_add_f32 v[94:95], v[96:97], v[86:87]
	v_pk_add_f32 v[86:87], v[96:97], v[86:87] neg_lo:[0,1] neg_hi:[0,1]
	v_pk_add_f32 v[96:97], v[80:81], v[88:89]
	v_pk_add_f32 v[80:81], v[80:81], v[88:89] neg_lo:[0,1] neg_hi:[0,1]
	v_pk_add_f32 v[88:89], v[82:83], v[90:91]
	v_pk_add_f32 v[82:83], v[82:83], v[90:91] neg_lo:[0,1] neg_hi:[0,1]
	v_pk_add_f32 v[90:91], v[84:85], v[92:93]
	v_pk_add_f32 v[84:85], v[84:85], v[92:93] neg_lo:[0,1] neg_hi:[0,1]
	v_pk_add_f32 v[92:93], v[94:95], v[88:89]
	v_pk_add_f32 v[88:89], v[94:95], v[88:89] neg_lo:[0,1] neg_hi:[0,1]
	v_pk_add_f32 v[94:95], v[96:97], v[90:91]
	v_pk_add_f32 v[90:91], v[96:97], v[90:91] neg_lo:[0,1] neg_hi:[0,1]
	v_pk_add_f32 v[96:97], v[92:93], v[94:95]
	v_pk_add_f32 v[92:93], v[92:93], v[94:95] neg_lo:[0,1] neg_hi:[0,1]
	ds_write_b64 v98, v[96:97]
	v_pk_mul_f32 v[94:95], v[30:31], v[92:93] op_sel:[0,1]
	v_add_u32_e32 v62, 0x200, v62
	v_fma_f32 v96, v28, v92, -v94
	v_fma_f32 v97, v29, v92, v95
	v_cmp_lt_i32_e32 vcc, -1, v62

; __device__ __forceinline__ float2 cmul(float2 a, float2 b) { return make_float2(a.x * b.x - a.y * b.y, a.x * b.y + a.y * b.x); }
; template <int LR, bool INV>
; __device__ __forceinline__ void fft_stages(float2 (&x)[1 << LR], const int r, const int s) {
;     ...
;       const float2 tw = cmul(wb, wc);
;       if (!INV) { const float2 p = x[m], q = x[m + hl]; x[m] = make_float2(p.x + q.x, p.y + q.y); x[m + hl] = cmul(make_float2(p.x - q.x, p.y - q.y), tw); }
	v_pk_mul_f32 v[92:93], v[32:33], v[88:89] op_sel:[0,1]
	ds_write_b64 v98, v[96:97] offset:4352
	v_fma_f32 v94, v24, v88, -v92
	v_fma_f32 v95, v25, v88, v93
	v_add_u32_e32 v63, 0x2000, v63

; __device__ __forceinline__ float2 cmul(float2 a, float2 b) { return make_float2(a.x * b.x - a.y * b.y, a.x * b.y + a.y * b.x); }
; template <int LR, bool INV>
; __device__ __forceinline__ void fft_stages(float2 (&x)[1 << LR], const int r, const int s) {
;     ...
;       const float2 tw = cmul(wb, wc);
;       if (!INV) { const float2 p = x[m], q = x[m + hl]; x[m] = make_float2(p.x + q.x, p.y + q.y); x[m + hl] = cmul(make_float2(p.x - q.x, p.y - q.y), tw); }
	v_pk_mul_f32 v[88:89], v[34:35], v[90:91] op_sel:[0,1]
	s_or_b64 s[14:15], vcc, s[14:15]
	v_fma_f32 v92, v26, v90, -v88
	v_fma_f32 v93, v27, v90, v89

; __device__ __forceinline__ float2 cmul(float2 a, float2 b) { return make_float2(a.x * b.x - a.y * b.y, a.x * b.y + a.y * b.x); }
; template <int LR, bool INV>
; __device__ __forceinline__ void fft_stages(float2 (&x)[1 << LR], const int r, const int s) {
;     ...
;     for (int m = 0; m < R; ++m) {
;       if (m & hl) continue;
;       const int k = m & (hl - 1); const int j = k * (8 / hl);
;       const float2 wc = make_float2(c16(j), INV ? s16(j) : -s16(j));
;       const float2 tw = cmul(wb, wc);
;       if (!INV) { const float2 p = x[m], q = x[m + hl]; x[m] = make_float2(p.x + q.x, p.y + q.y); x[m + hl] = cmul(make_float2(p.x - q.x, p.y - q.y), tw); }
;       else { const float2 p = x[m], q = cmul(x[m + hl], tw); x[m] = make_float2(p.x + q.x, p.y + q.y); x[m + hl] = make_float2(p.x - q.x, p.y - q.y); }
;     }
	v_pk_add_f32 v[88:89], v[94:95], v[92:93]
	v_pk_add_f32 v[90:91], v[94:95], v[92:93] neg_lo:[0,1] neg_hi:[0,1]
	ds_write_b64 v98, v[88:89] offset:8704
	v_pk_mul_f32 v[88:89], v[30:31], v[90:91] op_sel:[0,1]
	s_nop 0
	v_fma_f32 v92, v28, v90, -v88
	v_fma_f32 v93, v29, v90, v89

; __device__ __forceinline__ float2 cmul(float2 a, float2 b) { return make_float2(a.x * b.x - a.y * b.y, a.x * b.y + a.y * b.x); }
; template <int LR, bool INV>
; __device__ __forceinline__ void fft_stages(float2 (&x)[1 << LR], const int r, const int s) {
;     ...
;       const float2 tw = cmul(wb, wc);
;       if (!INV) { const float2 p = x[m], q = x[m + hl]; x[m] = make_float2(p.x + q.x, p.y + q.y); x[m + hl] = cmul(make_float2(p.x - q.x, p.y - q.y), tw); }
	v_pk_mul_f32 v[88:89], v[36:37], v[86:87] op_sel:[0,1]
	ds_write_b64 v98, v[92:93] offset:13056
	v_fma_f32 v90, v16, v86, -v88
	v_fma_f32 v91, v17, v86, v89

; __device__ __forceinline__ float2 cmul(float2 a, float2 b) { return make_float2(a.x * b.x - a.y * b.y, a.x * b.y + a.y * b.x); }
; template <int LR, bool INV>
; __device__ __forceinline__ void fft_stages(float2 (&x)[1 << LR], const int r, const int s) {
;     ...
;       const float2 tw = cmul(wb, wc);
;       if (!INV) { const float2 p = x[m], q = x[m + hl]; x[m] = make_float2(p.x + q.x, p.y + q.y); x[m + hl] = cmul(make_float2(p.x - q.x, p.y - q.y), tw); }
	v_pk_mul_f32 v[86:87], v[38:39], v[80:81] op_sel:[0,1]
	s_nop 0
	v_fma_f32 v88, v18, v80, -v86
	v_fma_f32 v89, v19, v80, v87

; __device__ __forceinline__ float2 cmul(float2 a, float2 b) { return make_float2(a.x * b.x - a.y * b.y, a.x * b.y + a.y * b.x); }
; template <int LR, bool INV>
; __device__ __forceinline__ void fft_stages(float2 (&x)[1 << LR], const int r, const int s) {
;     ...
;       const float2 tw = cmul(wb, wc);
;       if (!INV) { const float2 p = x[m], q = x[m + hl]; x[m] = make_float2(p.x + q.x, p.y + q.y); x[m + hl] = cmul(make_float2(p.x - q.x, p.y - q.y), tw); }
	v_pk_mul_f32 v[80:81], v[40:41], v[82:83] op_sel:[0,1]
	s_nop 0
	v_fma_f32 v86, v20, v82, -v80
	v_fma_f32 v87, v21, v82, v81

; __device__ __forceinline__ float2 cmul(float2 a, float2 b) { return make_float2(a.x * b.x - a.y * b.y, a.x * b.y + a.y * b.x); }
; template <int LR, bool INV>
; __device__ __forceinline__ void fft_stages(float2 (&x)[1 << LR], const int r, const int s) {
;     ...
;     for (int m = 0; m < R; ++m) {
;       if (m & hl) continue;
;       const int k = m & (hl - 1); const int j = k * (8 / hl);
;       const float2 wc = make_float2(c16(j), INV ? s16(j) : -s16(j));
;       const float2 tw = cmul(wb, wc);
;       if (!INV) { const float2 p = x[m], q = x[m + hl]; x[m] = make_float2(p.x + q.x, p.y + q.y); x[m + hl] = cmul(make_float2(p.x - q.x, p.y - q.y), tw); }
;       else { const float2 p = x[m], q = cmul(x[m + hl], tw); x[m] = make_float2(p.x + q.x, p.y + q.y); x[m + hl] = make_float2(p.x - q.x, p.y - q.y); }
;     }
	v_pk_mul_f32 v[80:81], v[42:43], v[84:85] op_sel:[0,1]
	s_nop 0
	v_fma_f32 v82, v22, v84, -v80
	v_fma_f32 v83, v23, v84, v81
	v_pk_add_f32 v[84:85], v[90:91], v[86:87] neg_lo:[0,1] neg_hi:[0,1]

; __device__ __forceinline__ float2 cmul(float2 a, float2 b) { return make_float2(a.x * b.x - a.y * b.y, a.x * b.y + a.y * b.x); }
; template <int LR, bool INV>
; __device__ __forceinline__ void fft_stages(float2 (&x)[1 << LR], const int r, const int s) {
;     ...
;     for (int m = 0; m < R; ++m) {
;       if (m & hl) continue;
;       const int k = m & (hl - 1); const int j = k * (8 / hl);
;       const float2 wc = make_float2(c16(j), INV ? s16(j) : -s16(j));
;       const float2 tw = cmul(wb, wc);
;       if (!INV) { const float2 p = x[m], q = x[m + hl]; x[m] = make_float2(p.x + q.x, p.y + q.y); x[m + hl] = cmul(make_float2(p.x - q.x, p.y - q.y), tw); }
;       else { const float2 p = x[m], q = cmul(x[m + hl], tw); x[m] = make_float2(p.x + q.x, p.y + q.y); x[m + hl] = make_float2(p.x - q.x, p.y - q.y); }
;     }
	v_pk_add_f32 v[80:81], v[90:91], v[86:87]
	v_pk_add_f32 v[86:87], v[88:89], v[82:83]
	v_pk_add_f32 v[82:83], v[88:89], v[82:83] neg_lo:[0,1] neg_hi:[0,1]
	v_pk_add_f32 v[88:89], v[80:81], v[86:87]
	v_pk_add_f32 v[80:81], v[80:81], v[86:87] neg_lo:[0,1] neg_hi:[0,1]
	ds_write_b64 v98, v[88:89] offset:17408
	v_pk_mul_f32 v[86:87], v[30:31], v[80:81] op_sel:[0,1]
	s_nop 0
	v_fma_f32 v88, v28, v80, -v86
	v_fma_f32 v89, v29, v80, v87

; __device__ __forceinline__ float2 cmul(float2 a, float2 b) { return make_float2(a.x * b.x - a.y * b.y, a.x * b.y + a.y * b.x); }
; template <int LR, bool INV>
; __device__ __forceinline__ void fft_stages(float2 (&x)[1 << LR], const int r, const int s) {
;     ...
;       const float2 tw = cmul(wb, wc);
;       if (!INV) { const float2 p = x[m], q = x[m + hl]; x[m] = make_float2(p.x + q.x, p.y + q.y); x[m + hl] = cmul(make_float2(p.x - q.x, p.y - q.y), tw); }
	v_pk_mul_f32 v[80:81], v[32:33], v[84:85] op_sel:[0,1]
	ds_write_b64 v98, v[88:89] offset:21760
	v_fma_f32 v86, v24, v84, -v80
	v_fma_f32 v87, v25, v84, v81

; __device__ __forceinline__ float2 cmul(float2 a, float2 b) { return make_float2(a.x * b.x - a.y * b.y, a.x * b.y + a.y * b.x); }
; template <int LR, bool INV>
; __device__ __forceinline__ void fft_stages(float2 (&x)[1 << LR], const int r, const int s) {
;     ...
;       const float2 tw = cmul(wb, wc);
;       if (!INV) { const float2 p = x[m], q = x[m + hl]; x[m] = make_float2(p.x + q.x, p.y + q.y); x[m + hl] = cmul(make_float2(p.x - q.x, p.y - q.y), tw); }
	v_pk_mul_f32 v[80:81], v[34:35], v[82:83] op_sel:[0,1]
	s_nop 0
	v_fma_f32 v84, v26, v82, -v80
	v_fma_f32 v85, v27, v82, v81

; __device__ __forceinline__ float2 cmul(float2 a, float2 b) { return make_float2(a.x * b.x - a.y * b.y, a.x * b.y + a.y * b.x); }
; template <int LR, bool INV>
; __device__ __forceinline__ void fft_stages(float2 (&x)[1 << LR], const int r, const int s) {
;     ...
;     for (int m = 0; m < R; ++m) {
;       if (m & hl) continue;
;       const int k = m & (hl - 1); const int j = k * (8 / hl);
;       const float2 wc = make_float2(c16(j), INV ? s16(j) : -s16(j));
;       const float2 tw = cmul(wb, wc);
;       if (!INV) { const float2 p = x[m], q = x[m + hl]; x[m] = make_float2(p.x + q.x, p.y + q.y); x[m + hl] = cmul(make_float2(p.x - q.x, p.y - q.y), tw); }
;       else { const float2 p = x[m], q = cmul(x[m + hl], tw); x[m] = make_float2(p.x + q.x, p.y + q.y); x[m + hl] = make_float2(p.x - q.x, p.y - q.y); }
;     }
	v_pk_add_f32 v[80:81], v[86:87], v[84:85]
	v_pk_add_f32 v[82:83], v[86:87], v[84:85] neg_lo:[0,1] neg_hi:[0,1]
	ds_write_b64 v98, v[80:81] offset:26112
	v_pk_mul_f32 v[80:81], v[30:31], v[82:83] op_sel:[0,1]
	s_nop 0
	v_fma_f32 v84, v28, v82, -v80
	v_fma_f32 v85, v29, v82, v81

; __device__ __forceinline__ float2 cmul(float2 a, float2 b) { return make_float2(a.x * b.x - a.y * b.y, a.x * b.y + a.y * b.x); }
; template <int LR, bool INV>
; __device__ __forceinline__ void fft_stages(float2 (&x)[1 << LR], const int r, const int s) {
;     ...
;       const float2 tw = cmul(wb, wc);
;       if (!INV) { const float2 p = x[m], q = x[m + hl]; x[m] = make_float2(p.x + q.x, p.y + q.y); x[m + hl] = cmul(make_float2(p.x - q.x, p.y - q.y), tw); }
	v_pk_mul_f32 v[80:81], v[44:45], v[64:65] op_sel:[0,1]
	ds_write_b64 v98, v[84:85] offset:30464
	v_fma_f32 v82, v0, v64, -v80
	v_fma_f32 v83, v1, v64, v81

; __device__ __forceinline__ float2 cmul(float2 a, float2 b) { return make_float2(a.x * b.x - a.y * b.y, a.x * b.y + a.y * b.x); }
; template <int LR, bool INV>
; __device__ __forceinline__ void fft_stages(float2 (&x)[1 << LR], const int r, const int s) {
;     ...
;       const float2 tw = cmul(wb, wc);
;       if (!INV) { const float2 p = x[m], q = x[m + hl]; x[m] = make_float2(p.x + q.x, p.y + q.y); x[m + hl] = cmul(make_float2(p.x - q.x, p.y - q.y), tw); }
	v_pk_mul_f32 v[64:65], v[46:47], v[66:67] op_sel:[0,1]
	s_nop 0
	v_fma_f32 v80, v2, v66, -v64
	v_fma_f32 v81, v3, v66, v65

; __device__ __forceinline__ float2 cmul(float2 a, float2 b) { return make_float2(a.x * b.x - a.y * b.y, a.x * b.y + a.y * b.x); }
; template <int LR, bool INV>
; __device__ __forceinline__ void fft_stages(float2 (&x)[1 << LR], const int r, const int s) {
;     ...
;       const float2 tw = cmul(wb, wc);
;       if (!INV) { const float2 p = x[m], q = x[m + hl]; x[m] = make_float2(p.x + q.x, p.y + q.y); x[m + hl] = cmul(make_float2(p.x - q.x, p.y - q.y), tw); }
	v_pk_mul_f32 v[64:65], v[48:49], v[68:69] op_sel:[0,1]
	s_nop 0
	v_fma_f32 v66, v4, v68, -v64
	v_fma_f32 v67, v5, v68, v65

; __device__ __forceinline__ float2 cmul(float2 a, float2 b) { return make_float2(a.x * b.x - a.y * b.y, a.x * b.y + a.y * b.x); }
; template <int LR, bool INV>
; __device__ __forceinline__ void fft_stages(float2 (&x)[1 << LR], const int r, const int s) {
;     ...
;       const float2 tw = cmul(wb, wc);
;       if (!INV) { const float2 p = x[m], q = x[m + hl]; x[m] = make_float2(p.x + q.x, p.y + q.y); x[m + hl] = cmul(make_float2(p.x - q.x, p.y - q.y), tw); }
	v_pk_mul_f32 v[64:65], v[50:51], v[70:71] op_sel:[0,1]
	s_nop 0
	v_fma_f32 v68, v6, v70, -v64
	v_fma_f32 v69, v7, v70, v65

; __device__ __forceinline__ float2 cmul(float2 a, float2 b) { return make_float2(a.x * b.x - a.y * b.y, a.x * b.y + a.y * b.x); }
; template <int LR, bool INV>
; __device__ __forceinline__ void fft_stages(float2 (&x)[1 << LR], const int r, const int s) {
;     ...
;       const float2 tw = cmul(wb, wc);
;       if (!INV) { const float2 p = x[m], q = x[m + hl]; x[m] = make_float2(p.x + q.x, p.y + q.y); x[m + hl] = cmul(make_float2(p.x - q.x, p.y - q.y), tw); }
	v_pk_mul_f32 v[64:65], v[52:53], v[72:73] op_sel:[0,1]
	s_nop 0
	v_fma_f32 v70, v8, v72, -v64
	v_fma_f32 v71, v9, v72, v65

; __device__ __forceinline__ float2 cmul(float2 a, float2 b) { return make_float2(a.x * b.x - a.y * b.y, a.x * b.y + a.y * b.x); }
; template <int LR, bool INV>
; __device__ __forceinline__ void fft_stages(float2 (&x)[1 << LR], const int r, const int s) {
;     ...
;       const float2 tw = cmul(wb, wc);
;       if (!INV) { const float2 p = x[m], q = x[m + hl]; x[m] = make_float2(p.x + q.x, p.y + q.y); x[m + hl] = cmul(make_float2(p.x - q.x, p.y - q.y), tw); }
	v_pk_mul_f32 v[64:65], v[54:55], v[74:75] op_sel:[0,1]
	s_nop 0
	v_fma_f32 v72, v10, v74, -v64
	v_fma_f32 v73, v11, v74, v65

; __device__ __forceinline__ float2 cmul(float2 a, float2 b) { return make_float2(a.x * b.x - a.y * b.y, a.x * b.y + a.y * b.x); }
; template <int LR, bool INV>
; __device__ __forceinline__ void fft_stages(float2 (&x)[1 << LR], const int r, const int s) {
;     ...
;       const float2 tw = cmul(wb, wc);
;       if (!INV) { const float2 p = x[m], q = x[m + hl]; x[m] = make_float2(p.x + q.x, p.y + q.y); x[m + hl] = cmul(make_float2(p.x - q.x, p.y - q.y), tw); }
	v_pk_mul_f32 v[64:65], v[56:57], v[76:77] op_sel:[0,1]
	s_nop 0
	v_fma_f32 v74, v12, v76, -v64
	v_fma_f32 v75, v13, v76, v65

; __device__ __forceinline__ float2 cmul(float2 a, float2 b) { return make_float2(a.x * b.x - a.y * b.y, a.x * b.y + a.y * b.x); }
; template <int LR, bool INV>
; __device__ __forceinline__ void fft_stages(float2 (&x)[1 << LR], const int r, const int s) {
;     ...
;     for (int m = 0; m < R; ++m) {
;       if (m & hl) continue;
;       const int k = m & (hl - 1); const int j = k * (8 / hl);
;       const float2 wc = make_float2(c16(j), INV ? s16(j) : -s16(j));
;       const float2 tw = cmul(wb, wc);
;       if (!INV) { const float2 p = x[m], q = x[m + hl]; x[m] = make_float2(p.x + q.x, p.y + q.y); x[m + hl] = cmul(make_float2(p.x - q.x, p.y - q.y), tw); }
;       else { const float2 p = x[m], q = cmul(x[m + hl], tw); x[m] = make_float2(p.x + q.x, p.y + q.y); x[m + hl] = make_float2(p.x - q.x, p.y - q.y); }
;     }
	v_pk_mul_f32 v[64:65], v[58:59], v[78:79] op_sel:[0,1]
	s_nop 0
	v_fma_f32 v76, v14, v78, -v64
	v_fma_f32 v77, v15, v78, v65
	v_pk_add_f32 v[78:79], v[80:81], v[72:73]

; __device__ __forceinline__ float2 cmul(float2 a, float2 b) { return make_float2(a.x * b.x - a.y * b.y, a.x * b.y + a.y * b.x); }
; template <int LR, bool INV>
; __device__ __forceinline__ void fft_stages(float2 (&x)[1 << LR], const int r, const int s) {
;     ...
;     for (int m = 0; m < R; ++m) {
;       if (m & hl) continue;
;       const int k = m & (hl - 1); const int j = k * (8 / hl);
;       const float2 wc = make_float2(c16(j), INV ? s16(j) : -s16(j));
;       const float2 tw = cmul(wb, wc);
;       if (!INV) { const float2 p = x[m], q = x[m + hl]; x[m] = make_float2(p.x + q.x, p.y + q.y); x[m + hl] = cmul(make_float2(p.x - q.x, p.y - q.y), tw); }
;       else { const float2 p = x[m], q = cmul(x[m + hl], tw); x[m] = make_float2(p.x + q.x, p.y + q.y); x[m + hl] = make_float2(p.x - q.x, p.y - q.y); }
;     }
	v_pk_add_f32 v[64:65], v[82:83], v[70:71]
	v_pk_add_f32 v[72:73], v[80:81], v[72:73] neg_lo:[0,1] neg_hi:[0,1]
	v_pk_add_f32 v[80:81], v[66:67], v[74:75]
	v_pk_add_f32 v[66:67], v[66:67], v[74:75] neg_lo:[0,1] neg_hi:[0,1]
	v_pk_add_f32 v[74:75], v[68:69], v[76:77]
	v_pk_add_f32 v[68:69], v[68:69], v[76:77] neg_lo:[0,1] neg_hi:[0,1]
	v_pk_add_f32 v[76:77], v[64:65], v[80:81]
	v_pk_add_f32 v[64:65], v[64:65], v[80:81] neg_lo:[0,1] neg_hi:[0,1]
	v_pk_add_f32 v[80:81], v[78:79], v[74:75]
	v_pk_add_f32 v[74:75], v[78:79], v[74:75] neg_lo:[0,1] neg_hi:[0,1]
	v_pk_add_f32 v[78:79], v[76:77], v[80:81]
	v_pk_add_f32 v[76:77], v[76:77], v[80:81] neg_lo:[0,1] neg_hi:[0,1]
	ds_write_b64 v98, v[78:79] offset:34816
	v_pk_mul_f32 v[78:79], v[30:31], v[76:77] op_sel:[0,1]
	v_pk_add_f32 v[70:71], v[82:83], v[70:71] neg_lo:[0,1] neg_hi:[0,1]
	v_fma_f32 v80, v28, v76, -v78
	v_fma_f32 v81, v29, v76, v79

; __device__ __forceinline__ float2 cmul(float2 a, float2 b) { return make_float2(a.x * b.x - a.y * b.y, a.x * b.y + a.y * b.x); }
; template <int LR, bool INV>
; __device__ __forceinline__ void fft_stages(float2 (&x)[1 << LR], const int r, const int s) {
;     ...
;       const float2 tw = cmul(wb, wc);
;       if (!INV) { const float2 p = x[m], q = x[m + hl]; x[m] = make_float2(p.x + q.x, p.y + q.y); x[m + hl] = cmul(make_float2(p.x - q.x, p.y - q.y), tw); }
	v_pk_mul_f32 v[76:77], v[32:33], v[64:65] op_sel:[0,1]
	ds_write_b64 v98, v[80:81] offset:39168
	v_fma_f32 v78, v24, v64, -v76
	v_fma_f32 v79, v25, v64, v77

; __device__ __forceinline__ float2 cmul(float2 a, float2 b) { return make_float2(a.x * b.x - a.y * b.y, a.x * b.y + a.y * b.x); }
; template <int LR, bool INV>
; __device__ __forceinline__ void fft_stages(float2 (&x)[1 << LR], const int r, const int s) {
;     ...
;       const float2 tw = cmul(wb, wc);
;       if (!INV) { const float2 p = x[m], q = x[m + hl]; x[m] = make_float2(p.x + q.x, p.y + q.y); x[m + hl] = cmul(make_float2(p.x - q.x, p.y - q.y), tw); }
	v_pk_mul_f32 v[64:65], v[34:35], v[74:75] op_sel:[0,1]
	s_nop 0
	v_fma_f32 v76, v26, v74, -v64
	v_fma_f32 v77, v27, v74, v65

; __device__ __forceinline__ float2 cmul(float2 a, float2 b) { return make_float2(a.x * b.x - a.y * b.y, a.x * b.y + a.y * b.x); }
; template <int LR, bool INV>
; __device__ __forceinline__ void fft_stages(float2 (&x)[1 << LR], const int r, const int s) {
;     ...
;     for (int m = 0; m < R; ++m) {
;       if (m & hl) continue;
;       const int k = m & (hl - 1); const int j = k * (8 / hl);
;       const float2 wc = make_float2(c16(j), INV ? s16(j) : -s16(j));
;       const float2 tw = cmul(wb, wc);
;       if (!INV) { const float2 p = x[m], q = x[m + hl]; x[m] = make_float2(p.x + q.x, p.y + q.y); x[m + hl] = cmul(make_float2(p.x - q.x, p.y - q.y), tw); }
;       else { const float2 p = x[m], q = cmul(x[m + hl], tw); x[m] = make_float2(p.x + q.x, p.y + q.y); x[m + hl] = make_float2(p.x - q.x, p.y - q.y); }
;     }
	v_pk_add_f32 v[64:65], v[78:79], v[76:77]
	v_pk_add_f32 v[74:75], v[78:79], v[76:77] neg_lo:[0,1] neg_hi:[0,1]
	ds_write_b64 v98, v[64:65] offset:43520
	v_pk_mul_f32 v[64:65], v[30:31], v[74:75] op_sel:[0,1]
	s_nop 0
	v_fma_f32 v76, v28, v74, -v64
	v_fma_f32 v77, v29, v74, v65

; __device__ __forceinline__ float2 cmul(float2 a, float2 b) { return make_float2(a.x * b.x - a.y * b.y, a.x * b.y + a.y * b.x); }
; template <int LR, bool INV>
; __device__ __forceinline__ void fft_stages(float2 (&x)[1 << LR], const int r, const int s) {
;     ...
;       const float2 tw = cmul(wb, wc);
;       if (!INV) { const float2 p = x[m], q = x[m + hl]; x[m] = make_float2(p.x + q.x, p.y + q.y); x[m + hl] = cmul(make_float2(p.x - q.x, p.y - q.y), tw); }
	v_pk_mul_f32 v[64:65], v[36:37], v[70:71] op_sel:[0,1]
	ds_write_b64 v98, v[76:77] offset:47872
	v_fma_f32 v74, v16, v70, -v64
	v_fma_f32 v75, v17, v70, v65

; __device__ __forceinline__ float2 cmul(float2 a, float2 b) { return make_float2(a.x * b.x - a.y * b.y, a.x * b.y + a.y * b.x); }
; template <int LR, bool INV>
; __device__ __forceinline__ void fft_stages(float2 (&x)[1 << LR], const int r, const int s) {
;     ...
;       const float2 tw = cmul(wb, wc);
;       if (!INV) { const float2 p = x[m], q = x[m + hl]; x[m] = make_float2(p.x + q.x, p.y + q.y); x[m + hl] = cmul(make_float2(p.x - q.x, p.y - q.y), tw); }
	v_pk_mul_f32 v[64:65], v[38:39], v[72:73] op_sel:[0,1]
	s_nop 0
	v_fma_f32 v70, v18, v72, -v64
	v_fma_f32 v71, v19, v72, v65

; __device__ __forceinline__ float2 cmul(float2 a, float2 b) { return make_float2(a.x * b.x - a.y * b.y, a.x * b.y + a.y * b.x); }
; template <int LR, bool INV>
; __device__ __forceinline__ void fft_stages(float2 (&x)[1 << LR], const int r, const int s) {
;     ...
;       const float2 tw = cmul(wb, wc);
;       if (!INV) { const float2 p = x[m], q = x[m + hl]; x[m] = make_float2(p.x + q.x, p.y + q.y); x[m + hl] = cmul(make_float2(p.x - q.x, p.y - q.y), tw); }
	v_pk_mul_f32 v[64:65], v[40:41], v[66:67] op_sel:[0,1]
	s_nop 0
	v_fma_f32 v72, v20, v66, -v64
	v_fma_f32 v73, v21, v66, v65

; __device__ __forceinline__ float2 cmul(float2 a, float2 b) { return make_float2(a.x * b.x - a.y * b.y, a.x * b.y + a.y * b.x); }
; template <int LR, bool INV>
; __device__ __forceinline__ void fft_stages(float2 (&x)[1 << LR], const int r, const int s) {
;     ...
;     for (int m = 0; m < R; ++m) {
;       if (m & hl) continue;
;       const int k = m & (hl - 1); const int j = k * (8 / hl);
;       const float2 wc = make_float2(c16(j), INV ? s16(j) : -s16(j));
;       const float2 tw = cmul(wb, wc);
;       if (!INV) { const float2 p = x[m], q = x[m + hl]; x[m] = make_float2(p.x + q.x, p.y + q.y); x[m + hl] = cmul(make_float2(p.x - q.x, p.y - q.y), tw); }
;       else { const float2 p = x[m], q = cmul(x[m + hl], tw); x[m] = make_float2(p.x + q.x, p.y + q.y); x[m + hl] = make_float2(p.x - q.x, p.y - q.y); }
;     }
	v_pk_mul_f32 v[64:65], v[42:43], v[68:69] op_sel:[0,1]
	s_nop 0
	v_fma_f32 v66, v22, v68, -v64
	v_fma_f32 v67, v23, v68, v65
	v_pk_add_f32 v[68:69], v[74:75], v[72:73] neg_lo:[0,1] neg_hi:[0,1]

; __device__ __forceinline__ float2 cmul(float2 a, float2 b) { return make_float2(a.x * b.x - a.y * b.y, a.x * b.y + a.y * b.x); }
; template <int LR, bool INV>
; __device__ __forceinline__ void fft_stages(float2 (&x)[1 << LR], const int r, const int s) {
;     ...
;     for (int m = 0; m < R; ++m) {
;       if (m & hl) continue;
;       const int k = m & (hl - 1); const int j = k * (8 / hl);
;       const float2 wc = make_float2(c16(j), INV ? s16(j) : -s16(j));
;       const float2 tw = cmul(wb, wc);
;       if (!INV) { const float2 p = x[m], q = x[m + hl]; x[m] = make_float2(p.x + q.x, p.y + q.y); x[m + hl] = cmul(make_float2(p.x - q.x, p.y - q.y), tw); }
;       else { const float2 p = x[m], q = cmul(x[m + hl], tw); x[m] = make_float2(p.x + q.x, p.y + q.y); x[m + hl] = make_float2(p.x - q.x, p.y - q.y); }
;     }
	v_pk_add_f32 v[64:65], v[74:75], v[72:73]
	v_pk_add_f32 v[72:73], v[70:71], v[66:67]
	v_pk_add_f32 v[66:67], v[70:71], v[66:67] neg_lo:[0,1] neg_hi:[0,1]
	v_pk_add_f32 v[70:71], v[64:65], v[72:73]
	v_pk_add_f32 v[64:65], v[64:65], v[72:73] neg_lo:[0,1] neg_hi:[0,1]
	ds_write_b64 v98, v[70:71] offset:52224
	v_pk_mul_f32 v[70:71], v[30:31], v[64:65] op_sel:[0,1]
	s_nop 0
	v_fma_f32 v72, v28, v64, -v70
	v_fma_f32 v73, v29, v64, v71

; __device__ __forceinline__ float2 cmul(float2 a, float2 b) { return make_float2(a.x * b.x - a.y * b.y, a.x * b.y + a.y * b.x); }
; template <int LR, bool INV>
; __device__ __forceinline__ void fft_stages(float2 (&x)[1 << LR], const int r, const int s) {
;     ...
;       const float2 tw = cmul(wb, wc);
;       if (!INV) { const float2 p = x[m], q = x[m + hl]; x[m] = make_float2(p.x + q.x, p.y + q.y); x[m + hl] = cmul(make_float2(p.x - q.x, p.y - q.y), tw); }
	v_pk_mul_f32 v[64:65], v[32:33], v[68:69] op_sel:[0,1]
	ds_write_b64 v98, v[72:73] offset:56576
	v_fma_f32 v70, v24, v68, -v64
	v_fma_f32 v71, v25, v68, v65

; __device__ __forceinline__ float2 cmul(float2 a, float2 b) { return make_float2(a.x * b.x - a.y * b.y, a.x * b.y + a.y * b.x); }
; template <int LR, bool INV>
; __device__ __forceinline__ void fft_stages(float2 (&x)[1 << LR], const int r, const int s) {
;     ...
;       const float2 tw = cmul(wb, wc);
;       if (!INV) { const float2 p = x[m], q = x[m + hl]; x[m] = make_float2(p.x + q.x, p.y + q.y); x[m + hl] = cmul(make_float2(p.x - q.x, p.y - q.y), tw); }
	v_pk_mul_f32 v[64:65], v[34:35], v[66:67] op_sel:[0,1]
	s_nop 0
	v_fma_f32 v68, v26, v66, -v64
	v_fma_f32 v69, v27, v66, v65

;     static __device__ __forceinline__ float sl(float g, float up) { return g * __builtin_amdgcn_rcpf(1.0f + __builtin_amdgcn_exp2f(-1.4426950408889634f * g)) * up; }
; __device__ __forceinline__ float2 cmul(float2 a, float2 b) { return make_float2(a.x * b.x - a.y * b.y, a.x * b.y + a.y * b.x); }
; template <int LR, bool INV>
; __device__ __forceinline__ void fft_stages(float2 (&x)[1 << LR], const int r, const int s) {
;     ...
;     for (int m = 0; m < R; ++m) {
;       if (m & hl) continue;
;       const int k = m & (hl - 1); const int j = k * (8 / hl);
;       const float2 wc = make_float2(c16(j), INV ? s16(j) : -s16(j));
;       const float2 tw = cmul(wb, wc);
;       if (!INV) { const float2 p = x[m], q = x[m + hl]; x[m] = make_float2(p.x + q.x, p.y + q.y); x[m + hl] = cmul(make_float2(p.x - q.x, p.y - q.y), tw); }
;       else { const float2 p = x[m], q = cmul(x[m + hl], tw); x[m] = make_float2(p.x + q.x, p.y + q.y); x[m + hl] = make_float2(p.x - q.x, p.y - q.y); }
;     }
; template <int LR, bool INV>
; __device__ __forceinline__ void fft_pass(float2* X, const int N, const int sl, const int tid) {
;     ...
;     for (int m = 0; m < R; ++m) X[PIDX(i0 + (m << sl))] = x[m];
	v_pk_add_f32 v[64:65], v[70:71], v[68:69]
	v_pk_add_f32 v[66:67], v[70:71], v[68:69] neg_lo:[0,1] neg_hi:[0,1]
	ds_write_b64 v98, v[64:65] offset:60928
	v_pk_mul_f32 v[64:65], v[30:31], v[66:67] op_sel:[0,1]
	s_nop 0
	v_fma_f32 v68, v28, v66, -v64
	v_fma_f32 v65, v29, v66, v65
	v_mov_b32_e32 v69, v65
	ds_write_b64 v98, v[68:69] offset:65280
	s_andn2_b64 exec, exec, s[14:15]
	s_cbranch_execnz .LBB0_656

;     static __device__ __forceinline__ float sl(float g, float up) { return g * __builtin_amdgcn_rcpf(1.0f + __builtin_amdgcn_exp2f(-1.4426950408889634f * g)) * up; }
; #define tid ltid()
; template <int LR, bool INV>
; __device__ __forceinline__ void fft_pass(float2* X, const int N, const int sl, const int tid) {
;     ...
;   for (int g = tid; g < (N >> LR); g += NTHR) {
;     const int r = g & (s - 1);
;     const int i0 = ((g >> sl) << (sl + LR)) + r;
;     float2 x[R];
; #pragma unroll
;     for (int m = 0; m < R; ++m) x[m] = X[PIDX(i0 + (m << sl))];
.LBB0_660:
	v_and_or_b32 v32, v30, s53, v29
	v_ashrrev_i32_e32 v33, 4, v32
	v_lshlrev_b32_e32 v33, 3, v33
	v_lshlrev_b32_e32 v34, 3, v32
	v_add3_u32 v50, s52, v33, v34


;     static __device__ __forceinline__ float sl(float g, float up) { return g * __builtin_amdgcn_rcpf(1.0f + __builtin_amdgcn_exp2f(-1.4426950408889634f * g)) * up; }
; __device__ __forceinline__ float2 cmul(float2 a, float2 b) { return make_float2(a.x * b.x - a.y * b.y, a.x * b.y + a.y * b.x); }
; #define tid ltid()
; template <int LR, bool INV>
; __device__ __forceinline__ void fft_stages(float2 (&x)[1 << LR], const int r, const int s) {
;     ...
;     for (int m = 0; m < R; ++m) {
;       if (m & hl) continue;
;       const int k = m & (hl - 1); const int j = k * (8 / hl);
;       const float2 wc = make_float2(c16(j), INV ? s16(j) : -s16(j));
;       const float2 tw = cmul(wb, wc);
;       if (!INV) { const float2 p = x[m], q = x[m + hl]; x[m] = make_float2(p.x + q.x, p.y + q.y); x[m + hl] = cmul(make_float2(p.x - q.x, p.y - q.y), tw); }
;       else { const float2 p = x[m], q = cmul(x[m + hl], tw); x[m] = make_float2(p.x + q.x, p.y + q.y); x[m + hl] = make_float2(p.x - q.x, p.y - q.y); }
;     }
; template <int LR, bool INV>
; __device__ __forceinline__ void fft_pass(float2* X, const int N, const int sl, const int tid) {
;     ...
;   for (int g = tid; g < (N >> LR); g += NTHR) {
;     const int r = g & (s - 1);
;     const int i0 = ((g >> sl) << (sl + LR)) + r;
;     float2 x[R];
; #pragma unroll
;     for (int m = 0; m < R; ++m) x[m] = X[PIDX(i0 + (m << sl))];
	ds_read_b64 v[32:33], v50
	ds_read_b64 v[34:35], v50 offset:544
	ds_read_b64 v[36:37], v50 offset:1088
	ds_read_b64 v[38:39], v50 offset:1632
	ds_read_b64 v[40:41], v50 offset:2176
	ds_read_b64 v[42:43], v50 offset:2720
	ds_read_b64 v[44:45], v50 offset:3264
	ds_read_b64 v[46:47], v50 offset:3808
	v_add_u32_e32 v31, 0x200, v31
	s_waitcnt lgkmcnt(3)
	v_pk_add_f32 v[48:49], v[32:33], v[40:41]
	v_pk_add_f32 v[32:33], v[32:33], v[40:41] neg_lo:[0,1] neg_hi:[0,1]
	s_waitcnt lgkmcnt(2)
	v_pk_add_f32 v[40:41], v[34:35], v[42:43]
	v_pk_add_f32 v[34:35], v[34:35], v[42:43] neg_lo:[0,1] neg_hi:[0,1]
	s_waitcnt lgkmcnt(1)
	v_pk_add_f32 v[42:43], v[36:37], v[44:45]
	v_pk_add_f32 v[36:37], v[36:37], v[44:45] neg_lo:[0,1] neg_hi:[0,1]
	s_waitcnt lgkmcnt(0)
	v_pk_add_f32 v[44:45], v[38:39], v[46:47]
	v_pk_add_f32 v[38:39], v[38:39], v[46:47] neg_lo:[0,1] neg_hi:[0,1]
	v_pk_add_f32 v[46:47], v[48:49], v[42:43]
	v_pk_add_f32 v[42:43], v[48:49], v[42:43] neg_lo:[0,1] neg_hi:[0,1]
	v_pk_add_f32 v[48:49], v[40:41], v[44:45]
	v_pk_add_f32 v[40:41], v[40:41], v[44:45] neg_lo:[0,1] neg_hi:[0,1]
	v_pk_add_f32 v[44:45], v[46:47], v[48:49]
	v_pk_add_f32 v[46:47], v[46:47], v[48:49] neg_lo:[0,1] neg_hi:[0,1]
	ds_write_b64 v50, v[44:45]
	v_pk_mul_f32 v[44:45], v[14:15], v[46:47] op_sel:[0,1]
	v_cmp_le_i32_e64 s[40:41], s19, v31
	v_fma_f32 v48, v12, v46, -v44
	v_fma_f32 v49, v13, v46, v45
	v_add_u32_e32 v30, 0x1000, v30

; __device__ __forceinline__ float2 cmul(float2 a, float2 b) { return make_float2(a.x * b.x - a.y * b.y, a.x * b.y + a.y * b.x); }
; template <int LR, bool INV>
; __device__ __forceinline__ void fft_stages(float2 (&x)[1 << LR], const int r, const int s) {
;     ...
;       const float2 tw = cmul(wb, wc);
;       if (!INV) { const float2 p = x[m], q = x[m + hl]; x[m] = make_float2(p.x + q.x, p.y + q.y); x[m + hl] = cmul(make_float2(p.x - q.x, p.y - q.y), tw); }
	v_pk_mul_f32 v[44:45], v[16:17], v[42:43] op_sel:[0,1]
	ds_write_b64 v50, v[48:49] offset:544
	v_fma_f32 v46, v8, v42, -v44
	v_fma_f32 v47, v9, v42, v45
	s_or_b64 s[14:15], s[40:41], s[14:15]

; __device__ __forceinline__ float2 cmul(float2 a, float2 b) { return make_float2(a.x * b.x - a.y * b.y, a.x * b.y + a.y * b.x); }
; template <int LR, bool INV>
; __device__ __forceinline__ void fft_stages(float2 (&x)[1 << LR], const int r, const int s) {
;     ...
;       const float2 tw = cmul(wb, wc);
;       if (!INV) { const float2 p = x[m], q = x[m + hl]; x[m] = make_float2(p.x + q.x, p.y + q.y); x[m + hl] = cmul(make_float2(p.x - q.x, p.y - q.y), tw); }
	v_pk_mul_f32 v[42:43], v[18:19], v[40:41] op_sel:[0,1]
	s_nop 0
	v_fma_f32 v44, v10, v40, -v42
	v_fma_f32 v45, v11, v40, v43

; __device__ __forceinline__ float2 cmul(float2 a, float2 b) { return make_float2(a.x * b.x - a.y * b.y, a.x * b.y + a.y * b.x); }
; template <int LR, bool INV>
; __device__ __forceinline__ void fft_stages(float2 (&x)[1 << LR], const int r, const int s) {
;     ...
;     for (int m = 0; m < R; ++m) {
;       if (m & hl) continue;
;       const int k = m & (hl - 1); const int j = k * (8 / hl);
;       const float2 wc = make_float2(c16(j), INV ? s16(j) : -s16(j));
;       const float2 tw = cmul(wb, wc);
;       if (!INV) { const float2 p = x[m], q = x[m + hl]; x[m] = make_float2(p.x + q.x, p.y + q.y); x[m + hl] = cmul(make_float2(p.x - q.x, p.y - q.y), tw); }
;       else { const float2 p = x[m], q = cmul(x[m + hl], tw); x[m] = make_float2(p.x + q.x, p.y + q.y); x[m + hl] = make_float2(p.x - q.x, p.y - q.y); }
;     }
	v_pk_add_f32 v[40:41], v[46:47], v[44:45]
	v_pk_add_f32 v[42:43], v[46:47], v[44:45] neg_lo:[0,1] neg_hi:[0,1]
	ds_write_b64 v50, v[40:41] offset:1088
	v_pk_mul_f32 v[40:41], v[14:15], v[42:43] op_sel:[0,1]
	s_nop 0
	v_fma_f32 v44, v12, v42, -v40
	v_fma_f32 v45, v13, v42, v41

; __device__ __forceinline__ float2 cmul(float2 a, float2 b) { return make_float2(a.x * b.x - a.y * b.y, a.x * b.y + a.y * b.x); }
; template <int LR, bool INV>
; __device__ __forceinline__ void fft_stages(float2 (&x)[1 << LR], const int r, const int s) {
;     ...
;       const float2 tw = cmul(wb, wc);
;       if (!INV) { const float2 p = x[m], q = x[m + hl]; x[m] = make_float2(p.x + q.x, p.y + q.y); x[m + hl] = cmul(make_float2(p.x - q.x, p.y - q.y), tw); }
	v_pk_mul_f32 v[40:41], v[20:21], v[32:33] op_sel:[0,1]
	ds_write_b64 v50, v[44:45] offset:1632
	v_fma_f32 v42, v0, v32, -v40
	v_fma_f32 v43, v1, v32, v41

; __device__ __forceinline__ float2 cmul(float2 a, float2 b) { return make_float2(a.x * b.x - a.y * b.y, a.x * b.y + a.y * b.x); }
; template <int LR, bool INV>
; __device__ __forceinline__ void fft_stages(float2 (&x)[1 << LR], const int r, const int s) {
;     ...
;       const float2 tw = cmul(wb, wc);
;       if (!INV) { const float2 p = x[m], q = x[m + hl]; x[m] = make_float2(p.x + q.x, p.y + q.y); x[m + hl] = cmul(make_float2(p.x - q.x, p.y - q.y), tw); }
	v_pk_mul_f32 v[32:33], v[22:23], v[34:35] op_sel:[0,1]
	s_nop 0
	v_fma_f32 v40, v2, v34, -v32
	v_fma_f32 v41, v3, v34, v33

; __device__ __forceinline__ float2 cmul(float2 a, float2 b) { return make_float2(a.x * b.x - a.y * b.y, a.x * b.y + a.y * b.x); }
; template <int LR, bool INV>
; __device__ __forceinline__ void fft_stages(float2 (&x)[1 << LR], const int r, const int s) {
;     ...
;       const float2 tw = cmul(wb, wc);
;       if (!INV) { const float2 p = x[m], q = x[m + hl]; x[m] = make_float2(p.x + q.x, p.y + q.y); x[m + hl] = cmul(make_float2(p.x - q.x, p.y - q.y), tw); }
	v_pk_mul_f32 v[32:33], v[24:25], v[36:37] op_sel:[0,1]
	s_nop 0
	v_fma_f32 v34, v4, v36, -v32
	v_fma_f32 v35, v5, v36, v33

; __device__ __forceinline__ float2 cmul(float2 a, float2 b) { return make_float2(a.x * b.x - a.y * b.y, a.x * b.y + a.y * b.x); }
; template <int LR, bool INV>
; __device__ __forceinline__ void fft_stages(float2 (&x)[1 << LR], const int r, const int s) {
;     ...
;       const float2 tw = cmul(wb, wc);
;       if (!INV) { const float2 p = x[m], q = x[m + hl]; x[m] = make_float2(p.x + q.x, p.y + q.y); x[m + hl] = cmul(make_float2(p.x - q.x, p.y - q.y), tw); }
	v_pk_mul_f32 v[32:33], v[26:27], v[38:39] op_sel:[0,1]
	s_nop 0
	v_fma_f32 v36, v6, v38, -v32
	v_fma_f32 v37, v7, v38, v33

; __device__ __forceinline__ float2 cmul(float2 a, float2 b) { return make_float2(a.x * b.x - a.y * b.y, a.x * b.y + a.y * b.x); }
; template <int LR, bool INV>
; __device__ __forceinline__ void fft_stages(float2 (&x)[1 << LR], const int r, const int s) {
;     ...
;     for (int m = 0; m < R; ++m) {
;       if (m & hl) continue;
;       const int k = m & (hl - 1); const int j = k * (8 / hl);
;       const float2 wc = make_float2(c16(j), INV ? s16(j) : -s16(j));
;       const float2 tw = cmul(wb, wc);
;       if (!INV) { const float2 p = x[m], q = x[m + hl]; x[m] = make_float2(p.x + q.x, p.y + q.y); x[m + hl] = cmul(make_float2(p.x - q.x, p.y - q.y), tw); }
;       else { const float2 p = x[m], q = cmul(x[m + hl], tw); x[m] = make_float2(p.x + q.x, p.y + q.y); x[m + hl] = make_float2(p.x - q.x, p.y - q.y); }
;     }
	v_pk_add_f32 v[32:33], v[42:43], v[34:35]
	v_pk_add_f32 v[38:39], v[40:41], v[36:37]
	v_pk_add_f32 v[36:37], v[40:41], v[36:37] neg_lo:[0,1] neg_hi:[0,1]
	v_pk_add_f32 v[40:41], v[32:33], v[38:39]
	v_pk_add_f32 v[32:33], v[32:33], v[38:39] neg_lo:[0,1] neg_hi:[0,1]
	v_pk_add_f32 v[34:35], v[42:43], v[34:35] neg_lo:[0,1] neg_hi:[0,1]
	v_pk_mul_f32 v[38:39], v[14:15], v[32:33] op_sel:[0,1]
	ds_write_b64 v50, v[40:41] offset:2176
	v_fma_f32 v40, v12, v32, -v38
	v_fma_f32 v41, v13, v32, v39

; __device__ __forceinline__ float2 cmul(float2 a, float2 b) { return make_float2(a.x * b.x - a.y * b.y, a.x * b.y + a.y * b.x); }
; template <int LR, bool INV>
; __device__ __forceinline__ void fft_stages(float2 (&x)[1 << LR], const int r, const int s) {
;     ...
;       const float2 tw = cmul(wb, wc);
;       if (!INV) { const float2 p = x[m], q = x[m + hl]; x[m] = make_float2(p.x + q.x, p.y + q.y); x[m + hl] = cmul(make_float2(p.x - q.x, p.y - q.y), tw); }
	v_pk_mul_f32 v[32:33], v[16:17], v[34:35] op_sel:[0,1]
	ds_write_b64 v50, v[40:41] offset:2720
	v_fma_f32 v38, v8, v34, -v32
	v_fma_f32 v39, v9, v34, v33

; __device__ __forceinline__ float2 cmul(float2 a, float2 b) { return make_float2(a.x * b.x - a.y * b.y, a.x * b.y + a.y * b.x); }
; template <int LR, bool INV>
; __device__ __forceinline__ void fft_stages(float2 (&x)[1 << LR], const int r, const int s) {
;     ...
;       const float2 tw = cmul(wb, wc);
;       if (!INV) { const float2 p = x[m], q = x[m + hl]; x[m] = make_float2(p.x + q.x, p.y + q.y); x[m + hl] = cmul(make_float2(p.x - q.x, p.y - q.y), tw); }
	v_pk_mul_f32 v[32:33], v[18:19], v[36:37] op_sel:[0,1]
	s_nop 0
	v_fma_f32 v34, v10, v36, -v32
	v_fma_f32 v35, v11, v36, v33

;     static __device__ __forceinline__ float sl(float g, float up) { return g * __builtin_amdgcn_rcpf(1.0f + __builtin_amdgcn_exp2f(-1.4426950408889634f * g)) * up; }
; __device__ __forceinline__ float2 cmul(float2 a, float2 b) { return make_float2(a.x * b.x - a.y * b.y, a.x * b.y + a.y * b.x); }
; template <int LR, bool INV>
; __device__ __forceinline__ void fft_stages(float2 (&x)[1 << LR], const int r, const int s) {
;     ...
;     for (int m = 0; m < R; ++m) {
;       if (m & hl) continue;
;       const int k = m & (hl - 1); const int j = k * (8 / hl);
;       const float2 wc = make_float2(c16(j), INV ? s16(j) : -s16(j));
;       const float2 tw = cmul(wb, wc);
;       if (!INV) { const float2 p = x[m], q = x[m + hl]; x[m] = make_float2(p.x + q.x, p.y + q.y); x[m + hl] = cmul(make_float2(p.x - q.x, p.y - q.y), tw); }
;       else { const float2 p = x[m], q = cmul(x[m + hl], tw); x[m] = make_float2(p.x + q.x, p.y + q.y); x[m + hl] = make_float2(p.x - q.x, p.y - q.y); }
;     }
; template <int LR, bool INV>
; __device__ __forceinline__ void fft_pass(float2* X, const int N, const int sl, const int tid) {
;     ...
;     for (int m = 0; m < R; ++m) X[PIDX(i0 + (m << sl))] = x[m];
	v_pk_add_f32 v[32:33], v[38:39], v[34:35]
	v_pk_add_f32 v[34:35], v[38:39], v[34:35] neg_lo:[0,1] neg_hi:[0,1]
	ds_write_b64 v50, v[32:33] offset:3264
	v_pk_mul_f32 v[32:33], v[14:15], v[34:35] op_sel:[0,1]
	s_nop 0
	v_fma_f32 v36, v12, v34, -v32
	v_pk_fma_f32 v[32:33], v[12:13], v[34:35], v[32:33] op_sel_hi:[1,0,1]
	s_nop 0
	v_mov_b32_e32 v37, v33
	ds_write_b64 v50, v[36:37] offset:3808
	s_andn2_b64 exec, exec, s[14:15]
	s_cbranch_execnz .LBB0_660

;     static __device__ __forceinline__ float sl(float g, float up) { return g * __builtin_amdgcn_rcpf(1.0f + __builtin_amdgcn_exp2f(-1.4426950408889634f * g)) * up; }
; #define tid ltid()
; template <int LR, bool INV>
; __device__ __forceinline__ void fft_pass(float2* X, const int N, const int sl, const int tid) {
;     ...
;   for (int g = tid; g < (N >> LR); g += NTHR) {
;     const int r = g & (s - 1);
;     const int i0 = ((g >> sl) << (sl + LR)) + r;
;     float2 x[R];
; #pragma unroll
;     for (int m = 0; m < R; ++m) x[m] = X[PIDX(i0 + (m << sl))];
.LBB0_663:
	v_and_b32_e32 v32, 0xffffffc0, v30
	v_or_b32_e32 v33, v32, v29
	v_ashrrev_i32_e32 v34, 1, v32
	v_lshlrev_b32_e32 v33, 3, v33
	v_add3_u32 v52, s52, v34, v33
	v_or_b32_e32 v34, 16, v32
	v_ashrrev_i32_e32 v34, 4, v34
	v_lshlrev_b32_e32 v34, 3, v34
	v_add3_u32 v53, s52, v34, v33


;     static __device__ __forceinline__ float sl(float g, float up) { return g * __builtin_amdgcn_rcpf(1.0f + __builtin_amdgcn_exp2f(-1.4426950408889634f * g)) * up; }
; __device__ __forceinline__ float2 cmul(float2 a, float2 b) { return make_float2(a.x * b.x - a.y * b.y, a.x * b.y + a.y * b.x); }
; #define tid ltid()
; template <int LR, bool INV>
; __device__ __forceinline__ void fft_stages(float2 (&x)[1 << LR], const int r, const int s) {
;     ...
;     for (int m = 0; m < R; ++m) {
;       if (m & hl) continue;
;       const int k = m & (hl - 1); const int j = k * (8 / hl);
;       const float2 wc = make_float2(c16(j), INV ? s16(j) : -s16(j));
;       const float2 tw = cmul(wb, wc);
;       if (!INV) { const float2 p = x[m], q = x[m + hl]; x[m] = make_float2(p.x + q.x, p.y + q.y); x[m + hl] = cmul(make_float2(p.x - q.x, p.y - q.y), tw); }
;       else { const float2 p = x[m], q = cmul(x[m + hl], tw); x[m] = make_float2(p.x + q.x, p.y + q.y); x[m + hl] = make_float2(p.x - q.x, p.y - q.y); }
;     }
; template <int LR, bool INV>
; __device__ __forceinline__ void fft_pass(float2* X, const int N, const int sl, const int tid) {
;     ...
;   for (int g = tid; g < (N >> LR); g += NTHR) {
;     const int r = g & (s - 1);
;     const int i0 = ((g >> sl) << (sl + LR)) + r;
;     float2 x[R];
; #pragma unroll
;     for (int m = 0; m < R; ++m) x[m] = X[PIDX(i0 + (m << sl))];
	ds_read2_b64 v[32:35], v52 offset1:8
	ds_read2_b64 v[36:39], v53 offset0:16 offset1:24
	ds_read2_b64 v[40:43], v53 offset0:33 offset1:41
	ds_read2_b64 v[44:47], v53 offset0:50 offset1:58
	v_add_u32_e32 v31, 0x200, v31
	v_cmp_le_i32_e64 s[40:41], s19, v31
	v_add_u32_e32 v30, 0x1000, v30
	s_waitcnt lgkmcnt(1)
	v_pk_add_f32 v[48:49], v[32:33], v[40:41]
	v_pk_add_f32 v[32:33], v[32:33], v[40:41] neg_lo:[0,1] neg_hi:[0,1]
	v_pk_add_f32 v[40:41], v[34:35], v[42:43]
	v_pk_add_f32 v[34:35], v[34:35], v[42:43] neg_lo:[0,1] neg_hi:[0,1]
	s_waitcnt lgkmcnt(0)
	v_pk_add_f32 v[42:43], v[36:37], v[44:45]
	v_pk_add_f32 v[36:37], v[36:37], v[44:45] neg_lo:[0,1] neg_hi:[0,1]
	v_pk_add_f32 v[44:45], v[38:39], v[46:47]
	v_pk_add_f32 v[38:39], v[38:39], v[46:47] neg_lo:[0,1] neg_hi:[0,1]
	v_pk_add_f32 v[46:47], v[48:49], v[42:43]
	v_pk_add_f32 v[42:43], v[48:49], v[42:43] neg_lo:[0,1] neg_hi:[0,1]
	v_pk_add_f32 v[48:49], v[40:41], v[44:45]
	v_pk_add_f32 v[40:41], v[40:41], v[44:45] neg_lo:[0,1] neg_hi:[0,1]
	v_pk_add_f32 v[44:45], v[46:47], v[48:49]
	v_pk_add_f32 v[46:47], v[46:47], v[48:49] neg_lo:[0,1] neg_hi:[0,1]
	s_or_b64 s[14:15], s[40:41], s[14:15]
	v_pk_mul_f32 v[48:49], v[14:15], v[46:47] op_sel:[0,1]
	s_nop 0
	v_fma_f32 v50, v12, v46, -v48
	v_fma_f32 v51, v13, v46, v49

;     static __device__ __forceinline__ float sl(float g, float up) { return g * __builtin_amdgcn_rcpf(1.0f + __builtin_amdgcn_exp2f(-1.4426950408889634f * g)) * up; }
; __device__ __forceinline__ float2 cmul(float2 a, float2 b) { return make_float2(a.x * b.x - a.y * b.y, a.x * b.y + a.y * b.x); }
; template <int LR, bool INV>
; __device__ __forceinline__ void fft_stages(float2 (&x)[1 << LR], const int r, const int s) {
;     ...
;       const float2 tw = cmul(wb, wc);
;       if (!INV) { const float2 p = x[m], q = x[m + hl]; x[m] = make_float2(p.x + q.x, p.y + q.y); x[m + hl] = cmul(make_float2(p.x - q.x, p.y - q.y), tw); }
; template <int LR, bool INV>
; __device__ __forceinline__ void fft_pass(float2* X, const int N, const int sl, const int tid) {
;     ...
;     for (int m = 0; m < R; ++m) X[PIDX(i0 + (m << sl))] = x[m];
	ds_write2_b64 v52, v[44:45], v[50:51] offset1:8
	v_pk_mul_f32 v[44:45], v[16:17], v[42:43] op_sel:[0,1]
	s_nop 0
	v_fma_f32 v46, v8, v42, -v44
	v_fma_f32 v47, v9, v42, v45

; __device__ __forceinline__ float2 cmul(float2 a, float2 b) { return make_float2(a.x * b.x - a.y * b.y, a.x * b.y + a.y * b.x); }
; template <int LR, bool INV>
; __device__ __forceinline__ void fft_stages(float2 (&x)[1 << LR], const int r, const int s) {
;     ...
;       const float2 tw = cmul(wb, wc);
;       if (!INV) { const float2 p = x[m], q = x[m + hl]; x[m] = make_float2(p.x + q.x, p.y + q.y); x[m + hl] = cmul(make_float2(p.x - q.x, p.y - q.y), tw); }
	v_pk_mul_f32 v[42:43], v[18:19], v[40:41] op_sel:[0,1]
	s_nop 0
	v_fma_f32 v44, v10, v40, -v42
	v_fma_f32 v45, v11, v40, v43

; __device__ __forceinline__ float2 cmul(float2 a, float2 b) { return make_float2(a.x * b.x - a.y * b.y, a.x * b.y + a.y * b.x); }
; template <int LR, bool INV>
; __device__ __forceinline__ void fft_stages(float2 (&x)[1 << LR], const int r, const int s) {
;     ...
;     for (int m = 0; m < R; ++m) {
;       if (m & hl) continue;
;       const int k = m & (hl - 1); const int j = k * (8 / hl);
;       const float2 wc = make_float2(c16(j), INV ? s16(j) : -s16(j));
;       const float2 tw = cmul(wb, wc);
;       if (!INV) { const float2 p = x[m], q = x[m + hl]; x[m] = make_float2(p.x + q.x, p.y + q.y); x[m + hl] = cmul(make_float2(p.x - q.x, p.y - q.y), tw); }
;       else { const float2 p = x[m], q = cmul(x[m + hl], tw); x[m] = make_float2(p.x + q.x, p.y + q.y); x[m + hl] = make_float2(p.x - q.x, p.y - q.y); }
;     }
	v_pk_add_f32 v[42:43], v[46:47], v[44:45] neg_lo:[0,1] neg_hi:[0,1]
	v_pk_add_f32 v[40:41], v[46:47], v[44:45]
	v_pk_mul_f32 v[44:45], v[14:15], v[42:43] op_sel:[0,1]
	s_nop 0
	v_fma_f32 v46, v12, v42, -v44
	v_fma_f32 v47, v13, v42, v45

;     static __device__ __forceinline__ float sl(float g, float up) { return g * __builtin_amdgcn_rcpf(1.0f + __builtin_amdgcn_exp2f(-1.4426950408889634f * g)) * up; }
; __device__ __forceinline__ float2 cmul(float2 a, float2 b) { return make_float2(a.x * b.x - a.y * b.y, a.x * b.y + a.y * b.x); }
; template <int LR, bool INV>
; __device__ __forceinline__ void fft_stages(float2 (&x)[1 << LR], const int r, const int s) {
;     ...
;       const float2 tw = cmul(wb, wc);
;       if (!INV) { const float2 p = x[m], q = x[m + hl]; x[m] = make_float2(p.x + q.x, p.y + q.y); x[m + hl] = cmul(make_float2(p.x - q.x, p.y - q.y), tw); }
; template <int LR, bool INV>
; __device__ __forceinline__ void fft_pass(float2* X, const int N, const int sl, const int tid) {
;     ...
;     for (int m = 0; m < R; ++m) X[PIDX(i0 + (m << sl))] = x[m];
	ds_write2_b64 v53, v[40:41], v[46:47] offset0:16 offset1:24
	v_pk_mul_f32 v[40:41], v[20:21], v[32:33] op_sel:[0,1]
	s_nop 0
	v_fma_f32 v42, v0, v32, -v40
	v_fma_f32 v43, v1, v32, v41

; __device__ __forceinline__ float2 cmul(float2 a, float2 b) { return make_float2(a.x * b.x - a.y * b.y, a.x * b.y + a.y * b.x); }
; template <int LR, bool INV>
; __device__ __forceinline__ void fft_stages(float2 (&x)[1 << LR], const int r, const int s) {
;     ...
;       const float2 tw = cmul(wb, wc);
;       if (!INV) { const float2 p = x[m], q = x[m + hl]; x[m] = make_float2(p.x + q.x, p.y + q.y); x[m + hl] = cmul(make_float2(p.x - q.x, p.y - q.y), tw); }
	v_pk_mul_f32 v[32:33], v[22:23], v[34:35] op_sel:[0,1]
	s_nop 0
	v_fma_f32 v40, v2, v34, -v32
	v_fma_f32 v41, v3, v34, v33

; __device__ __forceinline__ float2 cmul(float2 a, float2 b) { return make_float2(a.x * b.x - a.y * b.y, a.x * b.y + a.y * b.x); }
; template <int LR, bool INV>
; __device__ __forceinline__ void fft_stages(float2 (&x)[1 << LR], const int r, const int s) {
;     ...
;       const float2 tw = cmul(wb, wc);
;       if (!INV) { const float2 p = x[m], q = x[m + hl]; x[m] = make_float2(p.x + q.x, p.y + q.y); x[m + hl] = cmul(make_float2(p.x - q.x, p.y - q.y), tw); }
	v_pk_mul_f32 v[32:33], v[24:25], v[36:37] op_sel:[0,1]
	s_nop 0
	v_fma_f32 v34, v4, v36, -v32
	v_fma_f32 v35, v5, v36, v33

; __device__ __forceinline__ float2 cmul(float2 a, float2 b) { return make_float2(a.x * b.x - a.y * b.y, a.x * b.y + a.y * b.x); }
; template <int LR, bool INV>
; __device__ __forceinline__ void fft_stages(float2 (&x)[1 << LR], const int r, const int s) {
;     ...
;       const float2 tw = cmul(wb, wc);
;       if (!INV) { const float2 p = x[m], q = x[m + hl]; x[m] = make_float2(p.x + q.x, p.y + q.y); x[m + hl] = cmul(make_float2(p.x - q.x, p.y - q.y), tw); }
	v_pk_mul_f32 v[32:33], v[26:27], v[38:39] op_sel:[0,1]
	s_nop 0
	v_fma_f32 v36, v6, v38, -v32
	v_fma_f32 v37, v7, v38, v33

; __device__ __forceinline__ float2 cmul(float2 a, float2 b) { return make_float2(a.x * b.x - a.y * b.y, a.x * b.y + a.y * b.x); }
; template <int LR, bool INV>
; __device__ __forceinline__ void fft_stages(float2 (&x)[1 << LR], const int r, const int s) {
;     ...
;     for (int m = 0; m < R; ++m) {
;       if (m & hl) continue;
;       const int k = m & (hl - 1); const int j = k * (8 / hl);
;       const float2 wc = make_float2(c16(j), INV ? s16(j) : -s16(j));
;       const float2 tw = cmul(wb, wc);
;       if (!INV) { const float2 p = x[m], q = x[m + hl]; x[m] = make_float2(p.x + q.x, p.y + q.y); x[m + hl] = cmul(make_float2(p.x - q.x, p.y - q.y), tw); }
;       else { const float2 p = x[m], q = cmul(x[m + hl], tw); x[m] = make_float2(p.x + q.x, p.y + q.y); x[m + hl] = make_float2(p.x - q.x, p.y - q.y); }
;     }
	v_pk_add_f32 v[32:33], v[42:43], v[34:35]
	v_pk_add_f32 v[38:39], v[40:41], v[36:37]
	v_pk_add_f32 v[36:37], v[40:41], v[36:37] neg_lo:[0,1] neg_hi:[0,1]
	v_pk_add_f32 v[40:41], v[32:33], v[38:39]
	v_pk_add_f32 v[32:33], v[32:33], v[38:39] neg_lo:[0,1] neg_hi:[0,1]
	v_pk_add_f32 v[34:35], v[42:43], v[34:35] neg_lo:[0,1] neg_hi:[0,1]
	v_pk_mul_f32 v[38:39], v[14:15], v[32:33] op_sel:[0,1]
	s_nop 0
	v_fma_f32 v42, v12, v32, -v38
	v_fma_f32 v43, v13, v32, v39

;     static __device__ __forceinline__ float sl(float g, float up) { return g * __builtin_amdgcn_rcpf(1.0f + __builtin_amdgcn_exp2f(-1.4426950408889634f * g)) * up; }
; __device__ __forceinline__ float2 cmul(float2 a, float2 b) { return make_float2(a.x * b.x - a.y * b.y, a.x * b.y + a.y * b.x); }
; template <int LR, bool INV>
; __device__ __forceinline__ void fft_stages(float2 (&x)[1 << LR], const int r, const int s) {
;     ...
;     for (int m = 0; m < R; ++m) {
;       if (m & hl) continue;
;       const int k = m & (hl - 1); const int j = k * (8 / hl);
;       const float2 wc = make_float2(c16(j), INV ? s16(j) : -s16(j));
;       const float2 tw = cmul(wb, wc);
;       if (!INV) { const float2 p = x[m], q = x[m + hl]; x[m] = make_float2(p.x + q.x, p.y + q.y); x[m + hl] = cmul(make_float2(p.x - q.x, p.y - q.y), tw); }
;       else { const float2 p = x[m], q = cmul(x[m + hl], tw); x[m] = make_float2(p.x + q.x, p.y + q.y); x[m + hl] = make_float2(p.x - q.x, p.y - q.y); }
;     }
; template <int LR, bool INV>
; __device__ __forceinline__ void fft_pass(float2* X, const int N, const int sl, const int tid) {
;     ...
;     for (int m = 0; m < R; ++m) x[m] = X[PIDX(i0 + (m << sl))];
;     fft_stages<LR, INV>(x, r, s);
; #pragma unroll
;     for (int m = 0; m < R; ++m) X[PIDX(i0 + (m << sl))] = x[m];
	v_pk_mul_f32 v[32:33], v[16:17], v[34:35] op_sel:[0,1]
	ds_write2_b64 v53, v[40:41], v[42:43] offset0:33 offset1:41
	v_fma_f32 v38, v8, v34, -v32
	v_fma_f32 v39, v9, v34, v33

; __device__ __forceinline__ float2 cmul(float2 a, float2 b) { return make_float2(a.x * b.x - a.y * b.y, a.x * b.y + a.y * b.x); }
; template <int LR, bool INV>
; __device__ __forceinline__ void fft_stages(float2 (&x)[1 << LR], const int r, const int s) {
;     ...
;     for (int m = 0; m < R; ++m) {
;       if (m & hl) continue;
;       const int k = m & (hl - 1); const int j = k * (8 / hl);
;       const float2 wc = make_float2(c16(j), INV ? s16(j) : -s16(j));
;       const float2 tw = cmul(wb, wc);
;       if (!INV) { const float2 p = x[m], q = x[m + hl]; x[m] = make_float2(p.x + q.x, p.y + q.y); x[m + hl] = cmul(make_float2(p.x - q.x, p.y - q.y), tw); }
;       else { const float2 p = x[m], q = cmul(x[m + hl], tw); x[m] = make_float2(p.x + q.x, p.y + q.y); x[m + hl] = make_float2(p.x - q.x, p.y - q.y); }
;     }
	v_pk_mul_f32 v[32:33], v[18:19], v[36:37] op_sel:[0,1]
	s_nop 0
	v_fma_f32 v34, v10, v36, -v32
	v_fma_f32 v35, v11, v36, v33

;     static __device__ __forceinline__ float sl(float g, float up) { return g * __builtin_amdgcn_rcpf(1.0f + __builtin_amdgcn_exp2f(-1.4426950408889634f * g)) * up; }
; __device__ __forceinline__ float2 cmul(float2 a, float2 b) { return make_float2(a.x * b.x - a.y * b.y, a.x * b.y + a.y * b.x); }
; template <int LR, bool INV>
; __device__ __forceinline__ void fft_stages(float2 (&x)[1 << LR], const int r, const int s) {
;     ...
;       if (!INV) { const float2 p = x[m], q = x[m + hl]; x[m] = make_float2(p.x + q.x, p.y + q.y); x[m + hl] = cmul(make_float2(p.x - q.x, p.y - q.y), tw); }
; template <int LR, bool INV>
; __device__ __forceinline__ void fft_pass(float2* X, const int N, const int sl, const int tid) {
;     ...
;     for (int m = 0; m < R; ++m) X[PIDX(i0 + (m << sl))] = x[m];
	v_pk_add_f32 v[32:33], v[38:39], v[34:35]
	v_pk_add_f32 v[34:35], v[38:39], v[34:35] neg_lo:[0,1] neg_hi:[0,1]
	s_nop 0
	v_pk_mul_f32 v[36:37], v[14:15], v[34:35] op_sel:[0,1]
	s_nop 0
	v_fma_f32 v38, v12, v34, -v36
	v_pk_fma_f32 v[34:35], v[12:13], v[34:35], v[36:37] op_sel_hi:[1,0,1]
	s_nop 0
	v_mov_b32_e32 v39, v35
	ds_write2_b64 v53, v[32:33], v[38:39] offset0:50 offset1:58
	s_andn2_b64 exec, exec, s[14:15]
	s_cbranch_execnz .LBB0_663

;     static __device__ __forceinline__ float sl(float g, float up) { return g * __builtin_amdgcn_rcpf(1.0f + __builtin_amdgcn_exp2f(-1.4426950408889634f * g)) * up; }
; __device__ __forceinline__ float2 cmul(float2 a, float2 b) { return make_float2(a.x * b.x - a.y * b.y, a.x * b.y + a.y * b.x); }
; #define tid ltid()
; template <int LR, bool INV>
; __device__ __forceinline__ void fft_stages(float2 (&x)[1 << LR], const int r, const int s) {
;     ...
;     for (int m = 0; m < R; ++m) {
;       if (m & hl) continue;
;       const int k = m & (hl - 1); const int j = k * (8 / hl);
;       const float2 wc = make_float2(c16(j), INV ? s16(j) : -s16(j));
;       const float2 tw = cmul(wb, wc);
;       if (!INV) { const float2 p = x[m], q = x[m + hl]; x[m] = make_float2(p.x + q.x, p.y + q.y); x[m + hl] = cmul(make_float2(p.x - q.x, p.y - q.y), tw); }
;       else { const float2 p = x[m], q = cmul(x[m + hl], tw); x[m] = make_float2(p.x + q.x, p.y + q.y); x[m + hl] = make_float2(p.x - q.x, p.y - q.y); }
;     }
; template <int LR, bool INV>
; __device__ __forceinline__ void fft_pass(float2* X, const int N, const int sl, const int tid) {
;     ...
;   for (int g = tid; g < (N >> LR); g += NTHR) {
;     const int r = g & (s - 1);
;     const int i0 = ((g >> sl) << (sl + LR)) + r;
;     float2 x[R];
; #pragma unroll
;     for (int m = 0; m < R; ++m) x[m] = X[PIDX(i0 + (m << sl))];
;     fft_stages<LR, INV>(x, r, s);
; #pragma unroll
;     for (int m = 0; m < R; ++m) X[PIDX(i0 + (m << sl))] = x[m];
.LBB0_666:
	v_ashrrev_i32_e32 v0, 4, v28
	v_lshl_add_u32 v5, v0, 3, v4
	ds_read2_b64 v[6:9], v5 offset1:1
	ds_read2_b64 v[10:13], v5 offset0:2 offset1:3
	ds_read2_b64 v[14:17], v5 offset0:4 offset1:5
	ds_read2_b64 v[18:21], v5 offset0:6 offset1:7
	s_mov_b32 s74, s71
	s_mov_b32 s20, s75
	s_mov_b32 s21, s71
	s_waitcnt lgkmcnt(1)
	v_pk_add_f32 v[0:1], v[6:7], v[14:15]
	v_pk_add_f32 v[2:3], v[8:9], v[16:17]
	s_waitcnt lgkmcnt(0)
	v_pk_add_f32 v[24:25], v[10:11], v[18:19]
	v_pk_add_f32 v[26:27], v[12:13], v[20:21]
	v_pk_add_f32 v[30:31], v[0:1], v[24:25]
	v_pk_add_f32 v[32:33], v[2:3], v[26:27]
	v_pk_add_f32 v[0:1], v[0:1], v[24:25] neg_lo:[0,1] neg_hi:[0,1]
	v_pk_add_f32 v[34:35], v[30:31], v[32:33]
	v_pk_add_f32 v[30:31], v[30:31], v[32:33] neg_lo:[0,1] neg_hi:[0,1]
	v_pk_mul_f32 v[24:25], v[0:1], 0 op_sel_hi:[1,0]
	v_pk_mul_f32 v[32:33], v[30:31], 0 op_sel_hi:[1,0]
	v_sub_f32_e32 v22, v8, v16
	v_add_f32_e32 v36, v30, v33
	v_sub_f32_e32 v37, v31, v32
	v_mul_f32_e32 v22, 0x3f3504f3, v22

; __device__ __forceinline__ float2 cmul(float2 a, float2 b) { return make_float2(a.x * b.x - a.y * b.y, a.x * b.y + a.y * b.x); }
; template <int LR, bool INV>
; __device__ __forceinline__ void fft_stages(float2 (&x)[1 << LR], const int r, const int s) {
;     ...
;       if (!INV) { const float2 p = x[m], q = x[m + hl]; x[m] = make_float2(p.x + q.x, p.y + q.y); x[m + hl] = cmul(make_float2(p.x - q.x, p.y - q.y), tw); }
	v_add_f32_e32 v30, v0, v25
	v_sub_f32_e32 v31, v1, v24
	v_add_u32_e32 v60, 0x200, v60

; __device__ __forceinline__ float2 cmul(float2 a, float2 b) { return make_float2(a.x * b.x - a.y * b.y, a.x * b.y + a.y * b.x); }
; template <int LR, bool INV>
; __device__ __forceinline__ void fft_stages(float2 (&x)[1 << LR], const int r, const int s) {
;     ...
;       if (!INV) { const float2 p = x[m], q = x[m + hl]; x[m] = make_float2(p.x + q.x, p.y + q.y); x[m + hl] = cmul(make_float2(p.x - q.x, p.y - q.y), tw); }
	v_pk_add_f32 v[0:1], v[2:3], v[26:27] neg_lo:[0,1] neg_hi:[0,1]
	v_cmp_le_i32_e32 vcc, s19, v60
	v_fma_f32 v2, v0, 0, v1
	v_fma_f32 v3, v1, 0, -v0
	v_add_u32_e32 v4, 0x8000, v4

; __device__ __forceinline__ float2 cmul(float2 a, float2 b) { return make_float2(a.x * b.x - a.y * b.y, a.x * b.y + a.y * b.x); }
; template <int LR, bool INV>
; __device__ __forceinline__ void fft_stages(float2 (&x)[1 << LR], const int r, const int s) {
;     ...
;       if (!INV) { const float2 p = x[m], q = x[m + hl]; x[m] = make_float2(p.x + q.x, p.y + q.y); x[m + hl] = cmul(make_float2(p.x - q.x, p.y - q.y), tw); }
;       else { const float2 p = x[m], q = cmul(x[m + hl], tw); x[m] = make_float2(p.x + q.x, p.y + q.y); x[m + hl] = make_float2(p.x - q.x, p.y - q.y); }
	v_pk_add_f32 v[0:1], v[30:31], v[2:3]
	v_pk_add_f32 v[2:3], v[30:31], v[2:3] neg_lo:[0,1] neg_hi:[0,1]
	v_add_u32_e32 v28, 0x1000, v28
	v_pk_mul_f32 v[24:25], v[2:3], 0 op_sel_hi:[1,0]
	s_or_b64 s[14:15], vcc, s[14:15]
	v_add_f32_e32 v26, v2, v25
	v_sub_f32_e32 v27, v3, v24
	ds_write2_b64 v5, v[34:35], v[36:37] offset1:1

;     static __device__ __forceinline__ float sl(float g, float up) { return g * __builtin_amdgcn_rcpf(1.0f + __builtin_amdgcn_exp2f(-1.4426950408889634f * g)) * up; }
; __device__ __forceinline__ float2 cmul(float2 a, float2 b) { return make_float2(a.x * b.x - a.y * b.y, a.x * b.y + a.y * b.x); }
; template <int LR, bool INV>
; __device__ __forceinline__ void fft_stages(float2 (&x)[1 << LR], const int r, const int s) {
;     ...
;     for (int m = 0; m < R; ++m) {
;       if (m & hl) continue;
;       const int k = m & (hl - 1); const int j = k * (8 / hl);
;       const float2 wc = make_float2(c16(j), INV ? s16(j) : -s16(j));
;       const float2 tw = cmul(wb, wc);
;       if (!INV) { const float2 p = x[m], q = x[m + hl]; x[m] = make_float2(p.x + q.x, p.y + q.y); x[m + hl] = cmul(make_float2(p.x - q.x, p.y - q.y), tw); }
;       else { const float2 p = x[m], q = cmul(x[m + hl], tw); x[m] = make_float2(p.x + q.x, p.y + q.y); x[m + hl] = make_float2(p.x - q.x, p.y - q.y); }
;     }
; template <int LR, bool INV>
; __device__ __forceinline__ void fft_pass(float2* X, const int N, const int sl, const int tid) {
;     ...
;     for (int m = 0; m < R; ++m) X[PIDX(i0 + (m << sl))] = x[m];
	ds_write2_b64 v5, v[0:1], v[26:27] offset0:2 offset1:3
	v_pk_mov_b32 v[0:1], v[8:9], v[6:7] op_sel:[1,0]
	v_pk_mov_b32 v[2:3], v[16:17], v[14:15] op_sel:[1,0]
	v_mov_b32_e32 v8, v10
	v_mov_b32_e32 v16, v18
	v_pk_add_f32 v[0:1], v[0:1], v[2:3] neg_lo:[0,1] neg_hi:[0,1]
	v_pk_add_f32 v[2:3], v[8:9], v[16:17] neg_lo:[0,1] neg_hi:[0,1]
	v_mov_b32_e32 v6, v7
	v_mov_b32_e32 v7, v13
	v_mov_b32_e32 v8, v15
	v_mov_b32_e32 v9, v21
	v_pk_add_f32 v[6:7], v[6:7], v[8:9] neg_lo:[0,1] neg_hi:[0,1]
	v_mov_b32_e32 v13, v11
	v_mov_b32_e32 v21, v19
	v_mov_b32_e32 v23, v6
	v_pk_add_f32 v[10:11], v[12:13], v[20:21] neg_lo:[0,1] neg_hi:[0,1]
	v_fma_f32 v8, v0, s74, v22
	v_pk_mov_b32 v[12:13], v[10:11], v[22:23] op_sel:[1,0]
	v_fma_f32 v15, -v1, s75, v23
	v_fma_f32 v16, v2, s20, v12
	v_fma_f32 v13, v3, s21, -v13
	s_mov_b32 s74, s70
	s_mov_b32 s21, s70
	v_pk_mul_f32 v[18:19], v[10:11], s[74:75]
	v_pk_mul_f32 v[20:21], v[6:7], s[20:21]
	v_pk_mov_b32 v[0:1], v[0:1], v[18:19] op_sel:[1,0]
	v_pk_mov_b32 v[2:3], v[20:21], v[2:3] op_sel:[1,0]
	v_mov_b32_e32 v9, v15
	v_mov_b32_e32 v17, v13
	v_pk_fma_f32 v[2:3], v[10:11], s[74:75], v[2:3] neg_lo:[0,0,1] neg_hi:[0,0,1]
	v_pk_fma_f32 v[0:1], v[6:7], s[20:21], v[0:1]
	v_pk_add_f32 v[6:7], v[8:9], v[2:3]
	v_pk_add_f32 v[10:11], v[0:1], v[16:17]
	v_mov_b32_e32 v21, v7
	v_pk_add_f32 v[18:19], v[6:7], v[10:11]
	v_mov_b32_e32 v20, v10
	v_mov_b32_e32 v7, v11
	v_pk_add_f32 v[6:7], v[20:21], v[6:7] neg_lo:[0,1] neg_hi:[0,1]
	v_mov_b32_e32 v14, v0
	v_pk_mul_f32 v[10:11], v[6:7], 0 op_sel_hi:[1,0]
	v_mov_b32_e32 v17, v3
	v_add_f32_e32 v20, v6, v11
	v_sub_f32_e32 v21, v7, v10
	v_mov_b32_e32 v9, v13

; __device__ __forceinline__ float2 cmul(float2 a, float2 b) { return make_float2(a.x * b.x - a.y * b.y, a.x * b.y + a.y * b.x); }
; template <int LR, bool INV>
; __device__ __forceinline__ void fft_stages(float2 (&x)[1 << LR], const int r, const int s) {
;     ...
;       if (!INV) { const float2 p = x[m], q = x[m + hl]; x[m] = make_float2(p.x + q.x, p.y + q.y); x[m + hl] = cmul(make_float2(p.x - q.x, p.y - q.y), tw); }
;       else { const float2 p = x[m], q = cmul(x[m + hl], tw); x[m] = make_float2(p.x + q.x, p.y + q.y); x[m + hl] = make_float2(p.x - q.x, p.y - q.y); }
;     }
	v_pk_add_f32 v[6:7], v[14:15], v[16:17] neg_lo:[0,1] neg_hi:[0,1]
	v_mov_b32_e32 v3, v1
	v_pk_mul_f32 v[10:11], v[6:7], 0 op_sel_hi:[1,0]
	v_pk_add_f32 v[0:1], v[8:9], v[2:3] neg_lo:[0,1] neg_hi:[0,1]
	v_add_f32_e32 v14, v6, v11
	v_sub_f32_e32 v15, v7, v10
	v_fma_f32 v2, v0, 0, v1
	v_fma_f32 v3, v1, 0, -v0


;     static __device__ __forceinline__ float sl(float g, float up) { return g * __builtin_amdgcn_rcpf(1.0f + __builtin_amdgcn_exp2f(-1.4426950408889634f * g)) * up; }
; __device__ __forceinline__ float2 cmul(float2 a, float2 b) { return make_float2(a.x * b.x - a.y * b.y, a.x * b.y + a.y * b.x); }
; template <int LR, bool INV>
; __device__ __forceinline__ void fft_stages(float2 (&x)[1 << LR], const int r, const int s) {
;     ...
;       if (!INV) { const float2 p = x[m], q = x[m + hl]; x[m] = make_float2(p.x + q.x, p.y + q.y); x[m + hl] = cmul(make_float2(p.x - q.x, p.y - q.y), tw); }
;       else { const float2 p = x[m], q = cmul(x[m + hl], tw); x[m] = make_float2(p.x + q.x, p.y + q.y); x[m + hl] = make_float2(p.x - q.x, p.y - q.y); }
;     }
; template <int LR, bool INV>
; __device__ __forceinline__ void fft_pass(float2* X, const int N, const int sl, const int tid) {
;     ...
;     for (int m = 0; m < R; ++m) X[PIDX(i0 + (m << sl))] = x[m];
	v_pk_add_f32 v[0:1], v[14:15], v[2:3]
	v_pk_add_f32 v[2:3], v[14:15], v[2:3] neg_lo:[0,1] neg_hi:[0,1]
	ds_write2_b64 v5, v[18:19], v[20:21] offset0:4 offset1:5
	v_pk_mul_f32 v[6:7], v[2:3], 0 op_sel_hi:[1,0]
	s_nop 0
	v_add_f32_e32 v8, v2, v7
	v_sub_f32_e32 v3, v3, v6
	v_mov_b32_e32 v9, v3
	ds_write2_b64 v5, v[0:1], v[8:9] offset0:6 offset1:7
	s_andn2_b64 exec, exec, s[14:15]
	s_cbranch_execnz .LBB0_666

; __device__ __forceinline__ float bfl(unsigned w) { return __uint_as_float(w << 16); }
; __device__ __forceinline__ float2 cmul(float2 a, float2 b) { return make_float2(a.x * b.x - a.y * b.y, a.x * b.y + a.y * b.x); }
; #define tid ltid()
; template <int LR, bool INV>
; __device__ __forceinline__ void fft_stages(float2 (&x)[1 << LR], const int r, const int s) {
;   constexpr int R = 1 << LR;
; #pragma unroll
;   for (int st = 0; st < LR; ++st) {
;     const int hl = INV ? (1 << st) : (R >> (st + 1));
;     const float fb = (float)r * (0.5f / (float)(hl * s));
;     const float2 wb = make_float2(__builtin_amdgcn_cosf(fb), INV ? __builtin_amdgcn_sinf(fb) : -__builtin_amdgcn_sinf(fb));
; #pragma unroll
;     for (int m = 0; m < R; ++m) {
;       if (m & hl) continue;
;       const int k = m & (hl - 1); const int j = k * (8 / hl);
;       const float2 wc = make_float2(c16(j), INV ? s16(j) : -s16(j));
;       const float2 tw = cmul(wb, wc);
;       if (!INV) { const float2 p = x[m], q = x[m + hl]; x[m] = make_float2(p.x + q.x, p.y + q.y); x[m + hl] = cmul(make_float2(p.x - q.x, p.y - q.y), tw); }
;       else { const float2 p = x[m], q = cmul(x[m + hl], tw); x[m] = make_float2(p.x + q.x, p.y + q.y); x[m + hl] = make_float2(p.x - q.x, p.y - q.y); }
;     }
; template <int LR>
; __device__ __forceinline__ void fft_first(float2* X, const bf16* __restrict__ u0, const bf16* __restrict__ u1, const int tid) {
;   constexpr int R = 1 << LR;
;   float2 x[R];
; #pragma unroll
;   for (int m = 0; m < R / 2; ++m) x[m] = make_float2(bfl(u0[tid + 512 * m]), bfl(u1[tid + 512 * m]));
; #pragma unroll
;   for (int m = R / 2; m < R; ++m) x[m] = make_float2(0.f, 0.f);
;   fft_stages<LR, false>(x, tid, 512);
; #pragma unroll
;   for (int m = 0; m < R; ++m) X[PIDX(tid + 512 * m)] = x[m];
;   __syncthreads();
; }
.LBB0_669:
	s_lshl_b32 s12, s18, 1
	s_lshl_b32 s12, s12, s20
	s_lshl_b32 s12, s12, 1
	s_add_u32 s40, s17, s12
	s_addc_u32 s41, s19, 0
	s_add_u32 s42, s40, s16
	s_addc_u32 s43, s41, 0
	s_mov_b64 s[12:13], -1
	s_and_b64 vcc, exec, s[10:11]
	s_cbranch_vccz .LBB0_671
	v_mov_b32_e32 v2, v208
	s_mov_b32 s12, s71
	v_ashrrev_i32_e32 v3, 31, v2
	v_lshlrev_b64 v[4:5], 1, v[2:3]
	v_lshl_add_u64 v[6:7], s[40:41], 0, v[4:5]
	v_lshl_add_u64 v[4:5], s[42:43], 0, v[4:5]
	global_load_ushort v9, v[4:5], off
	global_load_ushort v11, v[6:7], off
	global_load_ushort v13, v[4:5], off offset:1024
	global_load_ushort v15, v[6:7], off offset:1024
	global_load_ushort v22, v[4:5], off offset:2048
	global_load_ushort v24, v[6:7], off offset:2048
	s_nop 0
	global_load_ushort v5, v[4:5], off offset:3072
	s_nop 0
	global_load_ushort v7, v[6:7], off offset:3072
	v_cvt_f32_i32_e32 v8, v2
	v_add_u32_e32 v4, 0x400, v2
	v_add_u32_e32 v3, 0x200, v2
	v_add_u32_e32 v6, 0x600, v2
	v_ashrrev_i32_e32 v10, 4, v2
	v_lshl_add_u32 v12, v2, 3, 0
	v_add_u32_e32 v14, 0x800, v2
	v_add_u32_e32 v16, 0xa00, v2
	v_add_u32_e32 v17, 0xc00, v2
	v_add_u32_e32 v2, 0xe00, v2
	v_ashrrev_i32_e32 v4, 4, v4
	v_lshl_add_u32 v40, v10, 3, v12
	v_ashrrev_i32_e32 v3, 4, v3
	v_ashrrev_i32_e32 v6, 4, v6
	v_ashrrev_i32_e32 v10, 4, v14
	v_ashrrev_i32_e32 v14, 4, v16
	v_ashrrev_i32_e32 v16, 4, v17
	v_ashrrev_i32_e32 v2, 4, v2
	v_lshl_add_u32 v42, v4, 3, v12
	v_mul_f32_e32 v4, 0x3a000000, v8
	v_lshl_add_u32 v41, v3, 3, v12
	v_lshl_add_u32 v43, v6, 3, v12
	v_lshl_add_u32 v44, v10, 3, v12
	v_lshl_add_u32 v45, v14, 3, v12
	v_lshl_add_u32 v46, v16, 3, v12
	v_lshl_add_u32 v47, v2, 3, v12
	v_cos_f32_e32 v10, v4
	v_sin_f32_e32 v12, v4
	v_mul_f32_e32 v6, 0x3a800000, v8
	v_cos_f32_e32 v14, v6
	v_sin_f32_e32 v16, v6
	v_mul_f32_e32 v2, 0x39800000, v8
	v_fmamk_f32 v4, v12, 0x80000000, v10
	v_fma_f32 v6, v10, s91, -v12
	v_fma_f32 v8, v10, 0, -v12
	v_fma_f32 v10, v12, s91, -v10
	v_cos_f32_e32 v3, v2
	v_sin_f32_e32 v2, v2
	v_fmamk_f32 v12, v16, 0x80000000, v14
	v_fma_f32 v14, v14, s91, -v16
	s_mov_b32 s13, s70
	v_xor_b32_e32 v48, 0x80000000, v2
	v_pk_mov_b32 v[16:17], v[2:3], v[2:3] op_sel:[1,0]
	s_mov_b32 s90, s75
	v_mov_b32_e32 v17, v48
	v_pk_fma_f32 v[16:17], v[2:3], 0, v[16:17] op_sel_hi:[1,0,1] neg_lo:[1,0,0] neg_hi:[1,0,0]
	s_waitcnt vmcnt(7)
	v_lshlrev_b32_e32 v19, 16, v9
	s_waitcnt vmcnt(6)
	v_lshlrev_b32_e32 v18, 16, v11
	s_waitcnt vmcnt(5)
	v_lshlrev_b32_e32 v21, 16, v13
	s_waitcnt vmcnt(4)
	v_lshlrev_b32_e32 v20, 16, v15
	s_waitcnt vmcnt(3)
	v_lshlrev_b32_e32 v23, 16, v22
	s_waitcnt vmcnt(2)
	v_lshlrev_b32_e32 v22, 16, v24
	s_waitcnt vmcnt(1)
	v_lshlrev_b32_e32 v25, 16, v5
	s_waitcnt vmcnt(0)
	v_lshlrev_b32_e32 v24, 16, v7
	v_pk_add_f32 v[26:27], v[18:19], 0 op_sel_hi:[1,0]
	v_pk_add_f32 v[28:29], v[20:21], 0 op_sel_hi:[1,0]
	v_pk_add_f32 v[30:31], v[22:23], 0 op_sel_hi:[1,0]
	v_pk_add_f32 v[32:33], v[24:25], 0 op_sel_hi:[1,0]
	v_pk_add_f32 v[34:35], v[26:27], v[30:31] neg_lo:[0,1] neg_hi:[0,1]
	v_pk_add_f32 v[36:37], v[28:29], v[32:33] neg_lo:[0,1] neg_hi:[0,1]
	v_pk_add_f32 v[26:27], v[26:27], v[30:31]
	v_pk_add_f32 v[28:29], v[28:29], v[32:33]
	v_pk_mul_f32 v[30:31], v[6:7], v[34:35] op_sel_hi:[0,1]
	v_pk_mul_f32 v[32:33], v[10:11], v[36:37] op_sel_hi:[0,1]
	v_pk_add_f32 v[38:39], v[26:27], v[28:29] neg_lo:[0,1] neg_hi:[0,1]
	v_pk_add_f32 v[26:27], v[26:27], v[28:29]
	v_fma_f32 v28, v4, v34, -v31
	v_fma_f32 v29, v4, v35, v30
	v_fma_f32 v34, v8, v36, -v33
	v_fma_f32 v35, v8, v37, v32
	v_pk_mul_f32 v[36:37], v[14:15], v[38:39] op_sel_hi:[0,1]


; __device__ __forceinline__ float2 cmul(float2 a, float2 b) { return make_float2(a.x * b.x - a.y * b.y, a.x * b.y + a.y * b.x); }
; template <int LR, bool INV>
; __device__ __forceinline__ void fft_stages(float2 (&x)[1 << LR], const int r, const int s) {
;     ...
;       if (!INV) { const float2 p = x[m], q = x[m + hl]; x[m] = make_float2(p.x + q.x, p.y + q.y); x[m + hl] = cmul(make_float2(p.x - q.x, p.y - q.y), tw); }
	ds_write_b64 v40, v[26:27]
	v_fma_f32 v26, v12, v38, -v37
	v_fma_f32 v27, v12, v39, v36
	v_pk_add_f32 v[32:33], v[28:29], v[34:35] neg_lo:[0,1] neg_hi:[0,1]

; __device__ __forceinline__ float2 cmul(float2 a, float2 b) { return make_float2(a.x * b.x - a.y * b.y, a.x * b.y + a.y * b.x); }
; template <int LR, bool INV>
; __device__ __forceinline__ void fft_stages(float2 (&x)[1 << LR], const int r, const int s) {
;     ...
;       if (!INV) { const float2 p = x[m], q = x[m + hl]; x[m] = make_float2(p.x + q.x, p.y + q.y); x[m + hl] = cmul(make_float2(p.x - q.x, p.y - q.y), tw); }
	v_pk_add_f32 v[28:29], v[28:29], v[34:35]
	v_pk_mul_f32 v[30:31], v[14:15], v[32:33] op_sel_hi:[0,1]
	ds_write_b64 v41, v[26:27] offset:4096
	ds_write_b64 v42, v[28:29] offset:8192
	v_fma_f32 v26, v12, v32, -v31
	v_fma_f32 v27, v12, v33, v30

; __device__ __forceinline__ float2 cmul(float2 a, float2 b) { return make_float2(a.x * b.x - a.y * b.y, a.x * b.y + a.y * b.x); }
; template <int LR, bool INV>
; __device__ __forceinline__ void fft_stages(float2 (&x)[1 << LR], const int r, const int s) {
;     ...
;       const float2 tw = cmul(wb, wc);
;       if (!INV) { const float2 p = x[m], q = x[m + hl]; x[m] = make_float2(p.x + q.x, p.y + q.y); x[m + hl] = cmul(make_float2(p.x - q.x, p.y - q.y), tw); }
	ds_write_b64 v43, v[26:27] offset:12288
	v_mov_b32_e32 v26, v19
	v_pk_mul_f32 v[26:27], v[16:17], v[26:27] op_sel:[1,0] op_sel_hi:[0,0]
	v_fma_f32 v28, v16, v18, -v26
	v_fma_f32 v29, v17, v18, v27
	v_mov_b32_e32 v26, v21

; __device__ __forceinline__ float2 cmul(float2 a, float2 b) { return make_float2(a.x * b.x - a.y * b.y, a.x * b.y + a.y * b.x); }
; template <int LR, bool INV>
; __device__ __forceinline__ void fft_stages(float2 (&x)[1 << LR], const int r, const int s) {
;     ...
;       const float2 wc = make_float2(c16(j), INV ? s16(j) : -s16(j));
;       const float2 tw = cmul(wb, wc);
	v_pk_mul_f32 v[16:17], v[2:3], s[70:71] op_sel_hi:[1,0]
	s_nop 0
	v_pk_fma_f32 v[18:19], v[2:3], s[12:13], v[16:17] op_sel:[1,0,0] op_sel_hi:[0,1,1]
	v_pk_mul_f32 v[26:27], v[18:19], v[26:27] op_sel:[1,0] op_sel_hi:[0,0]
	v_fma_f32 v30, v18, v20, -v26
	v_fma_f32 v31, v19, v20, v27
	v_mov_b32_e32 v20, v23

; __device__ __forceinline__ float2 cmul(float2 a, float2 b) { return make_float2(a.x * b.x - a.y * b.y, a.x * b.y + a.y * b.x); }
; template <int LR, bool INV>
; __device__ __forceinline__ void fft_stages(float2 (&x)[1 << LR], const int r, const int s) {
;     ...
;       const float2 wc = make_float2(c16(j), INV ? s16(j) : -s16(j));
;       const float2 tw = cmul(wb, wc);
;       if (!INV) { const float2 p = x[m], q = x[m + hl]; x[m] = make_float2(p.x + q.x, p.y + q.y); x[m + hl] = cmul(make_float2(p.x - q.x, p.y - q.y), tw); }
	v_pk_fma_f32 v[18:19], v[2:3], s[90:91], v[2:3] op_sel:[1,0,0] op_sel_hi:[0,1,1] neg_lo:[0,0,1] neg_hi:[0,0,1]
	v_pk_mul_f32 v[20:21], v[18:19], v[20:21] op_sel:[1,0] op_sel_hi:[0,0]
	v_pk_fma_f32 v[2:3], v[2:3], s[70:71], v[16:17] op_sel:[1,0,0] op_sel_hi:[0,1,1]
	v_mov_b32_e32 v16, v25
	v_fma_f32 v26, v18, v22, -v20
	v_fma_f32 v27, v19, v22, v21
	v_pk_mul_f32 v[16:17], v[2:3], v[16:17] op_sel:[1,0] op_sel_hi:[0,0]

; __device__ __forceinline__ float2 cmul(float2 a, float2 b) { return make_float2(a.x * b.x - a.y * b.y, a.x * b.y + a.y * b.x); }
; template <int LR, bool INV>
; __device__ __forceinline__ void fft_stages(float2 (&x)[1 << LR], const int r, const int s) {
;     ...
;       if (!INV) { const float2 p = x[m], q = x[m + hl]; x[m] = make_float2(p.x + q.x, p.y + q.y); x[m + hl] = cmul(make_float2(p.x - q.x, p.y - q.y), tw); }
	v_fma_f32 v18, v2, v24, -v16
	v_fma_f32 v19, v3, v24, v17
	s_mov_b64 s[12:13], 0

; __device__ __forceinline__ float2 cmul(float2 a, float2 b) { return make_float2(a.x * b.x - a.y * b.y, a.x * b.y + a.y * b.x); }
; template <int LR, bool INV>
; __device__ __forceinline__ void fft_stages(float2 (&x)[1 << LR], const int r, const int s) {
;     ...
;       if (!INV) { const float2 p = x[m], q = x[m + hl]; x[m] = make_float2(p.x + q.x, p.y + q.y); x[m + hl] = cmul(make_float2(p.x - q.x, p.y - q.y), tw); }
	v_pk_add_f32 v[2:3], v[28:29], v[26:27] neg_lo:[0,1] neg_hi:[0,1]
	s_nop 0
	v_pk_mul_f32 v[6:7], v[6:7], v[2:3] op_sel_hi:[0,1]
	v_fma_f32 v16, v4, v2, -v7
	v_fma_f32 v17, v4, v3, v6

; __device__ __forceinline__ float2 cmul(float2 a, float2 b) { return make_float2(a.x * b.x - a.y * b.y, a.x * b.y + a.y * b.x); }
; template <int LR, bool INV>
; __device__ __forceinline__ void fft_stages(float2 (&x)[1 << LR], const int r, const int s) {
;     ...
;       if (!INV) { const float2 p = x[m], q = x[m + hl]; x[m] = make_float2(p.x + q.x, p.y + q.y); x[m + hl] = cmul(make_float2(p.x - q.x, p.y - q.y), tw); }
	v_pk_add_f32 v[2:3], v[30:31], v[18:19] neg_lo:[0,1] neg_hi:[0,1]
	s_nop 0
	v_pk_mul_f32 v[4:5], v[10:11], v[2:3] op_sel_hi:[0,1]
	v_fma_f32 v6, v8, v2, -v5
	v_fma_f32 v7, v8, v3, v4

; __device__ __forceinline__ float2 cmul(float2 a, float2 b) { return make_float2(a.x * b.x - a.y * b.y, a.x * b.y + a.y * b.x); }
; template <int LR, bool INV>
; __device__ __forceinline__ void fft_stages(float2 (&x)[1 << LR], const int r, const int s) {
;     ...
;       if (!INV) { const float2 p = x[m], q = x[m + hl]; x[m] = make_float2(p.x + q.x, p.y + q.y); x[m + hl] = cmul(make_float2(p.x - q.x, p.y - q.y), tw); }
	v_pk_add_f32 v[2:3], v[16:17], v[6:7] neg_lo:[0,1] neg_hi:[0,1]
	s_nop 0
	v_pk_mul_f32 v[4:5], v[14:15], v[2:3] op_sel_hi:[0,1]
	v_fma_f32 v8, v12, v2, -v5
	v_fma_f32 v9, v12, v3, v4

; __device__ __forceinline__ float bfl(unsigned w) { return __uint_as_float(w << 16); }
; #define tid ltid()
; template <int LR>
; __device__ __forceinline__ void fft_first(float2* X, const bf16* __restrict__ u0, const bf16* __restrict__ u1, const int tid) {
;   constexpr int R = 1 << LR;
;   float2 x[R];
; #pragma unroll
;   for (int m = 0; m < R / 2; ++m) x[m] = make_float2(bfl(u0[tid + 512 * m]), bfl(u1[tid + 512 * m]));
; #pragma unroll
;   for (int m = R / 2; m < R; ++m) x[m] = make_float2(0.f, 0.f);
;   fft_stages<LR, false>(x, tid, 512);
; #pragma unroll
;   for (int m = 0; m < R; ++m) X[PIDX(tid + 512 * m)] = x[m];
;   __syncthreads();
; }
; __global__ void __launch_bounds__(NTHR, 2) mega_fwd(Args a_unused) {
;     ...
;           for (int pr = 0; pr < 4; ++pr) {
;             bf16* u0 = urow + (size_t)(2 * pr) * L; bf16* u1 = u0 + L;
;             if (gsel) fft_first<4>(A, u0, u1, tid); else fft_first<3>(A, u0, u1, tid);
	v_pk_add_f32 v[2:3], v[28:29], v[26:27]
	v_pk_add_f32 v[4:5], v[30:31], v[18:19]
	s_nop 0
	v_pk_add_f32 v[10:11], v[2:3], v[4:5] neg_lo:[0,1] neg_hi:[0,1]
	v_pk_add_f32 v[2:3], v[2:3], v[4:5]
	v_pk_mul_f32 v[14:15], v[14:15], v[10:11] op_sel_hi:[0,1]
	v_fma_f32 v18, v12, v10, -v15
	v_fma_f32 v11, v12, v11, v14
	v_mov_b32_e32 v19, v11
	ds_write_b64 v44, v[2:3] offset:16384
	ds_write_b64 v45, v[18:19] offset:20480
	v_pk_add_f32 v[2:3], v[16:17], v[6:7]
	ds_write_b64 v46, v[2:3] offset:24576
	ds_write_b64 v47, v[8:9] offset:28672
	s_waitcnt lgkmcnt(0)
	s_barrier
.LBB0_671:
	s_andn2_b64 vcc, exec, s[12:13]
	s_cbranch_vccnz .LBB0_673
	v_mov_b32_e32 v2, v208
	s_mov_b32 s14, s71
	v_ashrrev_i32_e32 v3, 31, v2
	v_lshlrev_b64 v[4:5], 1, v[2:3]
	v_lshl_add_u64 v[6:7], s[40:41], 0, v[4:5]
	v_lshl_add_u64 v[4:5], s[42:43], 0, v[4:5]
	global_load_ushort v3, v[6:7], off
	global_load_ushort v20, v[4:5], off
	global_load_ushort v21, v[6:7], off offset:1024
	global_load_ushort v26, v[4:5], off offset:1024
	global_load_ushort v27, v[6:7], off offset:2048
	global_load_ushort v28, v[4:5], off offset:2048
	global_load_ushort v33, v[4:5], off offset:3072
	global_load_ushort v44, v[6:7], off offset:3072
	v_add_co_u32_e32 v6, vcc, s64, v6
	v_cvt_f32_i32_e32 v64, v2
	s_nop 0
	v_addc_co_u32_e32 v7, vcc, 0, v7, vcc
	v_add_co_u32_e32 v4, vcc, s64, v4
	s_mov_b32 s15, s70
	s_nop 0
	v_addc_co_u32_e32 v5, vcc, 0, v5, vcc
	global_load_ushort v45, v[6:7], off
	global_load_ushort v46, v[4:5], off
	global_load_ushort v47, v[6:7], off offset:1024
	global_load_ushort v48, v[4:5], off offset:1024
	global_load_ushort v49, v[6:7], off offset:2048
	global_load_ushort v50, v[4:5], off offset:2048
	global_load_ushort v51, v[4:5], off offset:3072
	global_load_ushort v52, v[6:7], off offset:3072
	v_mul_f32_e32 v4, 0x39000000, v64
	v_sin_f32_e32 v9, v4
	v_cos_f32_e32 v8, v4
	v_mul_f32_e32 v53, 0x39800000, v64
	s_mov_b32 s90, s75
	v_xor_b32_e32 v5, 0x80000000, v9
	v_mul_f32_e32 v10, 0, v9
	v_mov_b32_e32 v4, v8
	v_mul_f32_e32 v11, 0, v8
	v_mov_b32_e32 v36, v9
	v_mov_b32_e32 v37, v8
	s_mov_b32 s12, s71
	v_cos_f32_e32 v29, v53
	v_mul_f32_e32 v13, 0xbf3504f3, v9
	v_mul_f32_e32 v12, 0x3f3504f3, v8
	v_pk_add_f32 v[22:23], v[4:5], v[10:11] neg_lo:[0,1] neg_hi:[0,1]
	v_pk_mul_f32 v[4:5], v[36:37], s[14:15]
	v_pk_mul_f32 v[10:11], v[36:37], s[94:95] op_sel_hi:[1,0]
	v_pk_mul_f32 v[38:39], v[36:37], s[72:73]
	v_pk_fma_f32 v[6:7], v[8:9], s[90:91], v[8:9] op_sel:[0,0,1] op_sel_hi:[1,1,0] neg_lo:[0,0,1] neg_hi:[0,0,1]
	v_mul_f32_e32 v32, 0xbec3ef15, v8
	v_mul_f32_e32 v41, s72, v8
	v_pk_fma_f32 v[14:15], v[36:37], s[12:13], v[12:13] op_sel_hi:[1,0,1] neg_lo:[1,0,0] neg_hi:[1,0,0]
	v_pk_fma_f32 v[4:5], v[36:37], s[12:13], v[4:5] op_sel:[0,0,1] op_sel_hi:[1,0,0] neg_lo:[1,0,0] neg_hi:[1,0,0]
	v_pk_fma_f32 v[24:25], v[8:9], s[72:73], v[10:11] neg_lo:[0,0,1] neg_hi:[0,0,1]
	v_pk_mov_b32 v[42:43], v[10:11], v[10:11] op_sel:[1,0]

; __device__ __forceinline__ float bfl(unsigned w) { return __uint_as_float(w << 16); }
; __device__ __forceinline__ float2 cmul(float2 a, float2 b) { return make_float2(a.x * b.x - a.y * b.y, a.x * b.y + a.y * b.x); }
; #define tid ltid()
; template <int LR, bool INV>
; __device__ __forceinline__ void fft_stages(float2 (&x)[1 << LR], const int r, const int s) {
;   constexpr int R = 1 << LR;
; #pragma unroll
;   for (int st = 0; st < LR; ++st) {
;     const int hl = INV ? (1 << st) : (R >> (st + 1));
;     const float fb = (float)r * (0.5f / (float)(hl * s));
;     const float2 wb = make_float2(__builtin_amdgcn_cosf(fb), INV ? __builtin_amdgcn_sinf(fb) : -__builtin_amdgcn_sinf(fb));
; #pragma unroll
;     for (int m = 0; m < R; ++m) {
;       if (m & hl) continue;
;       const int k = m & (hl - 1); const int j = k * (8 / hl);
;       const float2 wc = make_float2(c16(j), INV ? s16(j) : -s16(j));
;       const float2 tw = cmul(wb, wc);
;       if (!INV) { const float2 p = x[m], q = x[m + hl]; x[m] = make_float2(p.x + q.x, p.y + q.y); x[m + hl] = cmul(make_float2(p.x - q.x, p.y - q.y), tw); }
;       else { const float2 p = x[m], q = cmul(x[m + hl], tw); x[m] = make_float2(p.x + q.x, p.y + q.y); x[m + hl] = make_float2(p.x - q.x, p.y - q.y); }
;     }
; template <int LR>
; __device__ __forceinline__ void fft_first(float2* X, const bf16* __restrict__ u0, const bf16* __restrict__ u1, const int tid) {
;   constexpr int R = 1 << LR;
;   float2 x[R];
; #pragma unroll
;   for (int m = 0; m < R / 2; ++m) x[m] = make_float2(bfl(u0[tid + 512 * m]), bfl(u1[tid + 512 * m]));
; #pragma unroll
;   for (int m = R / 2; m < R; ++m) x[m] = make_float2(0.f, 0.f);
;   fft_stages<LR, false>(x, tid, 512);
; #pragma unroll
;   for (int m = 0; m < R; ++m) X[PIDX(tid + 512 * m)] = x[m];
;   __syncthreads();
; }
	v_mov_b32_e32 v40, v38
	v_add_u32_e32 v60, 0x200, v2
	v_add_u32_e32 v61, 0x400, v2
	v_mul_f32_e32 v17, 0xbec3ef15, v9
	v_mov_b32_e32 v16, v42
	v_pk_add_f32 v[16:17], v[16:17], v[40:41] neg_lo:[0,1] neg_hi:[0,1]
	v_add_u32_e32 v62, 0x600, v2
	v_add_u32_e32 v63, 0x800, v2
	v_add_u32_e32 v65, 0xa00, v2
	v_add_u32_e32 v67, 0xe00, v2
	v_add_u32_e32 v66, 0xc00, v2
	s_waitcnt vmcnt(15)
	v_lshlrev_b32_e32 v34, 16, v3
	v_mul_f32_e32 v3, 0x3a000000, v64
	s_waitcnt vmcnt(13)
	v_lshlrev_b32_e32 v30, 16, v21
	s_waitcnt vmcnt(12)
	v_lshlrev_b32_e32 v31, 16, v26
	s_waitcnt vmcnt(11)
	v_lshlrev_b32_e32 v26, 16, v27
	s_waitcnt vmcnt(10)
	v_lshlrev_b32_e32 v27, 16, v28
	v_sin_f32_e32 v28, v53
	s_waitcnt vmcnt(9)
	v_lshlrev_b32_e32 v21, 16, v33
	v_mov_b32_e32 v33, v43
	v_lshlrev_b32_e32 v35, 16, v20
	v_pk_add_f32 v[54:55], v[32:33], v[40:41] neg_lo:[0,1] neg_hi:[0,1]
	s_waitcnt vmcnt(7)
	v_lshlrev_b32_e32 v18, 16, v45
	s_waitcnt vmcnt(6)
	v_lshlrev_b32_e32 v19, 16, v46
	v_mov_b32_e32 v32, v29
	v_mov_b32_e32 v33, v28
	v_pk_mul_f32 v[58:59], v[32:33], s[70:71]
	v_ashrrev_i32_e32 v33, 4, v60
	v_pk_add_f32 v[68:69], v[18:19], 0 op_sel_hi:[1,0]
	s_waitcnt vmcnt(0)
	v_lshlrev_b32_e32 v8, 16, v52
	v_pk_fma_f32 v[52:53], v[36:37], s[94:95], v[38:39] op_sel:[0,0,1] op_sel_hi:[1,0,0] neg_lo:[1,0,0] neg_hi:[1,0,0]
	v_cos_f32_e32 v37, v3
	v_sin_f32_e32 v3, v3
	v_lshlrev_b32_e32 v20, 16, v44
	v_lshlrev_b32_e32 v13, 16, v48
	v_lshlrev_b32_e32 v11, 16, v50
	v_fmamk_f32 v36, v3, 0x80000000, v37
	v_fma_f32 v42, v37, s91, -v3
	v_fma_f32 v38, v37, 0, -v3
	v_fma_f32 v40, v3, s91, -v37
	v_ashrrev_i32_e32 v37, 4, v61
	v_pk_add_f32 v[60:61], v[34:35], 0 op_sel_hi:[1,0]
	v_fmamk_f32 v48, v28, 0x80000000, v29
	v_fma_f32 v50, v29, s91, -v28
	v_pk_mul_f32 v[56:57], v[28:29], s[70:71]
	v_fma_f32 v44, v29, 0, -v28
	v_fma_f32 v46, v28, s91, -v29
	v_mul_f32_e32 v28, 0x3a800000, v64
	v_pk_add_f32 v[76:77], v[60:61], v[68:69] neg_lo:[0,1] neg_hi:[0,1]
	v_lshlrev_b32_e32 v12, 16, v47
	v_cos_f32_e32 v29, v28
	v_sin_f32_e32 v32, v28
	v_pk_mul_f32 v[78:79], v[50:51], v[76:77] op_sel_hi:[0,1]
	v_ashrrev_i32_e32 v39, 4, v62
	v_ashrrev_i32_e32 v41, 4, v63
	v_pk_add_f32 v[62:63], v[30:31], 0 op_sel_hi:[1,0]
	v_pk_add_f32 v[70:71], v[12:13], 0 op_sel_hi:[1,0]
	v_fma_f32 v80, v48, v76, -v79
	v_fma_f32 v81, v48, v77, v78

; __device__ __forceinline__ float2 cmul(float2 a, float2 b) { return make_float2(a.x * b.x - a.y * b.y, a.x * b.y + a.y * b.x); }
; template <int LR, bool INV>
; __device__ __forceinline__ void fft_stages(float2 (&x)[1 << LR], const int r, const int s) {
;     ...
;       if (!INV) { const float2 p = x[m], q = x[m + hl]; x[m] = make_float2(p.x + q.x, p.y + q.y); x[m + hl] = cmul(make_float2(p.x - q.x, p.y - q.y), tw); }
	v_pk_add_f32 v[76:77], v[62:63], v[70:71] neg_lo:[0,1] neg_hi:[0,1]
	v_pk_add_f32 v[78:79], v[56:57], v[56:57] op_sel:[0,1] op_sel_hi:[0,1] neg_lo:[0,1] neg_hi:[0,1]
	v_lshlrev_b32_e32 v10, 16, v49
	v_pk_mul_f32 v[82:83], v[78:79], v[76:77]
	v_sub_f32_e32 v56, v57, v59
	v_fmamk_f32 v28, v32, 0x80000000, v29
	v_fma_f32 v32, v29, s91, -v32
	v_lshl_add_u32 v29, v2, 3, 0
	v_ashrrev_i32_e32 v43, 4, v65
	v_ashrrev_i32_e32 v47, 4, v67
	v_pk_add_f32 v[64:65], v[26:27], 0 op_sel_hi:[1,0]
	v_pk_add_f32 v[72:73], v[10:11], 0 op_sel_hi:[1,0]
	v_fma_f32 v84, v56, v76, -v83
	v_fma_f32 v85, v56, v77, v82
	v_ashrrev_i32_e32 v45, 4, v66
	v_lshl_add_u32 v47, v47, 3, v29

; __device__ __forceinline__ float2 cmul(float2 a, float2 b) { return make_float2(a.x * b.x - a.y * b.y, a.x * b.y + a.y * b.x); }
; template <int LR, bool INV>
; __device__ __forceinline__ void fft_stages(float2 (&x)[1 << LR], const int r, const int s) {
;     ...
;       if (!INV) { const float2 p = x[m], q = x[m + hl]; x[m] = make_float2(p.x + q.x, p.y + q.y); x[m + hl] = cmul(make_float2(p.x - q.x, p.y - q.y), tw); }
	v_pk_add_f32 v[76:77], v[64:65], v[72:73] neg_lo:[0,1] neg_hi:[0,1]
	v_lshlrev_b32_e32 v9, 16, v51
	v_lshl_add_u32 v45, v45, 3, v29
	v_pk_mul_f32 v[82:83], v[46:47], v[76:77] op_sel_hi:[0,1]
	v_pk_add_f32 v[66:67], v[20:21], 0 op_sel_hi:[1,0]
	v_pk_add_f32 v[74:75], v[8:9], 0 op_sel_hi:[1,0]
	v_fma_f32 v86, v44, v76, -v83
	v_fma_f32 v87, v44, v77, v82

; __device__ __forceinline__ float2 cmul(float2 a, float2 b) { return make_float2(a.x * b.x - a.y * b.y, a.x * b.y + a.y * b.x); }
; template <int LR, bool INV>
; __device__ __forceinline__ void fft_stages(float2 (&x)[1 << LR], const int r, const int s) {
;     ...
;       if (!INV) { const float2 p = x[m], q = x[m + hl]; x[m] = make_float2(p.x + q.x, p.y + q.y); x[m + hl] = cmul(make_float2(p.x - q.x, p.y - q.y), tw); }
	v_pk_add_f32 v[76:77], v[66:67], v[74:75] neg_lo:[0,1] neg_hi:[0,1]
	v_sub_f32_e32 v82, v59, v57
	v_pk_mul_f32 v[88:89], v[82:83], v[76:77] op_sel_hi:[0,1]
	v_pk_add_f32 v[58:59], v[58:59], v[58:59] op_sel:[0,1] op_sel_hi:[0,1] neg_lo:[0,1] neg_hi:[0,1]
	v_fma_f32 v90, v58, v76, -v89
	v_fma_f32 v91, v59, v77, v88
	v_lshl_add_u32 v43, v43, 3, v29

; __device__ __forceinline__ float2 cmul(float2 a, float2 b) { return make_float2(a.x * b.x - a.y * b.y, a.x * b.y + a.y * b.x); }
; template <int LR, bool INV>
; __device__ __forceinline__ void fft_stages(float2 (&x)[1 << LR], const int r, const int s) {
;     ...
;       if (!INV) { const float2 p = x[m], q = x[m + hl]; x[m] = make_float2(p.x + q.x, p.y + q.y); x[m + hl] = cmul(make_float2(p.x - q.x, p.y - q.y), tw); }
	v_pk_add_f32 v[76:77], v[80:81], v[86:87] neg_lo:[0,1] neg_hi:[0,1]
	v_pk_add_f32 v[60:61], v[60:61], v[68:69]
	v_pk_add_f32 v[64:65], v[64:65], v[72:73]
	v_lshl_add_u32 v37, v37, 3, v29
	v_pk_mul_f32 v[88:89], v[42:43], v[76:77] op_sel_hi:[0,1]
	v_pk_add_f32 v[68:69], v[60:61], v[64:65] neg_lo:[0,1] neg_hi:[0,1]
	v_fma_f32 v92, v36, v76, -v89
	v_fma_f32 v93, v36, v77, v88
	v_pk_add_f32 v[62:63], v[62:63], v[70:71]
	v_pk_mul_f32 v[70:71], v[42:43], v[68:69] op_sel_hi:[0,1]
	v_lshl_add_u32 v41, v41, 3, v29

; __device__ __forceinline__ float2 cmul(float2 a, float2 b) { return make_float2(a.x * b.x - a.y * b.y, a.x * b.y + a.y * b.x); }
; template <int LR, bool INV>
; __device__ __forceinline__ void fft_stages(float2 (&x)[1 << LR], const int r, const int s) {
;     ...
;       if (!INV) { const float2 p = x[m], q = x[m + hl]; x[m] = make_float2(p.x + q.x, p.y + q.y); x[m + hl] = cmul(make_float2(p.x - q.x, p.y - q.y), tw); }
	v_pk_add_f32 v[76:77], v[84:85], v[90:91] neg_lo:[0,1] neg_hi:[0,1]
	v_pk_add_f32 v[66:67], v[66:67], v[74:75]
	v_fma_f32 v72, v36, v68, -v71
	v_fma_f32 v73, v36, v69, v70
	v_lshl_add_u32 v39, v39, 3, v29
	v_pk_mul_f32 v[88:89], v[40:41], v[76:77] op_sel_hi:[0,1]

; __device__ __forceinline__ float2 cmul(float2 a, float2 b) { return make_float2(a.x * b.x - a.y * b.y, a.x * b.y + a.y * b.x); }
; template <int LR, bool INV>
; __device__ __forceinline__ void fft_stages(float2 (&x)[1 << LR], const int r, const int s) {
;     ...
;       if (!INV) { const float2 p = x[m], q = x[m + hl]; x[m] = make_float2(p.x + q.x, p.y + q.y); x[m + hl] = cmul(make_float2(p.x - q.x, p.y - q.y), tw); }
	v_pk_add_f32 v[68:69], v[62:63], v[66:67] neg_lo:[0,1] neg_hi:[0,1]
	v_fma_f32 v94, v38, v76, -v89
	v_fma_f32 v95, v38, v77, v88
	v_pk_mul_f32 v[70:71], v[40:41], v[68:69] op_sel_hi:[0,1]

; __device__ __forceinline__ float2 cmul(float2 a, float2 b) { return make_float2(a.x * b.x - a.y * b.y, a.x * b.y + a.y * b.x); }
; template <int LR, bool INV>
; __device__ __forceinline__ void fft_stages(float2 (&x)[1 << LR], const int r, const int s) {
;     ...
;       if (!INV) { const float2 p = x[m], q = x[m + hl]; x[m] = make_float2(p.x + q.x, p.y + q.y); x[m + hl] = cmul(make_float2(p.x - q.x, p.y - q.y), tw); }
	v_fma_f32 v74, v38, v68, -v71
	v_fma_f32 v75, v38, v69, v70
	v_lshl_add_u32 v33, v33, 3, v29
	v_pk_add_f32 v[76:77], v[92:93], v[94:95] neg_lo:[0,1] neg_hi:[0,1]

; __device__ __forceinline__ float2 cmul(float2 a, float2 b) { return make_float2(a.x * b.x - a.y * b.y, a.x * b.y + a.y * b.x); }
; template <int LR, bool INV>
; __device__ __forceinline__ void fft_stages(float2 (&x)[1 << LR], const int r, const int s) {
;     ...
;       if (!INV) { const float2 p = x[m], q = x[m + hl]; x[m] = make_float2(p.x + q.x, p.y + q.y); x[m + hl] = cmul(make_float2(p.x - q.x, p.y - q.y), tw); }
	v_pk_mul_f32 v[88:89], v[32:33], v[76:77] op_sel_hi:[0,1]
	v_pk_add_f32 v[68:69], v[72:73], v[74:75] neg_lo:[0,1] neg_hi:[0,1]
	v_pk_add_f32 v[60:61], v[60:61], v[64:65]
	v_pk_add_f32 v[62:63], v[62:63], v[66:67]
	v_fma_f32 v96, v28, v76, -v89
	v_fma_f32 v97, v28, v77, v88
	v_pk_mul_f32 v[70:71], v[32:33], v[68:69] op_sel_hi:[0,1]
	v_pk_add_f32 v[64:65], v[60:61], v[62:63] neg_lo:[0,1] neg_hi:[0,1]
	v_ashrrev_i32_e32 v3, 4, v2

; __device__ __forceinline__ float2 cmul(float2 a, float2 b) { return make_float2(a.x * b.x - a.y * b.y, a.x * b.y + a.y * b.x); }
; template <int LR, bool INV>
; __device__ __forceinline__ void fft_stages(float2 (&x)[1 << LR], const int r, const int s) {
;     ...
;       if (!INV) { const float2 p = x[m], q = x[m + hl]; x[m] = make_float2(p.x + q.x, p.y + q.y); x[m + hl] = cmul(make_float2(p.x - q.x, p.y - q.y), tw); }
	v_fma_f32 v76, v28, v68, -v71
	v_fma_f32 v77, v28, v69, v70
	v_pk_mul_f32 v[66:67], v[32:33], v[64:65] op_sel_hi:[0,1]
	v_lshl_add_u32 v3, v3, 3, v29

; __device__ __forceinline__ float2 cmul(float2 a, float2 b) { return make_float2(a.x * b.x - a.y * b.y, a.x * b.y + a.y * b.x); }
; template <int LR, bool INV>
; __device__ __forceinline__ void fft_stages(float2 (&x)[1 << LR], const int r, const int s) {
;     ...
;       if (!INV) { const float2 p = x[m], q = x[m + hl]; x[m] = make_float2(p.x + q.x, p.y + q.y); x[m + hl] = cmul(make_float2(p.x - q.x, p.y - q.y), tw); }
	v_fma_f32 v68, v28, v64, -v67
	v_fma_f32 v69, v28, v65, v66
	v_pk_add_f32 v[60:61], v[60:61], v[62:63]

; __device__ __forceinline__ float2 cmul(float2 a, float2 b) { return make_float2(a.x * b.x - a.y * b.y, a.x * b.y + a.y * b.x); }
; #define tid ltid()
; template <int LR, bool INV>
; __device__ __forceinline__ void fft_stages(float2 (&x)[1 << LR], const int r, const int s) {
;     ...
;       if (!INV) { const float2 p = x[m], q = x[m + hl]; x[m] = make_float2(p.x + q.x, p.y + q.y); x[m + hl] = cmul(make_float2(p.x - q.x, p.y - q.y), tw); }
; template <int LR>
; __device__ __forceinline__ void fft_first(float2* X, const bf16* __restrict__ u0, const bf16* __restrict__ u1, const int tid) {
;     ...
;   for (int m = 0; m < R; ++m) X[PIDX(tid + 512 * m)] = x[m];
	ds_write_b64 v3, v[60:61]
	ds_write_b64 v33, v[68:69] offset:4096
	v_pk_add_f32 v[60:61], v[72:73], v[74:75]
	ds_write_b64 v37, v[60:61] offset:8192
	ds_write_b64 v39, v[76:77] offset:12288
	v_pk_add_f32 v[60:61], v[80:81], v[86:87]
	v_pk_add_f32 v[62:63], v[84:85], v[90:91]
	v_add_u32_e32 v3, 0x1000, v2
	v_pk_add_f32 v[64:65], v[60:61], v[62:63] neg_lo:[0,1] neg_hi:[0,1]
	v_ashrrev_i32_e32 v3, 4, v3
	v_pk_mul_f32 v[66:67], v[32:33], v[64:65] op_sel_hi:[0,1]
	v_lshl_add_u32 v33, v3, 3, v29
	v_add_u32_e32 v3, 0x1200, v2
	v_ashrrev_i32_e32 v3, 4, v3
	v_lshl_add_u32 v37, v3, 3, v29
	v_add_u32_e32 v3, 0x1400, v2
	v_ashrrev_i32_e32 v3, 4, v3
	v_lshl_add_u32 v39, v3, 3, v29
	v_add_u32_e32 v3, 0x1600, v2
	v_fma_f32 v68, v28, v64, -v67
	v_fma_f32 v65, v28, v65, v66
	v_pk_add_f32 v[60:61], v[60:61], v[62:63]
	v_ashrrev_i32_e32 v3, 4, v3
	v_mov_b32_e32 v69, v65
	ds_write_b64 v41, v[60:61] offset:16384
	ds_write_b64 v43, v[68:69] offset:20480
	v_lshl_add_u32 v41, v3, 3, v29
	v_add_u32_e32 v3, 0x1800, v2
	v_ashrrev_i32_e32 v3, 4, v3
	v_lshl_add_u32 v43, v3, 3, v29
	v_add_u32_e32 v3, 0x1a00, v2
	v_pk_add_f32 v[60:61], v[92:93], v[94:95]
	v_ashrrev_i32_e32 v3, 4, v3
	ds_write_b64 v45, v[60:61] offset:24576
	ds_write_b64 v47, v[96:97] offset:28672
	v_lshl_add_u32 v47, v3, 3, v29
	v_add_u32_e32 v3, 0x1c00, v2
	v_add_u32_e32 v2, 0x1e00, v2
	v_ashrrev_i32_e32 v3, 4, v3
	v_ashrrev_i32_e32 v2, 4, v2
	v_lshl_add_u32 v49, v3, 3, v29
	v_lshl_add_u32 v29, v2, 3, v29
	v_mov_b32_e32 v2, v35
	v_pk_mul_f32 v[2:3], v[22:23], v[2:3] op_sel:[1,0] op_sel_hi:[0,0]
	v_fma_f32 v60, v22, v34, -v2
	v_fma_f32 v3, v23, v34, v3
	v_mov_b32_e32 v2, v31
	v_mov_b32_e32 v61, v3
	v_pk_mul_f32 v[2:3], v[24:25], v[2:3] op_sel:[1,0] op_sel_hi:[0,0]
	v_fma_f32 v22, v24, v30, -v2
	v_fma_f32 v3, v25, v30, v3
	v_mov_b32_e32 v2, v27
	v_mov_b32_e32 v23, v3
	v_pk_mul_f32 v[2:3], v[14:15], v[2:3] op_sel:[1,0] op_sel_hi:[0,0]
	v_fma_f32 v24, v14, v26, -v2
	v_fma_f32 v3, v15, v26, v3
	v_mov_b32_e32 v2, v21
	v_mov_b32_e32 v25, v3
	v_pk_mul_f32 v[2:3], v[16:17], v[2:3] op_sel:[1,0] op_sel_hi:[0,0]
	v_fma_f32 v14, v16, v20, -v2
	v_fma_f32 v3, v17, v20, v3
	v_mov_b32_e32 v2, v19
	v_mov_b32_e32 v15, v3
	v_pk_mul_f32 v[2:3], v[6:7], v[2:3] op_sel:[1,0] op_sel_hi:[0,0]
	v_fma_f32 v16, v6, v18, -v2
	v_fma_f32 v3, v7, v18, v3
	v_mov_b32_e32 v2, v13
	v_mov_b32_e32 v17, v3
	v_pk_mul_f32 v[2:3], v[54:55], v[2:3] op_sel:[1,0] op_sel_hi:[0,0]
	v_fma_f32 v6, v54, v12, -v2
	v_fma_f32 v3, v55, v12, v3
	v_mov_b32_e32 v2, v11
	v_mov_b32_e32 v7, v3
	v_pk_mul_f32 v[2:3], v[4:5], v[2:3] op_sel:[1,0] op_sel_hi:[0,0]
	v_fma_f32 v12, v4, v10, -v2
	v_fma_f32 v3, v5, v10, v3
	v_mov_b32_e32 v2, v9
	v_mov_b32_e32 v13, v3
	v_pk_mul_f32 v[2:3], v[52:53], v[2:3] op_sel:[1,0] op_sel_hi:[0,0]
	v_fma_f32 v4, v52, v8, -v2
	v_fma_f32 v5, v53, v8, v3

; __device__ __forceinline__ float2 cmul(float2 a, float2 b) { return make_float2(a.x * b.x - a.y * b.y, a.x * b.y + a.y * b.x); }
; template <int LR, bool INV>
; __device__ __forceinline__ void fft_stages(float2 (&x)[1 << LR], const int r, const int s) {
;     ...
;       if (!INV) { const float2 p = x[m], q = x[m + hl]; x[m] = make_float2(p.x + q.x, p.y + q.y); x[m + hl] = cmul(make_float2(p.x - q.x, p.y - q.y), tw); }
	v_pk_add_f32 v[2:3], v[60:61], v[16:17] neg_lo:[0,1] neg_hi:[0,1]
	s_nop 0
	v_pk_mul_f32 v[8:9], v[50:51], v[2:3] op_sel_hi:[0,1]
	v_fma_f32 v10, v48, v2, -v9
	v_fma_f32 v11, v48, v3, v8

; __device__ __forceinline__ float2 cmul(float2 a, float2 b) { return make_float2(a.x * b.x - a.y * b.y, a.x * b.y + a.y * b.x); }
; template <int LR, bool INV>
; __device__ __forceinline__ void fft_stages(float2 (&x)[1 << LR], const int r, const int s) {
;     ...
;       if (!INV) { const float2 p = x[m], q = x[m + hl]; x[m] = make_float2(p.x + q.x, p.y + q.y); x[m + hl] = cmul(make_float2(p.x - q.x, p.y - q.y), tw); }
	v_pk_add_f32 v[2:3], v[22:23], v[6:7] neg_lo:[0,1] neg_hi:[0,1]
	v_pk_add_f32 v[6:7], v[22:23], v[6:7]
	v_pk_mul_f32 v[8:9], v[78:79], v[2:3]
	s_nop 0
	v_fma_f32 v18, v56, v2, -v9
	v_fma_f32 v19, v56, v3, v8

; __device__ __forceinline__ float2 cmul(float2 a, float2 b) { return make_float2(a.x * b.x - a.y * b.y, a.x * b.y + a.y * b.x); }
; template <int LR, bool INV>
; __device__ __forceinline__ void fft_stages(float2 (&x)[1 << LR], const int r, const int s) {
;     ...
;       if (!INV) { const float2 p = x[m], q = x[m + hl]; x[m] = make_float2(p.x + q.x, p.y + q.y); x[m + hl] = cmul(make_float2(p.x - q.x, p.y - q.y), tw); }
	v_pk_add_f32 v[2:3], v[24:25], v[12:13] neg_lo:[0,1] neg_hi:[0,1]
	s_nop 0
	v_pk_mul_f32 v[8:9], v[46:47], v[2:3] op_sel_hi:[0,1]
	v_fma_f32 v20, v44, v2, -v9
	v_fma_f32 v21, v44, v3, v8

; __device__ __forceinline__ float2 cmul(float2 a, float2 b) { return make_float2(a.x * b.x - a.y * b.y, a.x * b.y + a.y * b.x); }
; template <int LR, bool INV>
; __device__ __forceinline__ void fft_stages(float2 (&x)[1 << LR], const int r, const int s) {
;     ...
;       if (!INV) { const float2 p = x[m], q = x[m + hl]; x[m] = make_float2(p.x + q.x, p.y + q.y); x[m + hl] = cmul(make_float2(p.x - q.x, p.y - q.y), tw); }
	v_pk_add_f32 v[2:3], v[14:15], v[4:5] neg_lo:[0,1] neg_hi:[0,1]
	v_pk_add_f32 v[4:5], v[14:15], v[4:5]
	v_pk_mul_f32 v[8:9], v[82:83], v[2:3] op_sel_hi:[0,1]
	v_fma_f32 v26, v58, v2, -v9
	v_fma_f32 v27, v59, v3, v8

; __device__ __forceinline__ float2 cmul(float2 a, float2 b) { return make_float2(a.x * b.x - a.y * b.y, a.x * b.y + a.y * b.x); }
; template <int LR, bool INV>
; __device__ __forceinline__ void fft_stages(float2 (&x)[1 << LR], const int r, const int s) {
;     ...
;       if (!INV) { const float2 p = x[m], q = x[m + hl]; x[m] = make_float2(p.x + q.x, p.y + q.y); x[m + hl] = cmul(make_float2(p.x - q.x, p.y - q.y), tw); }
	v_pk_add_f32 v[2:3], v[10:11], v[20:21] neg_lo:[0,1] neg_hi:[0,1]
	s_nop 0
	v_pk_mul_f32 v[8:9], v[42:43], v[2:3] op_sel_hi:[0,1]
	v_fma_f32 v30, v36, v2, -v9
	v_fma_f32 v31, v36, v3, v8

; __device__ __forceinline__ float2 cmul(float2 a, float2 b) { return make_float2(a.x * b.x - a.y * b.y, a.x * b.y + a.y * b.x); }
; template <int LR, bool INV>
; __device__ __forceinline__ void fft_stages(float2 (&x)[1 << LR], const int r, const int s) {
;     ...
;       if (!INV) { const float2 p = x[m], q = x[m + hl]; x[m] = make_float2(p.x + q.x, p.y + q.y); x[m + hl] = cmul(make_float2(p.x - q.x, p.y - q.y), tw); }
	v_pk_add_f32 v[2:3], v[18:19], v[26:27] neg_lo:[0,1] neg_hi:[0,1]
	s_nop 0
	v_pk_mul_f32 v[8:9], v[40:41], v[2:3] op_sel_hi:[0,1]
	v_fma_f32 v34, v38, v2, -v9
	v_fma_f32 v35, v38, v3, v8

; __device__ __forceinline__ float2 cmul(float2 a, float2 b) { return make_float2(a.x * b.x - a.y * b.y, a.x * b.y + a.y * b.x); }
; template <int LR, bool INV>
; __device__ __forceinline__ void fft_stages(float2 (&x)[1 << LR], const int r, const int s) {
;     ...
;       if (!INV) { const float2 p = x[m], q = x[m + hl]; x[m] = make_float2(p.x + q.x, p.y + q.y); x[m + hl] = cmul(make_float2(p.x - q.x, p.y - q.y), tw); }
	v_pk_add_f32 v[2:3], v[30:31], v[34:35] neg_lo:[0,1] neg_hi:[0,1]
	s_nop 0
	v_pk_mul_f32 v[8:9], v[32:33], v[2:3] op_sel_hi:[0,1]
	v_fma_f32 v44, v28, v2, -v9
	v_fma_f32 v45, v28, v3, v8

; __device__ __forceinline__ float2 cmul(float2 a, float2 b) { return make_float2(a.x * b.x - a.y * b.y, a.x * b.y + a.y * b.x); }
; template <int LR, bool INV>
; __device__ __forceinline__ void fft_stages(float2 (&x)[1 << LR], const int r, const int s) {
;     ...
;       if (!INV) { const float2 p = x[m], q = x[m + hl]; x[m] = make_float2(p.x + q.x, p.y + q.y); x[m + hl] = cmul(make_float2(p.x - q.x, p.y - q.y), tw); }
	v_pk_add_f32 v[2:3], v[60:61], v[16:17]
	v_pk_add_f32 v[8:9], v[24:25], v[12:13]
	s_nop 0
	v_pk_add_f32 v[12:13], v[2:3], v[8:9] neg_lo:[0,1] neg_hi:[0,1]
	v_pk_add_f32 v[2:3], v[2:3], v[8:9]
	v_pk_mul_f32 v[14:15], v[42:43], v[12:13] op_sel_hi:[0,1]
	v_fma_f32 v16, v36, v12, -v15
	v_fma_f32 v17, v36, v13, v14

; __device__ __forceinline__ float2 cmul(float2 a, float2 b) { return make_float2(a.x * b.x - a.y * b.y, a.x * b.y + a.y * b.x); }
; template <int LR, bool INV>
; __device__ __forceinline__ void fft_stages(float2 (&x)[1 << LR], const int r, const int s) {
;     ...
;       if (!INV) { const float2 p = x[m], q = x[m + hl]; x[m] = make_float2(p.x + q.x, p.y + q.y); x[m + hl] = cmul(make_float2(p.x - q.x, p.y - q.y), tw); }
	v_pk_add_f32 v[12:13], v[6:7], v[4:5] neg_lo:[0,1] neg_hi:[0,1]
	v_pk_add_f32 v[4:5], v[6:7], v[4:5]
	v_pk_mul_f32 v[14:15], v[40:41], v[12:13] op_sel_hi:[0,1]
	v_fma_f32 v22, v38, v12, -v15
	v_fma_f32 v23, v38, v13, v14

; __device__ __forceinline__ float2 cmul(float2 a, float2 b) { return make_float2(a.x * b.x - a.y * b.y, a.x * b.y + a.y * b.x); }
; template <int LR, bool INV>
; __device__ __forceinline__ void fft_stages(float2 (&x)[1 << LR], const int r, const int s) {
;     ...
;       if (!INV) { const float2 p = x[m], q = x[m + hl]; x[m] = make_float2(p.x + q.x, p.y + q.y); x[m + hl] = cmul(make_float2(p.x - q.x, p.y - q.y), tw); }
	v_pk_add_f32 v[12:13], v[16:17], v[22:23] neg_lo:[0,1] neg_hi:[0,1]
	v_pk_add_f32 v[6:7], v[2:3], v[4:5] neg_lo:[0,1] neg_hi:[0,1]
	v_pk_mul_f32 v[14:15], v[32:33], v[12:13] op_sel_hi:[0,1]
	v_fma_f32 v24, v28, v12, -v15
	v_fma_f32 v25, v28, v13, v14
	v_pk_mul_f32 v[8:9], v[32:33], v[6:7] op_sel_hi:[0,1]

; __device__ __forceinline__ float2 cmul(float2 a, float2 b) { return make_float2(a.x * b.x - a.y * b.y, a.x * b.y + a.y * b.x); }
; template <int LR, bool INV>
; __device__ __forceinline__ void fft_stages(float2 (&x)[1 << LR], const int r, const int s) {
;     ...
;       if (!INV) { const float2 p = x[m], q = x[m + hl]; x[m] = make_float2(p.x + q.x, p.y + q.y); x[m + hl] = cmul(make_float2(p.x - q.x, p.y - q.y), tw); }
	v_fma_f32 v12, v28, v6, -v9
	v_fma_f32 v13, v28, v7, v8
	v_pk_add_f32 v[2:3], v[2:3], v[4:5]

; __device__ __forceinline__ float2 cmul(float2 a, float2 b) { return make_float2(a.x * b.x - a.y * b.y, a.x * b.y + a.y * b.x); }
; #define tid ltid()
; template <int LR, bool INV>
; __device__ __forceinline__ void fft_stages(float2 (&x)[1 << LR], const int r, const int s) {
;     ...
;       if (!INV) { const float2 p = x[m], q = x[m + hl]; x[m] = make_float2(p.x + q.x, p.y + q.y); x[m + hl] = cmul(make_float2(p.x - q.x, p.y - q.y), tw); }
; template <int LR>
; __device__ __forceinline__ void fft_first(float2* X, const bf16* __restrict__ u0, const bf16* __restrict__ u1, const int tid) {
;     ...
;   for (int m = 0; m < R; ++m) X[PIDX(tid + 512 * m)] = x[m];
;   __syncthreads();
	ds_write_b64 v33, v[2:3] offset:32768
	ds_write_b64 v37, v[12:13] offset:36864
	v_pk_add_f32 v[2:3], v[16:17], v[22:23]
	ds_write_b64 v39, v[2:3] offset:40960
	ds_write_b64 v41, v[24:25] offset:45056
	v_pk_add_f32 v[2:3], v[10:11], v[20:21]
	v_pk_add_f32 v[4:5], v[18:19], v[26:27]
	s_nop 0
	v_pk_add_f32 v[6:7], v[2:3], v[4:5] neg_lo:[0,1] neg_hi:[0,1]
	v_pk_add_f32 v[2:3], v[2:3], v[4:5]
	v_pk_mul_f32 v[8:9], v[32:33], v[6:7] op_sel_hi:[0,1]
	v_fma_f32 v10, v28, v6, -v9
	v_fma_f32 v7, v28, v7, v8
	v_mov_b32_e32 v11, v7
	ds_write_b64 v43, v[2:3] offset:49152
	ds_write_b64 v47, v[10:11] offset:53248
	v_pk_add_f32 v[2:3], v[30:31], v[34:35]
	ds_write_b64 v49, v[2:3] offset:57344
	ds_write_b64 v29, v[44:45] offset:61440
	s_waitcnt lgkmcnt(0)
	s_barrier

;     static __device__ __forceinline__ float sl(float g, float up) { return g * __builtin_amdgcn_rcpf(1.0f + __builtin_amdgcn_exp2f(-1.4426950408889634f * g)) * up; }
; #define tid ltid()
; template <int LR, bool INV>
; __device__ __forceinline__ void fft_pass(float2* X, const int N, const int sl, const int tid) {
;     ...
;   for (int g = tid; g < (N >> LR); g += NTHR) {
;     const int r = g & (s - 1);
;     const int i0 = ((g >> sl) << (sl + LR)) + r;
;     float2 x[R];
; #pragma unroll
;     for (int m = 0; m < R; ++m) x[m] = X[PIDX(i0 + (m << sl))];
.LBB0_675:
	v_and_or_b32 v33, v32, s53, v31
	v_ashrrev_i32_e32 v34, 4, v33
	v_lshlrev_b32_e32 v34, 3, v34
	v_lshlrev_b32_e32 v35, 3, v33
	v_add3_u32 v52, 0, v34, v35


;     static __device__ __forceinline__ float sl(float g, float up) { return g * __builtin_amdgcn_rcpf(1.0f + __builtin_amdgcn_exp2f(-1.4426950408889634f * g)) * up; }
; template <int LR, bool INV>
; __device__ __forceinline__ void fft_pass(float2* X, const int N, const int sl, const int tid) {
;     ...
;     const int i0 = ((g >> sl) << (sl + LR)) + r;
;     float2 x[R];
; #pragma unroll
;     for (int m = 0; m < R; ++m) x[m] = X[PIDX(i0 + (m << sl))];
	v_or_b32_e32 v33, 0x1c0, v33

;     static __device__ __forceinline__ float sl(float g, float up) { return g * __builtin_amdgcn_rcpf(1.0f + __builtin_amdgcn_exp2f(-1.4426950408889634f * g)) * up; }
; template <int LR, bool INV>
; __device__ __forceinline__ void fft_pass(float2* X, const int N, const int sl, const int tid) {
;     ...
;     const int i0 = ((g >> sl) << (sl + LR)) + r;
;     float2 x[R];
; #pragma unroll
;     for (int m = 0; m < R; ++m) x[m] = X[PIDX(i0 + (m << sl))];
	v_ashrrev_i32_e32 v33, 4, v33

;     static __device__ __forceinline__ float sl(float g, float up) { return g * __builtin_amdgcn_rcpf(1.0f + __builtin_amdgcn_exp2f(-1.4426950408889634f * g)) * up; }
; template <int LR, bool INV>
; __device__ __forceinline__ void fft_pass(float2* X, const int N, const int sl, const int tid) {
;     ...
;     const int i0 = ((g >> sl) << (sl + LR)) + r;
;     float2 x[R];
; #pragma unroll
;     for (int m = 0; m < R; ++m) x[m] = X[PIDX(i0 + (m << sl))];
	v_lshlrev_b32_e32 v33, 3, v33

;     static __device__ __forceinline__ float sl(float g, float up) { return g * __builtin_amdgcn_rcpf(1.0f + __builtin_amdgcn_exp2f(-1.4426950408889634f * g)) * up; }
; __device__ __forceinline__ float2 cmul(float2 a, float2 b) { return make_float2(a.x * b.x - a.y * b.y, a.x * b.y + a.y * b.x); }
; #define tid ltid()
; template <int LR, bool INV>
; __device__ __forceinline__ void fft_stages(float2 (&x)[1 << LR], const int r, const int s) {
;     ...
;     for (int m = 0; m < R; ++m) {
;       if (m & hl) continue;
;       const int k = m & (hl - 1); const int j = k * (8 / hl);
;       const float2 wc = make_float2(c16(j), INV ? s16(j) : -s16(j));
;       const float2 tw = cmul(wb, wc);
;       if (!INV) { const float2 p = x[m], q = x[m + hl]; x[m] = make_float2(p.x + q.x, p.y + q.y); x[m + hl] = cmul(make_float2(p.x - q.x, p.y - q.y), tw); }
;       else { const float2 p = x[m], q = cmul(x[m + hl], tw); x[m] = make_float2(p.x + q.x, p.y + q.y); x[m + hl] = make_float2(p.x - q.x, p.y - q.y); }
;     }
; template <int LR, bool INV>
; __device__ __forceinline__ void fft_pass(float2* X, const int N, const int sl, const int tid) {
;     ...
;   for (int g = tid; g < (N >> LR); g += NTHR) {
;     const int r = g & (s - 1);
;     const int i0 = ((g >> sl) << (sl + LR)) + r;
;     float2 x[R];
; #pragma unroll
;     for (int m = 0; m < R; ++m) x[m] = X[PIDX(i0 + (m << sl))];
;     fft_stages<LR, INV>(x, r, s);
; #pragma unroll
;     for (int m = 0; m < R; ++m) X[PIDX(i0 + (m << sl))] = x[m];
	v_add3_u32 v33, 0, v33, v35
	ds_read_b64 v[34:35], v52
	ds_read_b64 v[36:37], v52 offset:544
	ds_read_b64 v[38:39], v52 offset:1088
	ds_read_b64 v[40:41], v52 offset:1632
	ds_read_b64 v[42:43], v52 offset:2176
	ds_read_b64 v[44:45], v52 offset:2720
	ds_read_b64 v[46:47], v52 offset:3264
	ds_read_b64 v[48:49], v52 offset:3808
	v_add_u32_e32 v30, 0x200, v30
	s_waitcnt lgkmcnt(3)
	v_pk_add_f32 v[50:51], v[34:35], v[42:43]
	v_pk_add_f32 v[34:35], v[34:35], v[42:43] neg_lo:[0,1] neg_hi:[0,1]
	s_waitcnt lgkmcnt(2)
	v_pk_add_f32 v[42:43], v[36:37], v[44:45]
	v_pk_add_f32 v[36:37], v[36:37], v[44:45] neg_lo:[0,1] neg_hi:[0,1]
	s_waitcnt lgkmcnt(1)
	v_pk_add_f32 v[44:45], v[38:39], v[46:47]
	v_pk_add_f32 v[38:39], v[38:39], v[46:47] neg_lo:[0,1] neg_hi:[0,1]
	s_waitcnt lgkmcnt(0)
	v_pk_add_f32 v[46:47], v[40:41], v[48:49]
	v_pk_add_f32 v[40:41], v[40:41], v[48:49] neg_lo:[0,1] neg_hi:[0,1]
	v_pk_add_f32 v[48:49], v[50:51], v[44:45]
	v_pk_add_f32 v[44:45], v[50:51], v[44:45] neg_lo:[0,1] neg_hi:[0,1]
	v_pk_add_f32 v[50:51], v[42:43], v[46:47]
	v_pk_add_f32 v[42:43], v[42:43], v[46:47] neg_lo:[0,1] neg_hi:[0,1]
	v_pk_add_f32 v[46:47], v[48:49], v[50:51]
	v_pk_add_f32 v[48:49], v[48:49], v[50:51] neg_lo:[0,1] neg_hi:[0,1]
	ds_write_b64 v52, v[46:47]
	v_pk_mul_f32 v[46:47], v[16:17], v[48:49] op_sel:[0,1]
	v_cmp_le_i32_e32 vcc, s21, v30
	v_fma_f32 v50, v14, v48, -v46
	v_fma_f32 v51, v15, v48, v47
	v_add_u32_e32 v32, 0x1000, v32

; __device__ __forceinline__ float2 cmul(float2 a, float2 b) { return make_float2(a.x * b.x - a.y * b.y, a.x * b.y + a.y * b.x); }
; template <int LR, bool INV>
; __device__ __forceinline__ void fft_stages(float2 (&x)[1 << LR], const int r, const int s) {
;     ...
;       if (!INV) { const float2 p = x[m], q = x[m + hl]; x[m] = make_float2(p.x + q.x, p.y + q.y); x[m + hl] = cmul(make_float2(p.x - q.x, p.y - q.y), tw); }
	v_pk_mul_f32 v[46:47], v[18:19], v[44:45] op_sel:[0,1]
	ds_write_b64 v52, v[50:51] offset:544
	v_fma_f32 v48, v10, v44, -v46
	v_fma_f32 v49, v11, v44, v47
	s_or_b64 s[14:15], vcc, s[14:15]

; __device__ __forceinline__ float2 cmul(float2 a, float2 b) { return make_float2(a.x * b.x - a.y * b.y, a.x * b.y + a.y * b.x); }
; template <int LR, bool INV>
; __device__ __forceinline__ void fft_stages(float2 (&x)[1 << LR], const int r, const int s) {
;     ...
;       if (!INV) { const float2 p = x[m], q = x[m + hl]; x[m] = make_float2(p.x + q.x, p.y + q.y); x[m + hl] = cmul(make_float2(p.x - q.x, p.y - q.y), tw); }
	v_pk_mul_f32 v[44:45], v[20:21], v[42:43] op_sel:[0,1]
	s_nop 0
	v_fma_f32 v46, v12, v42, -v44
	v_fma_f32 v47, v13, v42, v45

; __device__ __forceinline__ float2 cmul(float2 a, float2 b) { return make_float2(a.x * b.x - a.y * b.y, a.x * b.y + a.y * b.x); }
; template <int LR, bool INV>
; __device__ __forceinline__ void fft_stages(float2 (&x)[1 << LR], const int r, const int s) {
;     ...
;       if (!INV) { const float2 p = x[m], q = x[m + hl]; x[m] = make_float2(p.x + q.x, p.y + q.y); x[m + hl] = cmul(make_float2(p.x - q.x, p.y - q.y), tw); }
	v_pk_add_f32 v[42:43], v[48:49], v[46:47]
	v_pk_add_f32 v[44:45], v[48:49], v[46:47] neg_lo:[0,1] neg_hi:[0,1]
	ds_write_b64 v52, v[42:43] offset:1088
	v_pk_mul_f32 v[42:43], v[16:17], v[44:45] op_sel:[0,1]
	s_nop 0
	v_fma_f32 v46, v14, v44, -v42
	v_fma_f32 v47, v15, v44, v43

; __device__ __forceinline__ float2 cmul(float2 a, float2 b) { return make_float2(a.x * b.x - a.y * b.y, a.x * b.y + a.y * b.x); }
; template <int LR, bool INV>
; __device__ __forceinline__ void fft_stages(float2 (&x)[1 << LR], const int r, const int s) {
;     ...
;       if (!INV) { const float2 p = x[m], q = x[m + hl]; x[m] = make_float2(p.x + q.x, p.y + q.y); x[m + hl] = cmul(make_float2(p.x - q.x, p.y - q.y), tw); }
	v_pk_mul_f32 v[42:43], v[22:23], v[34:35] op_sel:[0,1]
	ds_write_b64 v52, v[46:47] offset:1632
	v_fma_f32 v44, v2, v34, -v42
	v_fma_f32 v45, v3, v34, v43

; __device__ __forceinline__ float2 cmul(float2 a, float2 b) { return make_float2(a.x * b.x - a.y * b.y, a.x * b.y + a.y * b.x); }
; template <int LR, bool INV>
; __device__ __forceinline__ void fft_stages(float2 (&x)[1 << LR], const int r, const int s) {
;     ...
;       if (!INV) { const float2 p = x[m], q = x[m + hl]; x[m] = make_float2(p.x + q.x, p.y + q.y); x[m + hl] = cmul(make_float2(p.x - q.x, p.y - q.y), tw); }
	v_pk_mul_f32 v[34:35], v[24:25], v[36:37] op_sel:[0,1]
	s_nop 0
	v_fma_f32 v42, v4, v36, -v34
	v_fma_f32 v43, v5, v36, v35

; __device__ __forceinline__ float2 cmul(float2 a, float2 b) { return make_float2(a.x * b.x - a.y * b.y, a.x * b.y + a.y * b.x); }
; template <int LR, bool INV>
; __device__ __forceinline__ void fft_stages(float2 (&x)[1 << LR], const int r, const int s) {
;     ...
;       if (!INV) { const float2 p = x[m], q = x[m + hl]; x[m] = make_float2(p.x + q.x, p.y + q.y); x[m + hl] = cmul(make_float2(p.x - q.x, p.y - q.y), tw); }
	v_pk_mul_f32 v[34:35], v[26:27], v[38:39] op_sel:[0,1]
	s_nop 0
	v_fma_f32 v36, v6, v38, -v34
	v_fma_f32 v37, v7, v38, v35

; __device__ __forceinline__ float2 cmul(float2 a, float2 b) { return make_float2(a.x * b.x - a.y * b.y, a.x * b.y + a.y * b.x); }
; template <int LR, bool INV>
; __device__ __forceinline__ void fft_stages(float2 (&x)[1 << LR], const int r, const int s) {
;     ...
;       if (!INV) { const float2 p = x[m], q = x[m + hl]; x[m] = make_float2(p.x + q.x, p.y + q.y); x[m + hl] = cmul(make_float2(p.x - q.x, p.y - q.y), tw); }
	v_pk_mul_f32 v[34:35], v[28:29], v[40:41] op_sel:[0,1]
	s_nop 0
	v_fma_f32 v38, v8, v40, -v34
	v_fma_f32 v39, v9, v40, v35

; __device__ __forceinline__ float2 cmul(float2 a, float2 b) { return make_float2(a.x * b.x - a.y * b.y, a.x * b.y + a.y * b.x); }
; template <int LR, bool INV>
; __device__ __forceinline__ void fft_stages(float2 (&x)[1 << LR], const int r, const int s) {
;     ...
;       if (!INV) { const float2 p = x[m], q = x[m + hl]; x[m] = make_float2(p.x + q.x, p.y + q.y); x[m + hl] = cmul(make_float2(p.x - q.x, p.y - q.y), tw); }
	v_pk_add_f32 v[34:35], v[44:45], v[36:37]
	v_pk_add_f32 v[40:41], v[42:43], v[38:39]
	v_pk_add_f32 v[38:39], v[42:43], v[38:39] neg_lo:[0,1] neg_hi:[0,1]
	v_pk_add_f32 v[42:43], v[34:35], v[40:41]
	v_pk_add_f32 v[34:35], v[34:35], v[40:41] neg_lo:[0,1] neg_hi:[0,1]
	v_pk_add_f32 v[36:37], v[44:45], v[36:37] neg_lo:[0,1] neg_hi:[0,1]
	v_pk_mul_f32 v[40:41], v[16:17], v[34:35] op_sel:[0,1]
	ds_write_b64 v52, v[42:43] offset:2176
	v_fma_f32 v42, v14, v34, -v40
	v_fma_f32 v43, v15, v34, v41

; __device__ __forceinline__ float2 cmul(float2 a, float2 b) { return make_float2(a.x * b.x - a.y * b.y, a.x * b.y + a.y * b.x); }
; template <int LR, bool INV>
; __device__ __forceinline__ void fft_stages(float2 (&x)[1 << LR], const int r, const int s) {
;     ...
;       if (!INV) { const float2 p = x[m], q = x[m + hl]; x[m] = make_float2(p.x + q.x, p.y + q.y); x[m + hl] = cmul(make_float2(p.x - q.x, p.y - q.y), tw); }
	v_pk_mul_f32 v[34:35], v[18:19], v[36:37] op_sel:[0,1]
	ds_write_b64 v52, v[42:43] offset:2720
	v_fma_f32 v40, v10, v36, -v34
	v_fma_f32 v41, v11, v36, v35

; __device__ __forceinline__ float2 cmul(float2 a, float2 b) { return make_float2(a.x * b.x - a.y * b.y, a.x * b.y + a.y * b.x); }
; template <int LR, bool INV>
; __device__ __forceinline__ void fft_stages(float2 (&x)[1 << LR], const int r, const int s) {
;     ...
;       if (!INV) { const float2 p = x[m], q = x[m + hl]; x[m] = make_float2(p.x + q.x, p.y + q.y); x[m + hl] = cmul(make_float2(p.x - q.x, p.y - q.y), tw); }
	v_pk_mul_f32 v[34:35], v[20:21], v[38:39] op_sel:[0,1]
	s_nop 0
	v_fma_f32 v36, v12, v38, -v34
	v_fma_f32 v37, v13, v38, v35

; __device__ __forceinline__ float2 cmul(float2 a, float2 b) { return make_float2(a.x * b.x - a.y * b.y, a.x * b.y + a.y * b.x); }
; template <int LR, bool INV>
; __device__ __forceinline__ void fft_stages(float2 (&x)[1 << LR], const int r, const int s) {
;     ...
;   for (int st = 0; st < LR; ++st) {
;     const int hl = INV ? (1 << st) : (R >> (st + 1));
;     const float fb = (float)r * (0.5f / (float)(hl * s));
;     const float2 wb = make_float2(__builtin_amdgcn_cosf(fb), INV ? __builtin_amdgcn_sinf(fb) : -__builtin_amdgcn_sinf(fb));
; #pragma unroll
;     for (int m = 0; m < R; ++m) {
;       if (m & hl) continue;
;       const int k = m & (hl - 1); const int j = k * (8 / hl);
;       const float2 wc = make_float2(c16(j), INV ? s16(j) : -s16(j));
;       const float2 tw = cmul(wb, wc);
;       if (!INV) { const float2 p = x[m], q = x[m + hl]; x[m] = make_float2(p.x + q.x, p.y + q.y); x[m + hl] = cmul(make_float2(p.x - q.x, p.y - q.y), tw); }
;       else { const float2 p = x[m], q = cmul(x[m + hl], tw); x[m] = make_float2(p.x + q.x, p.y + q.y); x[m + hl] = make_float2(p.x - q.x, p.y - q.y); }
;     }
	v_pk_add_f32 v[34:35], v[40:41], v[36:37]
	v_pk_add_f32 v[36:37], v[40:41], v[36:37] neg_lo:[0,1] neg_hi:[0,1]
	ds_write_b64 v52, v[34:35] offset:3264
	v_pk_mul_f32 v[34:35], v[16:17], v[36:37] op_sel:[0,1]
	s_nop 0
	v_fma_f32 v38, v14, v36, -v34
	v_pk_fma_f32 v[34:35], v[14:15], v[36:37], v[34:35] op_sel_hi:[1,0,1]
	s_nop 0
	v_mov_b32_e32 v39, v35
	ds_write_b64 v52, v[38:39] offset:3808
	s_andn2_b64 exec, exec, s[14:15]
	s_cbranch_execnz .LBB0_675

;     static __device__ __forceinline__ float sl(float g, float up) { return g * __builtin_amdgcn_rcpf(1.0f + __builtin_amdgcn_exp2f(-1.4426950408889634f * g)) * up; }
; #define tid ltid()
; template <int LR, bool INV>
; __device__ __forceinline__ void fft_pass(float2* X, const int N, const int sl, const int tid) {
;     ...
;   for (int g = tid; g < (N >> LR); g += NTHR) {
;     const int r = g & (s - 1);
;     const int i0 = ((g >> sl) << (sl + LR)) + r;
;     float2 x[R];
; #pragma unroll
;     for (int m = 0; m < R; ++m) x[m] = X[PIDX(i0 + (m << sl))];
.LBB0_678:
	v_and_b32_e32 v33, 0xffffffc0, v32
	v_or_b32_e32 v34, v33, v31
	v_ashrrev_i32_e32 v35, 1, v33
	v_lshlrev_b32_e32 v34, 3, v34
	v_add3_u32 v54, 0, v35, v34
	v_or_b32_e32 v35, 16, v33
	v_ashrrev_i32_e32 v35, 4, v35
	v_lshlrev_b32_e32 v35, 3, v35
	v_add3_u32 v55, 0, v35, v34

;     static __device__ __forceinline__ float sl(float g, float up) { return g * __builtin_amdgcn_rcpf(1.0f + __builtin_amdgcn_exp2f(-1.4426950408889634f * g)) * up; }
; #define tid ltid()
; template <int LR, bool INV>
; __device__ __forceinline__ void fft_pass(float2* X, const int N, const int sl, const int tid) {
;     ...
;   for (int g = tid; g < (N >> LR); g += NTHR) {
;     const int r = g & (s - 1);
;     const int i0 = ((g >> sl) << (sl + LR)) + r;
;     float2 x[R];
; #pragma unroll
;     for (int m = 0; m < R; ++m) x[m] = X[PIDX(i0 + (m << sl))];
	v_or_b32_e32 v33, 48, v33

;     static __device__ __forceinline__ float sl(float g, float up) { return g * __builtin_amdgcn_rcpf(1.0f + __builtin_amdgcn_exp2f(-1.4426950408889634f * g)) * up; }
; #define tid ltid()
; template <int LR, bool INV>
; __device__ __forceinline__ void fft_pass(float2* X, const int N, const int sl, const int tid) {
;     ...
;   for (int g = tid; g < (N >> LR); g += NTHR) {
;     const int r = g & (s - 1);
;     const int i0 = ((g >> sl) << (sl + LR)) + r;
;     float2 x[R];
; #pragma unroll
;     for (int m = 0; m < R; ++m) x[m] = X[PIDX(i0 + (m << sl))];
	v_ashrrev_i32_e32 v33, 4, v33

;     static __device__ __forceinline__ float sl(float g, float up) { return g * __builtin_amdgcn_rcpf(1.0f + __builtin_amdgcn_exp2f(-1.4426950408889634f * g)) * up; }
; #define tid ltid()
; template <int LR, bool INV>
; __device__ __forceinline__ void fft_pass(float2* X, const int N, const int sl, const int tid) {
;     ...
;   for (int g = tid; g < (N >> LR); g += NTHR) {
;     const int r = g & (s - 1);
;     const int i0 = ((g >> sl) << (sl + LR)) + r;
;     float2 x[R];
; #pragma unroll
;     for (int m = 0; m < R; ++m) x[m] = X[PIDX(i0 + (m << sl))];
	v_lshlrev_b32_e32 v33, 3, v33

;     static __device__ __forceinline__ float sl(float g, float up) { return g * __builtin_amdgcn_rcpf(1.0f + __builtin_amdgcn_exp2f(-1.4426950408889634f * g)) * up; }
; __device__ __forceinline__ float2 cmul(float2 a, float2 b) { return make_float2(a.x * b.x - a.y * b.y, a.x * b.y + a.y * b.x); }
; #define tid ltid()
; template <int LR, bool INV>
; __device__ __forceinline__ void fft_stages(float2 (&x)[1 << LR], const int r, const int s) {
;   constexpr int R = 1 << LR;
; #pragma unroll
;   for (int st = 0; st < LR; ++st) {
;     const int hl = INV ? (1 << st) : (R >> (st + 1));
;     const float fb = (float)r * (0.5f / (float)(hl * s));
;     const float2 wb = make_float2(__builtin_amdgcn_cosf(fb), INV ? __builtin_amdgcn_sinf(fb) : -__builtin_amdgcn_sinf(fb));
; #pragma unroll
;     for (int m = 0; m < R; ++m) {
;       if (m & hl) continue;
;       const int k = m & (hl - 1); const int j = k * (8 / hl);
;       const float2 wc = make_float2(c16(j), INV ? s16(j) : -s16(j));
;       const float2 tw = cmul(wb, wc);
;       if (!INV) { const float2 p = x[m], q = x[m + hl]; x[m] = make_float2(p.x + q.x, p.y + q.y); x[m + hl] = cmul(make_float2(p.x - q.x, p.y - q.y), tw); }
;       else { const float2 p = x[m], q = cmul(x[m + hl], tw); x[m] = make_float2(p.x + q.x, p.y + q.y); x[m + hl] = make_float2(p.x - q.x, p.y - q.y); }
;     }
;   }
; }
; template <int LR, bool INV>
; __device__ __forceinline__ void fft_pass(float2* X, const int N, const int sl, const int tid) {
;   constexpr int R = 1 << LR;
;   const int s = 1 << sl;
;   for (int g = tid; g < (N >> LR); g += NTHR) {
;     const int r = g & (s - 1);
;     const int i0 = ((g >> sl) << (sl + LR)) + r;
;     float2 x[R];
; #pragma unroll
;     for (int m = 0; m < R; ++m) x[m] = X[PIDX(i0 + (m << sl))];
;     fft_stages<LR, INV>(x, r, s);
; #pragma unroll
;     for (int m = 0; m < R; ++m) X[PIDX(i0 + (m << sl))] = x[m];
;   }
	v_add3_u32 v33, 0, v33, v34
	ds_read2_b64 v[34:37], v54 offset1:8
	ds_read2_b64 v[38:41], v55 offset0:16 offset1:24
	ds_read2_b64 v[42:45], v55 offset0:33 offset1:41
	ds_read2_b64 v[46:49], v55 offset0:50 offset1:58
	v_add_u32_e32 v30, 0x200, v30
	v_cmp_le_i32_e32 vcc, s21, v30
	v_add_u32_e32 v32, 0x1000, v32
	s_waitcnt lgkmcnt(1)
	v_pk_add_f32 v[50:51], v[34:35], v[42:43]
	v_pk_add_f32 v[34:35], v[34:35], v[42:43] neg_lo:[0,1] neg_hi:[0,1]
	v_pk_add_f32 v[42:43], v[36:37], v[44:45]
	v_pk_add_f32 v[36:37], v[36:37], v[44:45] neg_lo:[0,1] neg_hi:[0,1]
	s_waitcnt lgkmcnt(0)
	v_pk_add_f32 v[44:45], v[38:39], v[46:47]
	v_pk_add_f32 v[38:39], v[38:39], v[46:47] neg_lo:[0,1] neg_hi:[0,1]
	v_pk_add_f32 v[46:47], v[40:41], v[48:49]
	v_pk_add_f32 v[40:41], v[40:41], v[48:49] neg_lo:[0,1] neg_hi:[0,1]
	v_pk_add_f32 v[48:49], v[50:51], v[44:45]
	v_pk_add_f32 v[44:45], v[50:51], v[44:45] neg_lo:[0,1] neg_hi:[0,1]
	v_pk_add_f32 v[50:51], v[42:43], v[46:47]
	v_pk_add_f32 v[42:43], v[42:43], v[46:47] neg_lo:[0,1] neg_hi:[0,1]
	v_pk_add_f32 v[46:47], v[48:49], v[50:51]
	v_pk_add_f32 v[48:49], v[48:49], v[50:51] neg_lo:[0,1] neg_hi:[0,1]
	s_or_b64 s[14:15], vcc, s[14:15]
	v_pk_mul_f32 v[50:51], v[16:17], v[48:49] op_sel:[0,1]
	s_nop 0
	v_fma_f32 v52, v14, v48, -v50
	v_fma_f32 v53, v15, v48, v51

; __device__ __forceinline__ float2 cmul(float2 a, float2 b) { return make_float2(a.x * b.x - a.y * b.y, a.x * b.y + a.y * b.x); }
; template <int LR, bool INV>
; __device__ __forceinline__ void fft_stages(float2 (&x)[1 << LR], const int r, const int s) {
;     ...
;   for (int st = 0; st < LR; ++st) {
;     const int hl = INV ? (1 << st) : (R >> (st + 1));
;     const float fb = (float)r * (0.5f / (float)(hl * s));
;     const float2 wb = make_float2(__builtin_amdgcn_cosf(fb), INV ? __builtin_amdgcn_sinf(fb) : -__builtin_amdgcn_sinf(fb));
; #pragma unroll
;     for (int m = 0; m < R; ++m) {
;       if (m & hl) continue;
;       const int k = m & (hl - 1); const int j = k * (8 / hl);
;       const float2 wc = make_float2(c16(j), INV ? s16(j) : -s16(j));
;       const float2 tw = cmul(wb, wc);
;       if (!INV) { const float2 p = x[m], q = x[m + hl]; x[m] = make_float2(p.x + q.x, p.y + q.y); x[m + hl] = cmul(make_float2(p.x - q.x, p.y - q.y), tw); }
;       else { const float2 p = x[m], q = cmul(x[m + hl], tw); x[m] = make_float2(p.x + q.x, p.y + q.y); x[m + hl] = make_float2(p.x - q.x, p.y - q.y); }
;     }
	ds_write2_b64 v54, v[46:47], v[52:53] offset1:8
	v_pk_mul_f32 v[46:47], v[18:19], v[44:45] op_sel:[0,1]
	s_nop 0
	v_fma_f32 v48, v10, v44, -v46
	v_fma_f32 v49, v11, v44, v47

; __device__ __forceinline__ float2 cmul(float2 a, float2 b) { return make_float2(a.x * b.x - a.y * b.y, a.x * b.y + a.y * b.x); }
; template <int LR, bool INV>
; __device__ __forceinline__ void fft_stages(float2 (&x)[1 << LR], const int r, const int s) {
;     ...
;   for (int st = 0; st < LR; ++st) {
;     const int hl = INV ? (1 << st) : (R >> (st + 1));
;     const float fb = (float)r * (0.5f / (float)(hl * s));
;     const float2 wb = make_float2(__builtin_amdgcn_cosf(fb), INV ? __builtin_amdgcn_sinf(fb) : -__builtin_amdgcn_sinf(fb));
; #pragma unroll
;     for (int m = 0; m < R; ++m) {
;       if (m & hl) continue;
;       const int k = m & (hl - 1); const int j = k * (8 / hl);
;       const float2 wc = make_float2(c16(j), INV ? s16(j) : -s16(j));
;       const float2 tw = cmul(wb, wc);
;       if (!INV) { const float2 p = x[m], q = x[m + hl]; x[m] = make_float2(p.x + q.x, p.y + q.y); x[m + hl] = cmul(make_float2(p.x - q.x, p.y - q.y), tw); }
;       else { const float2 p = x[m], q = cmul(x[m + hl], tw); x[m] = make_float2(p.x + q.x, p.y + q.y); x[m + hl] = make_float2(p.x - q.x, p.y - q.y); }
;     }
	v_pk_mul_f32 v[44:45], v[20:21], v[42:43] op_sel:[0,1]
	s_nop 0
	v_fma_f32 v46, v12, v42, -v44
	v_fma_f32 v47, v13, v42, v45

; __device__ __forceinline__ float2 cmul(float2 a, float2 b) { return make_float2(a.x * b.x - a.y * b.y, a.x * b.y + a.y * b.x); }
; template <int LR, bool INV>
; __device__ __forceinline__ void fft_stages(float2 (&x)[1 << LR], const int r, const int s) {
;     ...
;   for (int st = 0; st < LR; ++st) {
;     const int hl = INV ? (1 << st) : (R >> (st + 1));
;     const float fb = (float)r * (0.5f / (float)(hl * s));
;     const float2 wb = make_float2(__builtin_amdgcn_cosf(fb), INV ? __builtin_amdgcn_sinf(fb) : -__builtin_amdgcn_sinf(fb));
; #pragma unroll
;     for (int m = 0; m < R; ++m) {
;       if (m & hl) continue;
;       const int k = m & (hl - 1); const int j = k * (8 / hl);
;       const float2 wc = make_float2(c16(j), INV ? s16(j) : -s16(j));
;       const float2 tw = cmul(wb, wc);
;       if (!INV) { const float2 p = x[m], q = x[m + hl]; x[m] = make_float2(p.x + q.x, p.y + q.y); x[m + hl] = cmul(make_float2(p.x - q.x, p.y - q.y), tw); }
;       else { const float2 p = x[m], q = cmul(x[m + hl], tw); x[m] = make_float2(p.x + q.x, p.y + q.y); x[m + hl] = make_float2(p.x - q.x, p.y - q.y); }
;     }
	v_pk_add_f32 v[44:45], v[48:49], v[46:47] neg_lo:[0,1] neg_hi:[0,1]
	v_pk_add_f32 v[42:43], v[48:49], v[46:47]
	v_pk_mul_f32 v[46:47], v[16:17], v[44:45] op_sel:[0,1]
	s_nop 0
	v_fma_f32 v48, v14, v44, -v46
	v_fma_f32 v49, v15, v44, v47

; __device__ __forceinline__ float2 cmul(float2 a, float2 b) { return make_float2(a.x * b.x - a.y * b.y, a.x * b.y + a.y * b.x); }
; template <int LR, bool INV>
; __device__ __forceinline__ void fft_stages(float2 (&x)[1 << LR], const int r, const int s) {
;     ...
;   for (int st = 0; st < LR; ++st) {
;     const int hl = INV ? (1 << st) : (R >> (st + 1));
;     const float fb = (float)r * (0.5f / (float)(hl * s));
;     const float2 wb = make_float2(__builtin_amdgcn_cosf(fb), INV ? __builtin_amdgcn_sinf(fb) : -__builtin_amdgcn_sinf(fb));
; #pragma unroll
;     for (int m = 0; m < R; ++m) {
;       if (m & hl) continue;
;       const int k = m & (hl - 1); const int j = k * (8 / hl);
;       const float2 wc = make_float2(c16(j), INV ? s16(j) : -s16(j));
;       const float2 tw = cmul(wb, wc);
;       if (!INV) { const float2 p = x[m], q = x[m + hl]; x[m] = make_float2(p.x + q.x, p.y + q.y); x[m + hl] = cmul(make_float2(p.x - q.x, p.y - q.y), tw); }
;       else { const float2 p = x[m], q = cmul(x[m + hl], tw); x[m] = make_float2(p.x + q.x, p.y + q.y); x[m + hl] = make_float2(p.x - q.x, p.y - q.y); }
;     }
	ds_write2_b64 v55, v[42:43], v[48:49] offset0:16 offset1:24
	v_pk_mul_f32 v[42:43], v[22:23], v[34:35] op_sel:[0,1]
	s_nop 0
	v_fma_f32 v44, v2, v34, -v42
	v_fma_f32 v45, v3, v34, v43

; __device__ __forceinline__ float2 cmul(float2 a, float2 b) { return make_float2(a.x * b.x - a.y * b.y, a.x * b.y + a.y * b.x); }
; template <int LR, bool INV>
; __device__ __forceinline__ void fft_stages(float2 (&x)[1 << LR], const int r, const int s) {
;     ...
;   for (int st = 0; st < LR; ++st) {
;     const int hl = INV ? (1 << st) : (R >> (st + 1));
;     const float fb = (float)r * (0.5f / (float)(hl * s));
;     const float2 wb = make_float2(__builtin_amdgcn_cosf(fb), INV ? __builtin_amdgcn_sinf(fb) : -__builtin_amdgcn_sinf(fb));
; #pragma unroll
;     for (int m = 0; m < R; ++m) {
;       if (m & hl) continue;
;       const int k = m & (hl - 1); const int j = k * (8 / hl);
;       const float2 wc = make_float2(c16(j), INV ? s16(j) : -s16(j));
;       const float2 tw = cmul(wb, wc);
;       if (!INV) { const float2 p = x[m], q = x[m + hl]; x[m] = make_float2(p.x + q.x, p.y + q.y); x[m + hl] = cmul(make_float2(p.x - q.x, p.y - q.y), tw); }
;       else { const float2 p = x[m], q = cmul(x[m + hl], tw); x[m] = make_float2(p.x + q.x, p.y + q.y); x[m + hl] = make_float2(p.x - q.x, p.y - q.y); }
;     }
	v_pk_mul_f32 v[34:35], v[24:25], v[36:37] op_sel:[0,1]
	s_nop 0
	v_fma_f32 v42, v4, v36, -v34
	v_fma_f32 v43, v5, v36, v35

; __device__ __forceinline__ float2 cmul(float2 a, float2 b) { return make_float2(a.x * b.x - a.y * b.y, a.x * b.y + a.y * b.x); }
; template <int LR, bool INV>
; __device__ __forceinline__ void fft_stages(float2 (&x)[1 << LR], const int r, const int s) {
;     ...
;   for (int st = 0; st < LR; ++st) {
;     const int hl = INV ? (1 << st) : (R >> (st + 1));
;     const float fb = (float)r * (0.5f / (float)(hl * s));
;     const float2 wb = make_float2(__builtin_amdgcn_cosf(fb), INV ? __builtin_amdgcn_sinf(fb) : -__builtin_amdgcn_sinf(fb));
; #pragma unroll
;     for (int m = 0; m < R; ++m) {
;       if (m & hl) continue;
;       const int k = m & (hl - 1); const int j = k * (8 / hl);
;       const float2 wc = make_float2(c16(j), INV ? s16(j) : -s16(j));
;       const float2 tw = cmul(wb, wc);
;       if (!INV) { const float2 p = x[m], q = x[m + hl]; x[m] = make_float2(p.x + q.x, p.y + q.y); x[m + hl] = cmul(make_float2(p.x - q.x, p.y - q.y), tw); }
;       else { const float2 p = x[m], q = cmul(x[m + hl], tw); x[m] = make_float2(p.x + q.x, p.y + q.y); x[m + hl] = make_float2(p.x - q.x, p.y - q.y); }
;     }
	v_pk_mul_f32 v[34:35], v[26:27], v[38:39] op_sel:[0,1]
	s_nop 0
	v_fma_f32 v36, v6, v38, -v34
	v_fma_f32 v37, v7, v38, v35

; __device__ __forceinline__ float2 cmul(float2 a, float2 b) { return make_float2(a.x * b.x - a.y * b.y, a.x * b.y + a.y * b.x); }
; template <int LR, bool INV>
; __device__ __forceinline__ void fft_stages(float2 (&x)[1 << LR], const int r, const int s) {
;     ...
;   for (int st = 0; st < LR; ++st) {
;     const int hl = INV ? (1 << st) : (R >> (st + 1));
;     const float fb = (float)r * (0.5f / (float)(hl * s));
;     const float2 wb = make_float2(__builtin_amdgcn_cosf(fb), INV ? __builtin_amdgcn_sinf(fb) : -__builtin_amdgcn_sinf(fb));
; #pragma unroll
;     for (int m = 0; m < R; ++m) {
;       if (m & hl) continue;
;       const int k = m & (hl - 1); const int j = k * (8 / hl);
;       const float2 wc = make_float2(c16(j), INV ? s16(j) : -s16(j));
;       const float2 tw = cmul(wb, wc);
;       if (!INV) { const float2 p = x[m], q = x[m + hl]; x[m] = make_float2(p.x + q.x, p.y + q.y); x[m + hl] = cmul(make_float2(p.x - q.x, p.y - q.y), tw); }
;       else { const float2 p = x[m], q = cmul(x[m + hl], tw); x[m] = make_float2(p.x + q.x, p.y + q.y); x[m + hl] = make_float2(p.x - q.x, p.y - q.y); }
;     }
	v_pk_mul_f32 v[34:35], v[28:29], v[40:41] op_sel:[0,1]
	s_nop 0
	v_fma_f32 v38, v8, v40, -v34
	v_fma_f32 v39, v9, v40, v35

; __device__ __forceinline__ float2 cmul(float2 a, float2 b) { return make_float2(a.x * b.x - a.y * b.y, a.x * b.y + a.y * b.x); }
; template <int LR, bool INV>
; __device__ __forceinline__ void fft_stages(float2 (&x)[1 << LR], const int r, const int s) {
;     ...
;   for (int st = 0; st < LR; ++st) {
;     const int hl = INV ? (1 << st) : (R >> (st + 1));
;     const float fb = (float)r * (0.5f / (float)(hl * s));
;     const float2 wb = make_float2(__builtin_amdgcn_cosf(fb), INV ? __builtin_amdgcn_sinf(fb) : -__builtin_amdgcn_sinf(fb));
; #pragma unroll
;     for (int m = 0; m < R; ++m) {
;       if (m & hl) continue;
;       const int k = m & (hl - 1); const int j = k * (8 / hl);
;       const float2 wc = make_float2(c16(j), INV ? s16(j) : -s16(j));
;       const float2 tw = cmul(wb, wc);
;       if (!INV) { const float2 p = x[m], q = x[m + hl]; x[m] = make_float2(p.x + q.x, p.y + q.y); x[m + hl] = cmul(make_float2(p.x - q.x, p.y - q.y), tw); }
;       else { const float2 p = x[m], q = cmul(x[m + hl], tw); x[m] = make_float2(p.x + q.x, p.y + q.y); x[m + hl] = make_float2(p.x - q.x, p.y - q.y); }
;     }
	v_pk_add_f32 v[34:35], v[44:45], v[36:37]
	v_pk_add_f32 v[40:41], v[42:43], v[38:39]
	v_pk_add_f32 v[38:39], v[42:43], v[38:39] neg_lo:[0,1] neg_hi:[0,1]
	v_pk_add_f32 v[42:43], v[34:35], v[40:41]
	v_pk_add_f32 v[34:35], v[34:35], v[40:41] neg_lo:[0,1] neg_hi:[0,1]
	v_pk_add_f32 v[36:37], v[44:45], v[36:37] neg_lo:[0,1] neg_hi:[0,1]
	v_pk_mul_f32 v[40:41], v[16:17], v[34:35] op_sel:[0,1]
	s_nop 0
	v_fma_f32 v44, v14, v34, -v40
	v_fma_f32 v45, v15, v34, v41

; __device__ __forceinline__ float2 cmul(float2 a, float2 b) { return make_float2(a.x * b.x - a.y * b.y, a.x * b.y + a.y * b.x); }
; template <int LR, bool INV>
; __device__ __forceinline__ void fft_stages(float2 (&x)[1 << LR], const int r, const int s) {
;     ...
;   for (int st = 0; st < LR; ++st) {
;     const int hl = INV ? (1 << st) : (R >> (st + 1));
;     const float fb = (float)r * (0.5f / (float)(hl * s));
;     const float2 wb = make_float2(__builtin_amdgcn_cosf(fb), INV ? __builtin_amdgcn_sinf(fb) : -__builtin_amdgcn_sinf(fb));
; #pragma unroll
;     for (int m = 0; m < R; ++m) {
;       if (m & hl) continue;
;       const int k = m & (hl - 1); const int j = k * (8 / hl);
;       const float2 wc = make_float2(c16(j), INV ? s16(j) : -s16(j));
;       const float2 tw = cmul(wb, wc);
;       if (!INV) { const float2 p = x[m], q = x[m + hl]; x[m] = make_float2(p.x + q.x, p.y + q.y); x[m + hl] = cmul(make_float2(p.x - q.x, p.y - q.y), tw); }
;       else { const float2 p = x[m], q = cmul(x[m + hl], tw); x[m] = make_float2(p.x + q.x, p.y + q.y); x[m + hl] = make_float2(p.x - q.x, p.y - q.y); }
;     }
	v_pk_mul_f32 v[34:35], v[18:19], v[36:37] op_sel:[0,1]
	ds_write2_b64 v55, v[42:43], v[44:45] offset0:33 offset1:41
	v_fma_f32 v40, v10, v36, -v34
	v_fma_f32 v41, v11, v36, v35

; __device__ __forceinline__ float2 cmul(float2 a, float2 b) { return make_float2(a.x * b.x - a.y * b.y, a.x * b.y + a.y * b.x); }
; template <int LR, bool INV>
; __device__ __forceinline__ void fft_stages(float2 (&x)[1 << LR], const int r, const int s) {
;     ...
;   for (int st = 0; st < LR; ++st) {
;     const int hl = INV ? (1 << st) : (R >> (st + 1));
;     const float fb = (float)r * (0.5f / (float)(hl * s));
;     const float2 wb = make_float2(__builtin_amdgcn_cosf(fb), INV ? __builtin_amdgcn_sinf(fb) : -__builtin_amdgcn_sinf(fb));
; #pragma unroll
;     for (int m = 0; m < R; ++m) {
;       if (m & hl) continue;
;       const int k = m & (hl - 1); const int j = k * (8 / hl);
;       const float2 wc = make_float2(c16(j), INV ? s16(j) : -s16(j));
;       const float2 tw = cmul(wb, wc);
;       if (!INV) { const float2 p = x[m], q = x[m + hl]; x[m] = make_float2(p.x + q.x, p.y + q.y); x[m + hl] = cmul(make_float2(p.x - q.x, p.y - q.y), tw); }
;       else { const float2 p = x[m], q = cmul(x[m + hl], tw); x[m] = make_float2(p.x + q.x, p.y + q.y); x[m + hl] = make_float2(p.x - q.x, p.y - q.y); }
;     }
	v_pk_mul_f32 v[34:35], v[20:21], v[38:39] op_sel:[0,1]
	s_nop 0
	v_fma_f32 v36, v12, v38, -v34
	v_fma_f32 v37, v13, v38, v35

; __device__ __forceinline__ float2 cmul(float2 a, float2 b) { return make_float2(a.x * b.x - a.y * b.y, a.x * b.y + a.y * b.x); }
; template <int LR, bool INV>
; __device__ __forceinline__ void fft_stages(float2 (&x)[1 << LR], const int r, const int s) {
;     ...
;   for (int st = 0; st < LR; ++st) {
;     const int hl = INV ? (1 << st) : (R >> (st + 1));
;     const float fb = (float)r * (0.5f / (float)(hl * s));
;     const float2 wb = make_float2(__builtin_amdgcn_cosf(fb), INV ? __builtin_amdgcn_sinf(fb) : -__builtin_amdgcn_sinf(fb));
; #pragma unroll
;     for (int m = 0; m < R; ++m) {
;       if (m & hl) continue;
;       const int k = m & (hl - 1); const int j = k * (8 / hl);
;       const float2 wc = make_float2(c16(j), INV ? s16(j) : -s16(j));
;       const float2 tw = cmul(wb, wc);
;       if (!INV) { const float2 p = x[m], q = x[m + hl]; x[m] = make_float2(p.x + q.x, p.y + q.y); x[m + hl] = cmul(make_float2(p.x - q.x, p.y - q.y), tw); }
;       else { const float2 p = x[m], q = cmul(x[m + hl], tw); x[m] = make_float2(p.x + q.x, p.y + q.y); x[m + hl] = make_float2(p.x - q.x, p.y - q.y); }
;     }
	v_pk_add_f32 v[34:35], v[40:41], v[36:37]
	v_pk_add_f32 v[36:37], v[40:41], v[36:37] neg_lo:[0,1] neg_hi:[0,1]
	s_nop 0
	v_pk_mul_f32 v[38:39], v[16:17], v[36:37] op_sel:[0,1]
	s_nop 0
	v_fma_f32 v40, v14, v36, -v38
	v_pk_fma_f32 v[36:37], v[14:15], v[36:37], v[38:39] op_sel_hi:[1,0,1]
	s_nop 0
	v_mov_b32_e32 v41, v37
	ds_write2_b64 v55, v[34:35], v[40:41] offset0:50 offset1:58
	s_andn2_b64 exec, exec, s[14:15]
	s_cbranch_execnz .LBB0_678

; #define tid ltid()
; __device__ __forceinline__ void fft_mid(float2* X, const float2* Hb, const int N, const float invN, const int tid) {
;   for (int g = tid; g < (N >> 3); g += NTHR) {
;     const int i0 = g << 3; const int p0 = PIDX(i0);
;     float2 x[8];
; #pragma unroll
;     for (int m = 0; m < 8; ++m) x[m] = X[p0 + m];
;     fft_stages<3, false>(x, 0, 1);
; #pragma unroll
;     for (int m = 0; m < 8; ++m) { const float2 h = Hb[p0 + m]; const float2 v = x[m]; x[m] = make_float2((v.x * h.x - v.y * h.y) * invN, (v.x * h.y + v.y * h.x) * invN); }
;     fft_stages<3, true>(x, 0, 1);
; #pragma unroll
;     for (int m = 0; m < 8; ++m) X[p0 + m] = x[m];
;   }
;   __syncthreads();
; }
.LBB0_681:
	v_ashrrev_i32_e32 v4, 4, v3
	v_add_u32_e32 v4, v3, v4
	v_lshl_add_u32 v38, v4, 3, 0
	ds_read2_b64 v[4:7], v38 offset1:1
	ds_read2_b64 v[8:11], v38 offset0:2 offset1:3
	ds_read2_b64 v[12:15], v38 offset0:4 offset1:5
	ds_read2_b64 v[16:19], v38 offset0:6 offset1:7
	v_add_u32_e32 v2, 0x200, v2
	v_cmp_le_i32_e32 vcc, s21, v2
	v_add_u32_e32 v3, 0x1000, v3
	s_waitcnt lgkmcnt(1)
	v_pk_add_f32 v[20:21], v[4:5], v[12:13] neg_lo:[0,1] neg_hi:[0,1]
	v_pk_add_f32 v[4:5], v[4:5], v[12:13]
	v_pk_mul_f32 v[22:23], v[20:21], 0 op_sel_hi:[1,0]
	s_or_b64 s[14:15], vcc, s[14:15]
	v_pk_add_f32 v[24:25], v[20:21], v[22:23] op_sel:[0,1] op_sel_hi:[1,0] neg_lo:[0,1] neg_hi:[0,1]
	v_pk_add_f32 v[20:21], v[20:21], v[22:23] op_sel:[0,1] op_sel_hi:[1,0]
	s_waitcnt lgkmcnt(0)
	v_pk_add_f32 v[22:23], v[8:9], v[16:17] neg_lo:[0,1] neg_hi:[0,1]
	v_pk_mov_b32 v[20:21], v[24:25], v[20:21] op_sel:[1,0]
	v_pk_mul_f32 v[24:25], v[22:23], 0 op_sel_hi:[1,0]
	s_nop 0
	v_sub_f32_e32 v26, v25, v22
	v_add_f32_e32 v27, v24, v23

; #define tid ltid()
; __device__ __forceinline__ void fft_mid(float2* X, const float2* Hb, const int N, const float invN, const int tid) {
;   for (int g = tid; g < (N >> 3); g += NTHR) {
;     const int i0 = g << 3; const int p0 = PIDX(i0);
;     float2 x[8];
; #pragma unroll
;     for (int m = 0; m < 8; ++m) x[m] = X[p0 + m];
;     fft_stages<3, false>(x, 0, 1);
; #pragma unroll
;     for (int m = 0; m < 8; ++m) { const float2 h = Hb[p0 + m]; const float2 v = x[m]; x[m] = make_float2((v.x * h.x - v.y * h.y) * invN, (v.x * h.y + v.y * h.x) * invN); }
;     fft_stages<3, true>(x, 0, 1);
; #pragma unroll
;     for (int m = 0; m < 8; ++m) X[p0 + m] = x[m];
;   }
;   __syncthreads();
; }
	v_pk_add_f32 v[22:23], v[20:21], v[26:27] neg_lo:[0,1] neg_hi:[0,1]
	s_nop 0
	v_pk_mul_f32 v[24:25], v[22:23], 0 op_sel_hi:[1,0]
	s_nop 0
	v_sub_f32_e32 v28, v22, v25
	v_add_f32_e32 v29, v23, v24
	v_pk_add_f32 v[24:25], v[10:11], v[18:19]

; #define tid ltid()
; __device__ __forceinline__ void fft_mid(float2* X, const float2* Hb, const int N, const float invN, const int tid) {
;   for (int g = tid; g < (N >> 3); g += NTHR) {
;     const int i0 = g << 3; const int p0 = PIDX(i0);
;     float2 x[8];
; #pragma unroll
;     for (int m = 0; m < 8; ++m) x[m] = X[p0 + m];
;     fft_stages<3, false>(x, 0, 1);
; #pragma unroll
;     for (int m = 0; m < 8; ++m) { const float2 h = Hb[p0 + m]; const float2 v = x[m]; x[m] = make_float2((v.x * h.x - v.y * h.y) * invN, (v.x * h.y + v.y * h.x) * invN); }
;     fft_stages<3, true>(x, 0, 1);
; #pragma unroll
;     for (int m = 0; m < 8; ++m) X[p0 + m] = x[m];
;   }
;   __syncthreads();
; }
	v_pk_add_f32 v[22:23], v[6:7], v[14:15]
	v_pk_add_f32 v[6:7], v[6:7], v[14:15] neg_lo:[0,1] neg_hi:[0,1]
	v_pk_add_f32 v[10:11], v[10:11], v[18:19] neg_lo:[0,1] neg_hi:[0,1]
	v_mul_f32_e32 v15, 0x3f3504f3, v6
	v_mul_f32_e32 v6, 0x3f3504f3, v7
	v_mul_f32_e32 v34, 0xbf3504f3, v10
	v_mul_f32_e32 v11, 0xbf3504f3, v11
	v_sub_f32_e32 v14, v6, v15
	v_fmac_f32_e32 v15, 0x3f3504f3, v7
	v_pk_add_f32 v[6:7], v[8:9], v[16:17]
	v_add_f32_e32 v8, v34, v11
	v_fma_f32 v9, v10, s70, -v11
	v_pk_add_f32 v[10:11], v[4:5], v[6:7] neg_lo:[0,1] neg_hi:[0,1]
	v_pk_add_f32 v[18:19], v[22:23], v[24:25] neg_lo:[0,1] neg_hi:[0,1]
	v_pk_mul_f32 v[12:13], v[10:11], 0 op_sel_hi:[1,0]
	v_pk_mul_f32 v[30:31], v[18:19], 0 op_sel_hi:[1,0]
	v_pk_add_f32 v[16:17], v[10:11], v[12:13] op_sel:[0,1] op_sel_hi:[1,0] neg_lo:[0,1] neg_hi:[0,1]
	v_pk_add_f32 v[10:11], v[10:11], v[12:13] op_sel:[0,1] op_sel_hi:[1,0]
	v_pk_add_f32 v[12:13], v[14:15], v[8:9] neg_lo:[0,1] neg_hi:[0,1]
	v_pk_mov_b32 v[10:11], v[16:17], v[10:11] op_sel:[1,0]
	v_fma_f32 v16, v12, 0, -v13
	v_fma_f32 v17, v13, 0, v12
	v_sub_f32_e32 v32, v31, v18
	v_add_f32_e32 v33, v30, v19

; #define tid ltid()
; __device__ __forceinline__ void fft_mid(float2* X, const float2* Hb, const int N, const float invN, const int tid) {
;   for (int g = tid; g < (N >> 3); g += NTHR) {
;     const int i0 = g << 3; const int p0 = PIDX(i0);
;     float2 x[8];
; #pragma unroll
;     for (int m = 0; m < 8; ++m) x[m] = X[p0 + m];
;     fft_stages<3, false>(x, 0, 1);
; #pragma unroll
;     for (int m = 0; m < 8; ++m) { const float2 h = Hb[p0 + m]; const float2 v = x[m]; x[m] = make_float2((v.x * h.x - v.y * h.y) * invN, (v.x * h.y + v.y * h.x) * invN); }
;     fft_stages<3, true>(x, 0, 1);
; #pragma unroll
;     for (int m = 0; m < 8; ++m) X[p0 + m] = x[m];
;   }
;   __syncthreads();
; }
	v_pk_add_f32 v[12:13], v[22:23], v[24:25]
	v_pk_add_f32 v[4:5], v[4:5], v[6:7]

; #define tid ltid()
; __device__ __forceinline__ void fft_mid(float2* X, const float2* Hb, const int N, const float invN, const int tid) {
;   for (int g = tid; g < (N >> 3); g += NTHR) {
;     const int i0 = g << 3; const int p0 = PIDX(i0);
;     float2 x[8];
; #pragma unroll
;     for (int m = 0; m < 8; ++m) x[m] = X[p0 + m];
;     fft_stages<3, false>(x, 0, 1);
; #pragma unroll
;     for (int m = 0; m < 8; ++m) { const float2 h = Hb[p0 + m]; const float2 v = x[m]; x[m] = make_float2((v.x * h.x - v.y * h.y) * invN, (v.x * h.y + v.y * h.x) * invN); }
;     fft_stages<3, true>(x, 0, 1);
; #pragma unroll
;     for (int m = 0; m < 8; ++m) X[p0 + m] = x[m];
;   }
;   __syncthreads();
; }
	v_pk_add_f32 v[18:19], v[4:5], v[12:13]
	v_pk_add_f32 v[12:13], v[4:5], v[12:13] neg_lo:[0,1] neg_hi:[0,1]
	v_pk_add_f32 v[4:5], v[20:21], v[26:27]
	v_pk_add_f32 v[26:27], v[28:29], v[16:17]
	v_pk_add_f32 v[16:17], v[28:29], v[16:17] neg_lo:[0,1] neg_hi:[0,1]
	v_pk_add_f32 v[6:7], v[14:15], v[8:9]
	v_fma_f32 v28, 0, v16, v17
	v_fmac_f32_e32 v16, 0x80000000, v17
	v_add_u32_e32 v17, 0x11000, v38
	v_pk_add_f32 v[8:9], v[4:5], v[6:7]
	v_pk_add_f32 v[14:15], v[4:5], v[6:7] neg_lo:[0,1] neg_hi:[0,1]
	ds_read2_b64 v[4:7], v17 offset1:1
	v_fma_f32 v22, 0, v13, v12
	v_fmac_f32_e32 v13, 0x80000000, v12
	v_pk_add_f32 v[24:25], v[10:11], v[32:33]
	v_pk_add_f32 v[10:11], v[10:11], v[32:33] neg_lo:[0,1] neg_hi:[0,1]
	s_waitcnt lgkmcnt(0)
	v_pk_mul_f32 v[30:31], v[4:5], v[18:19] op_sel:[1,1] op_sel_hi:[0,1]
	v_fma_f32 v32, v4, v18, -v30
	v_fma_f32 v5, v5, v18, v31
	v_fma_f32 v12, 0, v10, v11
	v_mov_b32_e32 v4, v13
	v_mov_b32_e32 v33, v5
	v_pk_mul_f32 v[4:5], v[6:7], v[4:5] op_sel:[1,0] op_sel_hi:[0,0]
	v_fma_f32 v18, v6, v22, -v4
	v_fma_f32 v19, v7, v22, v5
	v_fmac_f32_e32 v10, 0x80000000, v11

; #define tid ltid()
; __device__ __forceinline__ void fft_mid(float2* X, const float2* Hb, const int N, const float invN, const int tid) {
;   for (int g = tid; g < (N >> 3); g += NTHR) {
;     const int i0 = g << 3; const int p0 = PIDX(i0);
;     float2 x[8];
; #pragma unroll
;     for (int m = 0; m < 8; ++m) x[m] = X[p0 + m];
;     fft_stages<3, false>(x, 0, 1);
; #pragma unroll
;     for (int m = 0; m < 8; ++m) { const float2 h = Hb[p0 + m]; const float2 v = x[m]; x[m] = make_float2((v.x * h.x - v.y * h.y) * invN, (v.x * h.y + v.y * h.x) * invN); }
;     fft_stages<3, true>(x, 0, 1);
; #pragma unroll
;     for (int m = 0; m < 8; ++m) X[p0 + m] = x[m];
;   }
;   __syncthreads();
; }
	ds_read2_b64 v[4:7], v17 offset0:2 offset1:3
	v_fma_f32 v20, 0, v14, v15
	v_fmac_f32_e32 v14, 0x80000000, v15
	v_pk_mul_f32 v[22:23], v[0:1], v[18:19]
	s_waitcnt lgkmcnt(0)
	v_pk_mul_f32 v[30:31], v[24:25], v[4:5] op_sel:[0,1] op_sel_hi:[0,0]
	v_fma_f32 v34, v25, v4, -v30
	v_fma_f32 v35, v25, v5, v31

; #define tid ltid()
; __device__ __forceinline__ void fft_mid(float2* X, const float2* Hb, const int N, const float invN, const int tid) {
;   for (int g = tid; g < (N >> 3); g += NTHR) {
;     const int i0 = g << 3; const int p0 = PIDX(i0);
;     float2 x[8];
; #pragma unroll
;     for (int m = 0; m < 8; ++m) x[m] = X[p0 + m];
;     fft_stages<3, false>(x, 0, 1);
; #pragma unroll
;     for (int m = 0; m < 8; ++m) { const float2 h = Hb[p0 + m]; const float2 v = x[m]; x[m] = make_float2((v.x * h.x - v.y * h.y) * invN, (v.x * h.y + v.y * h.x) * invN); }
;     fft_stages<3, true>(x, 0, 1);
; #pragma unroll
;     for (int m = 0; m < 8; ++m) X[p0 + m] = x[m];
;   }
;   __syncthreads();
; }
	v_pk_mul_f32 v[4:5], v[10:11], v[6:7] op_sel:[0,1] op_sel_hi:[0,0]
	v_fma_f32 v10, v6, v12, -v4
	v_fma_f32 v11, v7, v12, v5

; #define tid ltid()
; __device__ __forceinline__ void fft_mid(float2* X, const float2* Hb, const int N, const float invN, const int tid) {
;   for (int g = tid; g < (N >> 3); g += NTHR) {
;     const int i0 = g << 3; const int p0 = PIDX(i0);
;     float2 x[8];
; #pragma unroll
;     for (int m = 0; m < 8; ++m) x[m] = X[p0 + m];
;     fft_stages<3, false>(x, 0, 1);
; #pragma unroll
;     for (int m = 0; m < 8; ++m) { const float2 h = Hb[p0 + m]; const float2 v = x[m]; x[m] = make_float2((v.x * h.x - v.y * h.y) * invN, (v.x * h.y + v.y * h.x) * invN); }
;     fft_stages<3, true>(x, 0, 1);
; #pragma unroll
;     for (int m = 0; m < 8; ++m) X[p0 + m] = x[m];
;   }
;   __syncthreads();
; }
	ds_read2_b64 v[4:7], v17 offset0:4 offset1:5
	v_pk_mul_f32 v[12:13], v[0:1], v[10:11]
	s_waitcnt lgkmcnt(0)
	v_pk_mul_f32 v[24:25], v[8:9], v[4:5] op_sel:[0,1] op_sel_hi:[0,0]
	v_pk_fma_f32 v[30:31], v[8:9], v[4:5], v[24:25] op_sel:[1,0,0] neg_lo:[0,0,1] neg_hi:[0,0,1]
	v_fma_f32 v9, v9, v5, v25
	v_pk_mul_f32 v[4:5], v[14:15], v[6:7] op_sel:[0,1] op_sel_hi:[0,0]
	v_fma_f32 v14, v20, v6, -v4
	v_fma_f32 v15, v20, v7, v5

; #define tid ltid()
; __device__ __forceinline__ void fft_mid(float2* X, const float2* Hb, const int N, const float invN, const int tid) {
;   for (int g = tid; g < (N >> 3); g += NTHR) {
;     const int i0 = g << 3; const int p0 = PIDX(i0);
;     float2 x[8];
; #pragma unroll
;     for (int m = 0; m < 8; ++m) x[m] = X[p0 + m];
;     fft_stages<3, false>(x, 0, 1);
; #pragma unroll
;     for (int m = 0; m < 8; ++m) { const float2 h = Hb[p0 + m]; const float2 v = x[m]; x[m] = make_float2((v.x * h.x - v.y * h.y) * invN, (v.x * h.y + v.y * h.x) * invN); }
;     fft_stages<3, true>(x, 0, 1);
; #pragma unroll
;     for (int m = 0; m < 8; ++m) X[p0 + m] = x[m];
;   }
;   __syncthreads();
; }
	ds_read2_b64 v[4:7], v17 offset0:6 offset1:7
	v_mov_b32_e32 v8, v30
	v_mul_f32_e32 v24, v0, v30
	v_pk_mul_f32 v[20:21], v[0:1], v[14:15]
	v_pk_mul_f32 v[12:13], v[12:13], 0 op_sel_hi:[1,0]
	s_waitcnt lgkmcnt(0)
	v_pk_mul_f32 v[30:31], v[26:27], v[4:5] op_sel:[0,1] op_sel_hi:[0,0]
	v_fma_f32 v36, v27, v4, -v30
	v_fma_f32 v37, v27, v5, v31

; #define tid ltid()
; __device__ __forceinline__ void fft_mid(float2* X, const float2* Hb, const int N, const float invN, const int tid) {
;   for (int g = tid; g < (N >> 3); g += NTHR) {
;     const int i0 = g << 3; const int p0 = PIDX(i0);
;     float2 x[8];
; #pragma unroll
;     for (int m = 0; m < 8; ++m) x[m] = X[p0 + m];
;     fft_stages<3, false>(x, 0, 1);
; #pragma unroll
;     for (int m = 0; m < 8; ++m) { const float2 h = Hb[p0 + m]; const float2 v = x[m]; x[m] = make_float2((v.x * h.x - v.y * h.y) * invN, (v.x * h.y + v.y * h.x) * invN); }
;     fft_stages<3, true>(x, 0, 1);
; #pragma unroll
;     for (int m = 0; m < 8; ++m) X[p0 + m] = x[m];
;   }
;   __syncthreads();
; }
	v_pk_mul_f32 v[4:5], v[16:17], v[6:7] op_sel:[0,1] op_sel_hi:[0,0]
	v_fma_f32 v16, v28, v6, -v4
	v_fma_f32 v17, v28, v7, v5
	v_pk_mul_f32 v[6:7], v[22:23], 0 op_sel_hi:[1,0]

; #define tid ltid()
; __device__ __forceinline__ void fft_mid(float2* X, const float2* Hb, const int N, const float invN, const int tid) {
;   for (int g = tid; g < (N >> 3); g += NTHR) {
;     const int i0 = g << 3; const int p0 = PIDX(i0);
;     float2 x[8];
; #pragma unroll
;     for (int m = 0; m < 8; ++m) x[m] = X[p0 + m];
;     fft_stages<3, false>(x, 0, 1);
; #pragma unroll
;     for (int m = 0; m < 8; ++m) { const float2 h = Hb[p0 + m]; const float2 v = x[m]; x[m] = make_float2((v.x * h.x - v.y * h.y) * invN, (v.x * h.y + v.y * h.x) * invN); }
;     fft_stages<3, true>(x, 0, 1);
; #pragma unroll
;     for (int m = 0; m < 8; ++m) X[p0 + m] = x[m];
;   }
;   __syncthreads();
; }
	v_fma_f32 v22, v0, v18, -v7
	v_fma_f32 v7, v1, v19, v6
	v_fma_f32 v18, v0, v10, -v13
	v_fma_f32 v19, v1, v11, v12
	v_pk_mul_f32 v[12:13], v[20:21], 0 op_sel_hi:[1,0]
	v_pk_mul_f32 v[4:5], v[0:1], v[16:17]
	v_fma_f32 v20, v0, v14, -v13
	v_pk_fma_f32 v[12:13], v[0:1], v[14:15], v[12:13] op_sel:[0,0,1] op_sel_hi:[1,1,0]
	v_pk_mul_f32 v[4:5], v[4:5], 0 op_sel_hi:[1,0]
	v_mov_b32_e32 v21, v13

; #define tid ltid()
; __device__ __forceinline__ void fft_mid(float2* X, const float2* Hb, const int N, const float invN, const int tid) {
;   for (int g = tid; g < (N >> 3); g += NTHR) {
;     const int i0 = g << 3; const int p0 = PIDX(i0);
;     float2 x[8];
; #pragma unroll
;     for (int m = 0; m < 8; ++m) x[m] = X[p0 + m];
;     fft_stages<3, false>(x, 0, 1);
; #pragma unroll
;     for (int m = 0; m < 8; ++m) { const float2 h = Hb[p0 + m]; const float2 v = x[m]; x[m] = make_float2((v.x * h.x - v.y * h.y) * invN, (v.x * h.y + v.y * h.x) * invN); }
;     fft_stages<3, true>(x, 0, 1);
; #pragma unroll
;     for (int m = 0; m < 8; ++m) X[p0 + m] = x[m];
;   }
;   __syncthreads();
; }
	v_pk_fma_f32 v[14:15], v[0:1], v[8:9], v[20:21]
	v_fma_f32 v9, v1, v9, -v13
	v_fma_f32 v12, v0, v16, -v5
	v_fma_f32 v13, v1, v17, v4
	v_pk_fma_f32 v[10:11], v[0:1], v[34:35], v[18:19]

; #define tid ltid()
; __device__ __forceinline__ void fft_mid(float2* X, const float2* Hb, const int N, const float invN, const int tid) {
;   for (int g = tid; g < (N >> 3); g += NTHR) {
;     const int i0 = g << 3; const int p0 = PIDX(i0);
;     float2 x[8];
; #pragma unroll
;     for (int m = 0; m < 8; ++m) x[m] = X[p0 + m];
;     fft_stages<3, false>(x, 0, 1);
; #pragma unroll
;     for (int m = 0; m < 8; ++m) { const float2 h = Hb[p0 + m]; const float2 v = x[m]; x[m] = make_float2((v.x * h.x - v.y * h.y) * invN, (v.x * h.y + v.y * h.x) * invN); }
;     fft_stages<3, true>(x, 0, 1);
; #pragma unroll
;     for (int m = 0; m < 8; ++m) X[p0 + m] = x[m];
;   }
;   __syncthreads();
; }
	v_pk_fma_f32 v[4:5], v[0:1], v[36:37], v[12:13]
	v_pk_mul_f32 v[16:17], v[10:11], 0 op_sel_hi:[1,0]
	v_pk_fma_f32 v[12:13], v[0:1], v[36:37], v[12:13] neg_lo:[0,0,1] neg_hi:[0,0,1]
	v_sub_f32_e32 v26, v10, v17
	v_add_f32_e32 v11, v11, v16
	v_pk_mul_f32 v[16:17], v[4:5], 0 op_sel_hi:[1,0]
	v_mul_f32_e32 v25, 0, v12
	v_sub_f32_e32 v28, v4, v17
	v_add_f32_e32 v29, v5, v16
	v_mov_b32_e32 v21, v13

; #define tid ltid()
; __device__ __forceinline__ void fft_mid(float2* X, const float2* Hb, const int N, const float invN, const int tid) {
;   for (int g = tid; g < (N >> 3); g += NTHR) {
;     const int i0 = g << 3; const int p0 = PIDX(i0);
;     float2 x[8];
; #pragma unroll
;     for (int m = 0; m < 8; ++m) x[m] = X[p0 + m];
;     fft_stages<3, false>(x, 0, 1);
; #pragma unroll
;     for (int m = 0; m < 8; ++m) { const float2 h = Hb[p0 + m]; const float2 v = x[m]; x[m] = make_float2((v.x * h.x - v.y * h.y) * invN, (v.x * h.y + v.y * h.x) * invN); }
;     fft_stages<3, true>(x, 0, 1);
; #pragma unroll
;     for (int m = 0; m < 8; ++m) X[p0 + m] = x[m];
;   }
;   __syncthreads();
; }
	v_pk_add_f32 v[4:5], v[14:15], v[28:29]
	v_fmac_f32_e32 v12, 0, v13
	v_pk_add_f32 v[16:17], v[24:25], v[20:21] neg_lo:[0,1] neg_hi:[0,1]
	v_add_f32_e32 v20, v9, v12
	v_sub_f32_e32 v24, v9, v12
	v_pk_mul_f32 v[8:9], v[4:5], 0 op_sel_hi:[1,0]
	v_pk_fma_f32 v[18:19], v[0:1], v[34:35], v[18:19] neg_lo:[0,0,1] neg_hi:[0,0,1]
	v_mov_b32_e32 v23, v7
	v_add_f32_e32 v21, v16, v17
	v_sub_f32_e32 v12, v4, v9
	v_add_f32_e32 v5, v5, v8
	v_mul_f32_e32 v9, 0x3f3504f3, v20
	v_mul_f32_e32 v20, 0x3f3504f3, v24
	v_fma_f32 v24, v18, 0, -v19
	v_fma_f32 v25, v19, 0, v18
	v_pk_fma_f32 v[6:7], v[0:1], v[32:33], v[22:23]
	v_mov_b32_e32 v27, v11
	v_mul_f32_e32 v8, 0x3f3504f3, v21
	v_pk_fma_f32 v[22:23], v[0:1], v[32:33], v[22:23] neg_lo:[0,0,1] neg_hi:[0,0,1]

; #define tid ltid()
; __device__ __forceinline__ void fft_mid(float2* X, const float2* Hb, const int N, const float invN, const int tid) {
;   for (int g = tid; g < (N >> 3); g += NTHR) {
;     const int i0 = g << 3; const int p0 = PIDX(i0);
;     float2 x[8];
; #pragma unroll
;     for (int m = 0; m < 8; ++m) x[m] = X[p0 + m];
;     fft_stages<3, false>(x, 0, 1);
; #pragma unroll
;     for (int m = 0; m < 8; ++m) { const float2 h = Hb[p0 + m]; const float2 v = x[m]; x[m] = make_float2((v.x * h.x - v.y * h.y) * invN, (v.x * h.y + v.y * h.x) * invN); }
;     fft_stages<3, true>(x, 0, 1);
; #pragma unroll
;     for (int m = 0; m < 8; ++m) X[p0 + m] = x[m];
;   }
;   __syncthreads();
; }
	v_pk_add_f32 v[10:11], v[6:7], v[26:27]
	v_mov_b32_e32 v13, v5
	v_pk_add_f32 v[18:19], v[22:23], v[24:25]
	v_sub_f32_e32 v8, v8, v9
	v_fmac_f32_e32 v9, 0x3f3504f3, v21
	v_pk_add_f32 v[4:5], v[10:11], v[12:13]
	v_pk_add_f32 v[30:31], v[18:19], v[8:9]
	ds_write2_b64 v38, v[4:5], v[30:31] offset1:1
	v_pk_add_f32 v[4:5], v[6:7], v[26:27] neg_lo:[0,1] neg_hi:[0,1]
	v_pk_add_f32 v[6:7], v[14:15], v[28:29] neg_lo:[0,1] neg_hi:[0,1]
	v_pk_add_f32 v[16:17], v[16:17], v[16:17] op_sel:[0,1] op_sel_hi:[0,1] neg_lo:[0,1] neg_hi:[0,1]
	v_fma_f32 v14, v6, 0, -v7
	v_fma_f32 v15, v7, 0, v6
	v_pk_fma_f32 v[16:17], v[16:17], s[70:71], v[20:21] op_sel_hi:[1,1,0] neg_lo:[0,0,1] neg_hi:[0,0,1]

; #define tid ltid()
; __device__ __forceinline__ void fft_mid(float2* X, const float2* Hb, const int N, const float invN, const int tid) {
;   for (int g = tid; g < (N >> 3); g += NTHR) {
;     const int i0 = g << 3; const int p0 = PIDX(i0);
;     float2 x[8];
; #pragma unroll
;     for (int m = 0; m < 8; ++m) x[m] = X[p0 + m];
;     fft_stages<3, false>(x, 0, 1);
; #pragma unroll
;     for (int m = 0; m < 8; ++m) { const float2 h = Hb[p0 + m]; const float2 v = x[m]; x[m] = make_float2((v.x * h.x - v.y * h.y) * invN, (v.x * h.y + v.y * h.x) * invN); }
;     fft_stages<3, true>(x, 0, 1);
; #pragma unroll
;     for (int m = 0; m < 8; ++m) X[p0 + m] = x[m];
;   }
;   __syncthreads();
; }
	v_pk_add_f32 v[20:21], v[22:23], v[24:25] neg_lo:[0,1] neg_hi:[0,1]
	v_pk_add_f32 v[6:7], v[4:5], v[14:15]
	v_pk_add_f32 v[22:23], v[20:21], v[16:17]
	ds_write2_b64 v38, v[6:7], v[22:23] offset0:2 offset1:3
	v_pk_add_f32 v[6:7], v[10:11], v[12:13] neg_lo:[0,1] neg_hi:[0,1]
	v_pk_add_f32 v[8:9], v[18:19], v[8:9] neg_lo:[0,1] neg_hi:[0,1]
	ds_write2_b64 v38, v[6:7], v[8:9] offset0:4 offset1:5
	v_pk_add_f32 v[4:5], v[4:5], v[14:15] neg_lo:[0,1] neg_hi:[0,1]
	v_pk_add_f32 v[6:7], v[20:21], v[16:17] neg_lo:[0,1] neg_hi:[0,1]
	ds_write2_b64 v38, v[4:5], v[6:7] offset0:6 offset1:7
	s_andn2_b64 exec, exec, s[14:15]
	s_cbranch_execnz .LBB0_681

;     static __device__ __forceinline__ float sl(float g, float up) { return g * __builtin_amdgcn_rcpf(1.0f + __builtin_amdgcn_exp2f(-1.4426950408889634f * g)) * up; }
; #define tid ltid()
; template <int LR, bool INV>
; __device__ __forceinline__ void fft_pass(float2* X, const int N, const int sl, const int tid) {
;     ...
;   for (int g = tid; g < (N >> LR); g += NTHR) {
;     const int r = g & (s - 1);
;     const int i0 = ((g >> sl) << (sl + LR)) + r;
;     float2 x[R];
; #pragma unroll
;     for (int m = 0; m < R; ++m) x[m] = X[PIDX(i0 + (m << sl))];
.LBB0_684:
	v_and_b32_e32 v33, 0xffffffc0, v32
	v_or_b32_e32 v34, v33, v31
	v_ashrrev_i32_e32 v35, 1, v33
	v_or_b32_e32 v36, 16, v33

;     static __device__ __forceinline__ float sl(float g, float up) { return g * __builtin_amdgcn_rcpf(1.0f + __builtin_amdgcn_exp2f(-1.4426950408889634f * g)) * up; }
; #define tid ltid()
; template <int LR, bool INV>
; __device__ __forceinline__ void fft_pass(float2* X, const int N, const int sl, const int tid) {
;     ...
;   for (int g = tid; g < (N >> LR); g += NTHR) {
;     const int r = g & (s - 1);
;     const int i0 = ((g >> sl) << (sl + LR)) + r;
;     float2 x[R];
; #pragma unroll
;     for (int m = 0; m < R; ++m) x[m] = X[PIDX(i0 + (m << sl))];
	v_or_b32_e32 v33, 48, v33
	v_lshl_add_u32 v34, v34, 3, 0
	v_ashrrev_i32_e32 v36, 4, v36

;     static __device__ __forceinline__ float sl(float g, float up) { return g * __builtin_amdgcn_rcpf(1.0f + __builtin_amdgcn_exp2f(-1.4426950408889634f * g)) * up; }
; #define tid ltid()
; template <int LR, bool INV>
; __device__ __forceinline__ void fft_pass(float2* X, const int N, const int sl, const int tid) {
;     ...
;   for (int g = tid; g < (N >> LR); g += NTHR) {
;     const int r = g & (s - 1);
;     const int i0 = ((g >> sl) << (sl + LR)) + r;
;     float2 x[R];
; #pragma unroll
;     for (int m = 0; m < R; ++m) x[m] = X[PIDX(i0 + (m << sl))];
	v_ashrrev_i32_e32 v33, 4, v33
	v_add_u32_e32 v60, v34, v35
	v_lshl_add_u32 v61, v36, 3, v34

;     static __device__ __forceinline__ float sl(float g, float up) { return g * __builtin_amdgcn_rcpf(1.0f + __builtin_amdgcn_exp2f(-1.4426950408889634f * g)) * up; }
; __device__ __forceinline__ float2 cmul(float2 a, float2 b) { return make_float2(a.x * b.x - a.y * b.y, a.x * b.y + a.y * b.x); }
; #define tid ltid()
; template <int LR, bool INV>
; __device__ __forceinline__ void fft_stages(float2 (&x)[1 << LR], const int r, const int s) {
;   constexpr int R = 1 << LR;
; #pragma unroll
;   for (int st = 0; st < LR; ++st) {
;     const int hl = INV ? (1 << st) : (R >> (st + 1));
;     const float fb = (float)r * (0.5f / (float)(hl * s));
;     const float2 wb = make_float2(__builtin_amdgcn_cosf(fb), INV ? __builtin_amdgcn_sinf(fb) : -__builtin_amdgcn_sinf(fb));
; #pragma unroll
;     for (int m = 0; m < R; ++m) {
;       if (m & hl) continue;
;       const int k = m & (hl - 1); const int j = k * (8 / hl);
;       const float2 wc = make_float2(c16(j), INV ? s16(j) : -s16(j));
;       const float2 tw = cmul(wb, wc);
;       if (!INV) { const float2 p = x[m], q = x[m + hl]; x[m] = make_float2(p.x + q.x, p.y + q.y); x[m + hl] = cmul(make_float2(p.x - q.x, p.y - q.y), tw); }
;       else { const float2 p = x[m], q = cmul(x[m + hl], tw); x[m] = make_float2(p.x + q.x, p.y + q.y); x[m + hl] = make_float2(p.x - q.x, p.y - q.y); }
;     }
;   }
; }
; template <int LR, bool INV>
; __device__ __forceinline__ void fft_pass(float2* X, const int N, const int sl, const int tid) {
;   constexpr int R = 1 << LR;
;   const int s = 1 << sl;
;   for (int g = tid; g < (N >> LR); g += NTHR) {
;     const int r = g & (s - 1);
;     const int i0 = ((g >> sl) << (sl + LR)) + r;
;     float2 x[R];
; #pragma unroll
;     for (int m = 0; m < R; ++m) x[m] = X[PIDX(i0 + (m << sl))];
;     fft_stages<LR, INV>(x, r, s);
; #pragma unroll
;     for (int m = 0; m < R; ++m) X[PIDX(i0 + (m << sl))] = x[m];
;   }
	v_lshl_add_u32 v33, v33, 3, v34
	ds_read2_b64 v[34:37], v60 offset1:8
	ds_read2_b64 v[38:41], v61 offset0:16 offset1:24
	ds_read2_b64 v[42:45], v61 offset0:33 offset1:41
	ds_read2_b64 v[46:49], v61 offset0:50 offset1:58
	v_add_u32_e32 v30, 0x200, v30
	s_waitcnt lgkmcnt(3)
	v_pk_mul_f32 v[50:51], v[36:37], v[2:3]
	s_waitcnt lgkmcnt(2)
	v_pk_mul_f32 v[52:53], v[2:3], v[40:41]
	s_waitcnt lgkmcnt(1)
	v_pk_mul_f32 v[54:55], v[2:3], v[44:45]
	s_waitcnt lgkmcnt(0)
	v_pk_mul_f32 v[56:57], v[2:3], v[48:49]
	v_fma_f32 v58, v36, v6, -v51
	v_fma_f32 v37, v37, v7, v50
	v_fma_f32 v50, v6, v40, -v53
	v_fma_f32 v51, v7, v41, v52
	v_fma_f32 v52, v6, v44, -v55
	v_fma_f32 v53, v7, v45, v54
	v_fma_f32 v54, v6, v48, -v57
	v_fma_f32 v55, v7, v49, v56


;     static __device__ __forceinline__ float sl(float g, float up) { return g * __builtin_amdgcn_rcpf(1.0f + __builtin_amdgcn_exp2f(-1.4426950408889634f * g)) * up; }
; __device__ __forceinline__ float2 cmul(float2 a, float2 b) { return make_float2(a.x * b.x - a.y * b.y, a.x * b.y + a.y * b.x); }
; #define tid ltid()
; template <int LR, bool INV>
; __device__ __forceinline__ void fft_stages(float2 (&x)[1 << LR], const int r, const int s) {
;   constexpr int R = 1 << LR;
; #pragma unroll
;   for (int st = 0; st < LR; ++st) {
;     const int hl = INV ? (1 << st) : (R >> (st + 1));
;     const float fb = (float)r * (0.5f / (float)(hl * s));
;     const float2 wb = make_float2(__builtin_amdgcn_cosf(fb), INV ? __builtin_amdgcn_sinf(fb) : -__builtin_amdgcn_sinf(fb));
; #pragma unroll
;     for (int m = 0; m < R; ++m) {
;       if (m & hl) continue;
;       const int k = m & (hl - 1); const int j = k * (8 / hl);
;       const float2 wc = make_float2(c16(j), INV ? s16(j) : -s16(j));
;       const float2 tw = cmul(wb, wc);
;       if (!INV) { const float2 p = x[m], q = x[m + hl]; x[m] = make_float2(p.x + q.x, p.y + q.y); x[m + hl] = cmul(make_float2(p.x - q.x, p.y - q.y), tw); }
;       else { const float2 p = x[m], q = cmul(x[m + hl], tw); x[m] = make_float2(p.x + q.x, p.y + q.y); x[m + hl] = make_float2(p.x - q.x, p.y - q.y); }
;     }
;   }
; }
; template <int LR, bool INV>
; __device__ __forceinline__ void fft_pass(float2* X, const int N, const int sl, const int tid) {
;   constexpr int R = 1 << LR;
;   const int s = 1 << sl;
;   for (int g = tid; g < (N >> LR); g += NTHR) {
;     const int r = g & (s - 1);
;     const int i0 = ((g >> sl) << (sl + LR)) + r;
;     float2 x[R];
; #pragma unroll
;     for (int m = 0; m < R; ++m) x[m] = X[PIDX(i0 + (m << sl))];
;     fft_stages<LR, INV>(x, r, s);
; #pragma unroll
;     for (int m = 0; m < R; ++m) X[PIDX(i0 + (m << sl))] = x[m];
;   }
	v_pk_add_f32 v[40:41], v[38:39], v[50:51] neg_lo:[0,1] neg_hi:[0,1]
	v_pk_add_f32 v[48:49], v[46:47], v[54:55]
	v_pk_add_f32 v[38:39], v[38:39], v[50:51]
	v_pk_add_f32 v[46:47], v[46:47], v[54:55] neg_lo:[0,1] neg_hi:[0,1]
	v_mov_b32_e32 v59, v37
	v_pk_add_f32 v[44:45], v[42:43], v[52:53]
	v_pk_add_f32 v[42:43], v[42:43], v[52:53] neg_lo:[0,1] neg_hi:[0,1]
	v_pk_mul_f32 v[50:51], v[4:5], v[40:41]
	v_pk_mul_f32 v[52:53], v[10:11], v[48:49]
	v_pk_mul_f32 v[54:55], v[10:11], v[38:39]
	v_pk_mul_f32 v[56:57], v[4:5], v[46:47]
	v_pk_add_f32 v[36:37], v[34:35], v[58:59] neg_lo:[0,1] neg_hi:[0,1]
	v_pk_add_f32 v[34:35], v[34:35], v[58:59]
	v_fma_f32 v58, v12, v40, -v51
	v_fma_f32 v59, v13, v41, v50
	v_fma_f32 v50, v8, v48, -v53
	v_fma_f32 v51, v9, v49, v52
	v_fma_f32 v52, v8, v38, -v55
	v_fma_f32 v53, v9, v39, v54
	v_fma_f32 v54, v12, v46, -v57
	v_fma_f32 v55, v13, v47, v56


;     static __device__ __forceinline__ float sl(float g, float up) { return g * __builtin_amdgcn_rcpf(1.0f + __builtin_amdgcn_exp2f(-1.4426950408889634f * g)) * up; }
; __device__ __forceinline__ float2 cmul(float2 a, float2 b) { return make_float2(a.x * b.x - a.y * b.y, a.x * b.y + a.y * b.x); }
; #define tid ltid()
; template <int LR, bool INV>
; __device__ __forceinline__ void fft_stages(float2 (&x)[1 << LR], const int r, const int s) {
;   constexpr int R = 1 << LR;
; #pragma unroll
;   for (int st = 0; st < LR; ++st) {
;     const int hl = INV ? (1 << st) : (R >> (st + 1));
;     const float fb = (float)r * (0.5f / (float)(hl * s));
;     const float2 wb = make_float2(__builtin_amdgcn_cosf(fb), INV ? __builtin_amdgcn_sinf(fb) : -__builtin_amdgcn_sinf(fb));
; #pragma unroll
;     for (int m = 0; m < R; ++m) {
;       if (m & hl) continue;
;       const int k = m & (hl - 1); const int j = k * (8 / hl);
;       const float2 wc = make_float2(c16(j), INV ? s16(j) : -s16(j));
;       const float2 tw = cmul(wb, wc);
;       if (!INV) { const float2 p = x[m], q = x[m + hl]; x[m] = make_float2(p.x + q.x, p.y + q.y); x[m + hl] = cmul(make_float2(p.x - q.x, p.y - q.y), tw); }
;       else { const float2 p = x[m], q = cmul(x[m + hl], tw); x[m] = make_float2(p.x + q.x, p.y + q.y); x[m + hl] = make_float2(p.x - q.x, p.y - q.y); }
;     }
;   }
; }
; template <int LR, bool INV>
; __device__ __forceinline__ void fft_pass(float2* X, const int N, const int sl, const int tid) {
;   constexpr int R = 1 << LR;
;   const int s = 1 << sl;
;   for (int g = tid; g < (N >> LR); g += NTHR) {
;     const int r = g & (s - 1);
;     const int i0 = ((g >> sl) << (sl + LR)) + r;
;     float2 x[R];
; #pragma unroll
;     for (int m = 0; m < R; ++m) x[m] = X[PIDX(i0 + (m << sl))];
;     fft_stages<LR, INV>(x, r, s);
; #pragma unroll
;     for (int m = 0; m < R; ++m) X[PIDX(i0 + (m << sl))] = x[m];
;   }
	v_pk_add_f32 v[40:41], v[44:45], v[50:51] neg_lo:[0,1] neg_hi:[0,1]
	v_pk_add_f32 v[44:45], v[44:45], v[50:51]
	v_pk_add_f32 v[48:49], v[42:43], v[54:55]
	v_pk_add_f32 v[46:47], v[34:35], v[52:53] neg_lo:[0,1] neg_hi:[0,1]
	v_pk_add_f32 v[34:35], v[34:35], v[52:53]
	v_pk_add_f32 v[42:43], v[42:43], v[54:55] neg_lo:[0,1] neg_hi:[0,1]
	v_pk_mul_f32 v[50:51], v[20:21], v[40:41] op_sel:[0,1] op_sel_hi:[1,0]
	v_pk_mul_f32 v[52:53], v[16:17], v[44:45] op_sel:[0,1] op_sel_hi:[1,0]
	v_pk_mul_f32 v[54:55], v[22:23], v[48:49] op_sel:[0,1] op_sel_hi:[1,0]
	v_pk_add_f32 v[38:39], v[36:37], v[58:59] neg_lo:[0,1] neg_hi:[0,1]
	v_pk_add_f32 v[36:37], v[36:37], v[58:59]
	v_pk_mul_f32 v[56:57], v[28:29], v[42:43] op_sel:[0,1]
	v_fma_f32 v58, v18, v40, -v50
	v_fma_f32 v41, v19, v41, v51
	v_fma_f32 v50, v14, v44, -v52
	v_fma_f32 v51, v15, v45, v53
	v_fma_f32 v52, v26, v48, -v54
	v_fma_f32 v53, v27, v49, v55
	v_cmp_le_i32_e32 vcc, s21, v30
	v_fma_f32 v54, v24, v42, -v56
	v_fma_f32 v55, v25, v42, v57


; #define tid ltid()
; template <int LR, bool INV>
; __device__ __forceinline__ void fft_pass(float2* X, const int N, const int sl, const int tid) {
;     ...
;   for (int g = tid; g < (N >> LR); g += NTHR) {
	v_add_u32_e32 v32, 0x1000, v32
	s_or_b64 s[14:15], vcc, s[14:15]
	v_mov_b32_e32 v59, v41

;     static __device__ __forceinline__ float sl(float g, float up) { return g * __builtin_amdgcn_rcpf(1.0f + __builtin_amdgcn_exp2f(-1.4426950408889634f * g)) * up; }
; __device__ __forceinline__ float2 cmul(float2 a, float2 b) { return make_float2(a.x * b.x - a.y * b.y, a.x * b.y + a.y * b.x); }
; template <int LR, bool INV>
; __device__ __forceinline__ void fft_stages(float2 (&x)[1 << LR], const int r, const int s) {
;     ...
;       else { const float2 p = x[m], q = cmul(x[m + hl], tw); x[m] = make_float2(p.x + q.x, p.y + q.y); x[m + hl] = make_float2(p.x - q.x, p.y - q.y); }
; template <int LR, bool INV>
; __device__ __forceinline__ void fft_pass(float2* X, const int N, const int sl, const int tid) {
;     ...
;     for (int m = 0; m < R; ++m) X[PIDX(i0 + (m << sl))] = x[m];
	v_pk_add_f32 v[42:43], v[34:35], v[50:51]
	v_pk_add_f32 v[44:45], v[36:37], v[52:53]
	v_pk_add_f32 v[40:41], v[46:47], v[58:59]
	v_pk_add_f32 v[48:49], v[38:39], v[54:55]
	v_pk_add_f32 v[34:35], v[34:35], v[50:51] neg_lo:[0,1] neg_hi:[0,1]
	v_pk_add_f32 v[36:37], v[36:37], v[52:53] neg_lo:[0,1] neg_hi:[0,1]
	v_pk_add_f32 v[46:47], v[46:47], v[58:59] neg_lo:[0,1] neg_hi:[0,1]
	v_pk_add_f32 v[38:39], v[38:39], v[54:55] neg_lo:[0,1] neg_hi:[0,1]
	ds_write2_b64 v60, v[42:43], v[44:45] offset1:8
	ds_write2_b64 v61, v[40:41], v[48:49] offset0:16 offset1:24
	ds_write2_b64 v61, v[34:35], v[36:37] offset0:33 offset1:41
	ds_write2_b64 v61, v[46:47], v[38:39] offset0:50 offset1:58
	s_andn2_b64 exec, exec, s[14:15]
	s_cbranch_execnz .LBB0_684

;     static __device__ __forceinline__ float sl(float g, float up) { return g * __builtin_amdgcn_rcpf(1.0f + __builtin_amdgcn_exp2f(-1.4426950408889634f * g)) * up; }
; #define tid ltid()
; template <int LR, bool INV>
; __device__ __forceinline__ void fft_pass(float2* X, const int N, const int sl, const int tid) {
;     ...
;   for (int g = tid; g < (N >> LR); g += NTHR) {
;     const int r = g & (s - 1);
;     const int i0 = ((g >> sl) << (sl + LR)) + r;
;     float2 x[R];
; #pragma unroll
;     for (int m = 0; m < R; ++m) x[m] = X[PIDX(i0 + (m << sl))];
.LBB0_687:
	v_and_or_b32 v33, v32, s53, v31
	v_ashrrev_i32_e32 v34, 4, v33
	v_lshl_add_u32 v35, v33, 3, 0
	v_or_b32_e32 v36, 64, v33


;     static __device__ __forceinline__ float sl(float g, float up) { return g * __builtin_amdgcn_rcpf(1.0f + __builtin_amdgcn_exp2f(-1.4426950408889634f * g)) * up; }
; #define tid ltid()
; template <int LR, bool INV>
; __device__ __forceinline__ void fft_pass(float2* X, const int N, const int sl, const int tid) {
;     ...
;   for (int g = tid; g < (N >> LR); g += NTHR) {
;     const int r = g & (s - 1);
;     const int i0 = ((g >> sl) << (sl + LR)) + r;
;     float2 x[R];
; #pragma unroll
;     for (int m = 0; m < R; ++m) x[m] = X[PIDX(i0 + (m << sl))];
	v_or_b32_e32 v33, 0x1c0, v33
	v_lshl_add_u32 v60, v34, 3, v35
	v_ashrrev_i32_e32 v34, 4, v36


;     static __device__ __forceinline__ float sl(float g, float up) { return g * __builtin_amdgcn_rcpf(1.0f + __builtin_amdgcn_exp2f(-1.4426950408889634f * g)) * up; }
; #define tid ltid()
; template <int LR, bool INV>
; __device__ __forceinline__ void fft_pass(float2* X, const int N, const int sl, const int tid) {
;     ...
;   for (int g = tid; g < (N >> LR); g += NTHR) {
;     const int r = g & (s - 1);
;     const int i0 = ((g >> sl) << (sl + LR)) + r;
;     float2 x[R];
; #pragma unroll
;     for (int m = 0; m < R; ++m) x[m] = X[PIDX(i0 + (m << sl))];
	v_ashrrev_i32_e32 v33, 4, v33
	v_lshl_add_u32 v61, v34, 3, v35


;     static __device__ __forceinline__ float sl(float g, float up) { return g * __builtin_amdgcn_rcpf(1.0f + __builtin_amdgcn_exp2f(-1.4426950408889634f * g)) * up; }
; __device__ __forceinline__ float2 cmul(float2 a, float2 b) { return make_float2(a.x * b.x - a.y * b.y, a.x * b.y + a.y * b.x); }
; #define tid ltid()
; template <int LR, bool INV>
; __device__ __forceinline__ void fft_stages(float2 (&x)[1 << LR], const int r, const int s) {
;   constexpr int R = 1 << LR;
; #pragma unroll
;   for (int st = 0; st < LR; ++st) {
;     const int hl = INV ? (1 << st) : (R >> (st + 1));
;     const float fb = (float)r * (0.5f / (float)(hl * s));
;     const float2 wb = make_float2(__builtin_amdgcn_cosf(fb), INV ? __builtin_amdgcn_sinf(fb) : -__builtin_amdgcn_sinf(fb));
; #pragma unroll
;     for (int m = 0; m < R; ++m) {
;       if (m & hl) continue;
;       const int k = m & (hl - 1); const int j = k * (8 / hl);
;       const float2 wc = make_float2(c16(j), INV ? s16(j) : -s16(j));
;       const float2 tw = cmul(wb, wc);
;       if (!INV) { const float2 p = x[m], q = x[m + hl]; x[m] = make_float2(p.x + q.x, p.y + q.y); x[m + hl] = cmul(make_float2(p.x - q.x, p.y - q.y), tw); }
;       else { const float2 p = x[m], q = cmul(x[m + hl], tw); x[m] = make_float2(p.x + q.x, p.y + q.y); x[m + hl] = make_float2(p.x - q.x, p.y - q.y); }
;     }
;   }
; }
; template <int LR, bool INV>
; __device__ __forceinline__ void fft_pass(float2* X, const int N, const int sl, const int tid) {
;   constexpr int R = 1 << LR;
;   const int s = 1 << sl;
;   for (int g = tid; g < (N >> LR); g += NTHR) {
;     const int r = g & (s - 1);
;     const int i0 = ((g >> sl) << (sl + LR)) + r;
;     float2 x[R];
; #pragma unroll
;     for (int m = 0; m < R; ++m) x[m] = X[PIDX(i0 + (m << sl))];
;     fft_stages<LR, INV>(x, r, s);
; #pragma unroll
;     for (int m = 0; m < R; ++m) X[PIDX(i0 + (m << sl))] = x[m];
;   }
	v_lshl_add_u32 v33, v33, 3, v35
	ds_read_b64 v[34:35], v60
	ds_read_b64 v[36:37], v60 offset:544
	ds_read_b64 v[38:39], v60 offset:1088
	ds_read_b64 v[40:41], v60 offset:1632
	ds_read_b64 v[42:43], v60 offset:2176
	ds_read_b64 v[44:45], v60 offset:2720
	ds_read_b64 v[46:47], v60 offset:3808
	ds_read_b64 v[48:49], v60 offset:3264
	s_waitcnt lgkmcnt(6)
	v_pk_mul_f32 v[50:51], v[36:37], v[2:3]
	s_waitcnt lgkmcnt(4)
	v_pk_mul_f32 v[52:53], v[2:3], v[40:41]
	s_waitcnt lgkmcnt(2)
	v_pk_mul_f32 v[54:55], v[2:3], v[44:45]
	s_waitcnt lgkmcnt(1)
	v_pk_mul_f32 v[56:57], v[2:3], v[46:47]
	v_fma_f32 v58, v36, v6, -v51
	v_fma_f32 v37, v37, v7, v50
	v_fma_f32 v50, v6, v40, -v53
	v_fma_f32 v51, v7, v41, v52
	v_fma_f32 v52, v6, v44, -v55
	v_fma_f32 v53, v7, v45, v54
	v_fma_f32 v54, v6, v46, -v57
	v_fma_f32 v55, v7, v47, v56


;     static __device__ __forceinline__ float sl(float g, float up) { return g * __builtin_amdgcn_rcpf(1.0f + __builtin_amdgcn_exp2f(-1.4426950408889634f * g)) * up; }
; __device__ __forceinline__ float2 cmul(float2 a, float2 b) { return make_float2(a.x * b.x - a.y * b.y, a.x * b.y + a.y * b.x); }
; #define tid ltid()
; template <int LR, bool INV>
; __device__ __forceinline__ void fft_stages(float2 (&x)[1 << LR], const int r, const int s) {
;   constexpr int R = 1 << LR;
; #pragma unroll
;   for (int st = 0; st < LR; ++st) {
;     const int hl = INV ? (1 << st) : (R >> (st + 1));
;     const float fb = (float)r * (0.5f / (float)(hl * s));
;     const float2 wb = make_float2(__builtin_amdgcn_cosf(fb), INV ? __builtin_amdgcn_sinf(fb) : -__builtin_amdgcn_sinf(fb));
; #pragma unroll
;     for (int m = 0; m < R; ++m) {
;       if (m & hl) continue;
;       const int k = m & (hl - 1); const int j = k * (8 / hl);
;       const float2 wc = make_float2(c16(j), INV ? s16(j) : -s16(j));
;       const float2 tw = cmul(wb, wc);
;       if (!INV) { const float2 p = x[m], q = x[m + hl]; x[m] = make_float2(p.x + q.x, p.y + q.y); x[m + hl] = cmul(make_float2(p.x - q.x, p.y - q.y), tw); }
;       else { const float2 p = x[m], q = cmul(x[m + hl], tw); x[m] = make_float2(p.x + q.x, p.y + q.y); x[m + hl] = make_float2(p.x - q.x, p.y - q.y); }
;     }
;   }
; }
; template <int LR, bool INV>
; __device__ __forceinline__ void fft_pass(float2* X, const int N, const int sl, const int tid) {
;   constexpr int R = 1 << LR;
;   const int s = 1 << sl;
;   for (int g = tid; g < (N >> LR); g += NTHR) {
;     const int r = g & (s - 1);
;     const int i0 = ((g >> sl) << (sl + LR)) + r;
;     float2 x[R];
; #pragma unroll
;     for (int m = 0; m < R; ++m) x[m] = X[PIDX(i0 + (m << sl))];
;     fft_stages<LR, INV>(x, r, s);
; #pragma unroll
;     for (int m = 0; m < R; ++m) X[PIDX(i0 + (m << sl))] = x[m];
;   }
	v_pk_add_f32 v[40:41], v[38:39], v[50:51] neg_lo:[0,1] neg_hi:[0,1]
	s_waitcnt lgkmcnt(0)
	v_pk_add_f32 v[46:47], v[48:49], v[54:55]
	v_mov_b32_e32 v59, v37
	v_pk_add_f32 v[44:45], v[42:43], v[52:53]
	v_pk_add_f32 v[38:39], v[38:39], v[50:51]
	v_pk_add_f32 v[42:43], v[42:43], v[52:53] neg_lo:[0,1] neg_hi:[0,1]
	v_pk_add_f32 v[48:49], v[48:49], v[54:55] neg_lo:[0,1] neg_hi:[0,1]
	v_pk_mul_f32 v[50:51], v[4:5], v[40:41]
	v_pk_mul_f32 v[52:53], v[10:11], v[46:47]
	v_pk_add_f32 v[36:37], v[34:35], v[58:59] neg_lo:[0,1] neg_hi:[0,1]
	v_pk_add_f32 v[34:35], v[34:35], v[58:59]
	v_pk_mul_f32 v[54:55], v[10:11], v[38:39]
	v_pk_mul_f32 v[56:57], v[4:5], v[48:49]
	v_fma_f32 v58, v12, v40, -v51
	v_fma_f32 v59, v13, v41, v50
	v_fma_f32 v50, v8, v46, -v53
	v_fma_f32 v51, v9, v47, v52
	v_fma_f32 v52, v8, v38, -v55
	v_fma_f32 v53, v9, v39, v54
	v_fma_f32 v54, v12, v48, -v57
	v_fma_f32 v55, v13, v49, v56


;     static __device__ __forceinline__ float sl(float g, float up) { return g * __builtin_amdgcn_rcpf(1.0f + __builtin_amdgcn_exp2f(-1.4426950408889634f * g)) * up; }
; __device__ __forceinline__ float2 cmul(float2 a, float2 b) { return make_float2(a.x * b.x - a.y * b.y, a.x * b.y + a.y * b.x); }
; #define tid ltid()
; template <int LR, bool INV>
; __device__ __forceinline__ void fft_stages(float2 (&x)[1 << LR], const int r, const int s) {
;   constexpr int R = 1 << LR;
; #pragma unroll
;   for (int st = 0; st < LR; ++st) {
;     const int hl = INV ? (1 << st) : (R >> (st + 1));
;     const float fb = (float)r * (0.5f / (float)(hl * s));
;     const float2 wb = make_float2(__builtin_amdgcn_cosf(fb), INV ? __builtin_amdgcn_sinf(fb) : -__builtin_amdgcn_sinf(fb));
; #pragma unroll
;     for (int m = 0; m < R; ++m) {
;       if (m & hl) continue;
;       const int k = m & (hl - 1); const int j = k * (8 / hl);
;       const float2 wc = make_float2(c16(j), INV ? s16(j) : -s16(j));
;       const float2 tw = cmul(wb, wc);
;       if (!INV) { const float2 p = x[m], q = x[m + hl]; x[m] = make_float2(p.x + q.x, p.y + q.y); x[m + hl] = cmul(make_float2(p.x - q.x, p.y - q.y), tw); }
;       else { const float2 p = x[m], q = cmul(x[m + hl], tw); x[m] = make_float2(p.x + q.x, p.y + q.y); x[m + hl] = make_float2(p.x - q.x, p.y - q.y); }
;     }
;   }
; }
; template <int LR, bool INV>
; __device__ __forceinline__ void fft_pass(float2* X, const int N, const int sl, const int tid) {
;   constexpr int R = 1 << LR;
;   const int s = 1 << sl;
;   for (int g = tid; g < (N >> LR); g += NTHR) {
;     const int r = g & (s - 1);
;     const int i0 = ((g >> sl) << (sl + LR)) + r;
;     float2 x[R];
; #pragma unroll
;     for (int m = 0; m < R; ++m) x[m] = X[PIDX(i0 + (m << sl))];
;     fft_stages<LR, INV>(x, r, s);
; #pragma unroll
;     for (int m = 0; m < R; ++m) X[PIDX(i0 + (m << sl))] = x[m];
;   }
	v_pk_add_f32 v[40:41], v[44:45], v[50:51] neg_lo:[0,1] neg_hi:[0,1]
	v_pk_add_f32 v[44:45], v[44:45], v[50:51]
	v_pk_add_f32 v[46:47], v[34:35], v[52:53] neg_lo:[0,1] neg_hi:[0,1]
	v_pk_add_f32 v[34:35], v[34:35], v[52:53]
	v_pk_add_f32 v[48:49], v[42:43], v[54:55]
	v_pk_add_f32 v[42:43], v[42:43], v[54:55] neg_lo:[0,1] neg_hi:[0,1]
	v_pk_mul_f32 v[50:51], v[20:21], v[40:41] op_sel:[0,1] op_sel_hi:[1,0]
	v_pk_mul_f32 v[52:53], v[16:17], v[44:45] op_sel:[0,1] op_sel_hi:[1,0]
	v_add_u32_e32 v30, 0x200, v30
	v_pk_add_f32 v[38:39], v[36:37], v[58:59] neg_lo:[0,1] neg_hi:[0,1]
	v_pk_add_f32 v[36:37], v[36:37], v[58:59]
	v_pk_mul_f32 v[54:55], v[22:23], v[48:49] op_sel:[0,1] op_sel_hi:[1,0]
	v_pk_mul_f32 v[56:57], v[28:29], v[42:43] op_sel:[0,1]
	v_fma_f32 v58, v18, v40, -v50
	v_fma_f32 v41, v19, v41, v51
	v_fma_f32 v50, v14, v44, -v52
	v_fma_f32 v51, v15, v45, v53
	v_cmp_le_i32_e32 vcc, s21, v30
	v_fma_f32 v52, v26, v48, -v54
	v_fma_f32 v53, v27, v49, v55
	v_fma_f32 v54, v24, v42, -v56
	v_fma_f32 v55, v25, v42, v57

; #define tid ltid()
; template <int LR, bool INV>
; __device__ __forceinline__ void fft_pass(float2* X, const int N, const int sl, const int tid) {
;     ...
;   for (int g = tid; g < (N >> LR); g += NTHR) {
	v_add_u32_e32 v32, 0x1000, v32
	s_or_b64 s[14:15], vcc, s[14:15]
	v_mov_b32_e32 v59, v41


;     static __device__ __forceinline__ float sl(float g, float up) { return g * __builtin_amdgcn_rcpf(1.0f + __builtin_amdgcn_exp2f(-1.4426950408889634f * g)) * up; }
; __device__ __forceinline__ float2 cmul(float2 a, float2 b) { return make_float2(a.x * b.x - a.y * b.y, a.x * b.y + a.y * b.x); }
; template <int LR, bool INV>
; __device__ __forceinline__ void fft_stages(float2 (&x)[1 << LR], const int r, const int s) {
;     ...
;       else { const float2 p = x[m], q = cmul(x[m + hl], tw); x[m] = make_float2(p.x + q.x, p.y + q.y); x[m + hl] = make_float2(p.x - q.x, p.y - q.y); }
; template <int LR, bool INV>
; __device__ __forceinline__ void fft_pass(float2* X, const int N, const int sl, const int tid) {
;     ...
;     for (int m = 0; m < R; ++m) X[PIDX(i0 + (m << sl))] = x[m];
	v_pk_add_f32 v[42:43], v[34:35], v[50:51]
	v_pk_add_f32 v[40:41], v[46:47], v[58:59]
	v_pk_add_f32 v[44:45], v[36:37], v[52:53]
	v_pk_add_f32 v[48:49], v[38:39], v[54:55]
	v_pk_add_f32 v[34:35], v[34:35], v[50:51] neg_lo:[0,1] neg_hi:[0,1]
	v_pk_add_f32 v[36:37], v[36:37], v[52:53] neg_lo:[0,1] neg_hi:[0,1]
	v_pk_add_f32 v[46:47], v[46:47], v[58:59] neg_lo:[0,1] neg_hi:[0,1]
	v_pk_add_f32 v[38:39], v[38:39], v[54:55] neg_lo:[0,1] neg_hi:[0,1]
	ds_write_b64 v60, v[42:43]
	ds_write_b64 v60, v[44:45] offset:544
	ds_write_b64 v60, v[40:41] offset:1088
	ds_write_b64 v60, v[48:49] offset:1632
	ds_write_b64 v60, v[34:35] offset:2176
	ds_write_b64 v60, v[36:37] offset:2720
	ds_write_b64 v60, v[46:47] offset:3264
	ds_write_b64 v60, v[38:39] offset:3808
	s_andn2_b64 exec, exec, s[14:15]
	s_cbranch_execnz .LBB0_687
